# PEER apply: 8 id ranges in U sweep, packed f32 FMA for U dot and V accumulate
# speedup vs baseline: 1.1695x; 1.0132x over previous
; __device__ __forceinline__ void ph_peer_apply(const Params& P, int layer, float* xlat, float* xctx_in, float* xctx_out, int nrows, bool write_next, char* smem, float* xlat_out = nullptr) {
;     ...
; #pragma unroll
;     for (int j8 = 0; j8 < 4; ++j8) {
;       const h16x8 t = *(const h16x8*)(xq + (size_t)row * D + lb * 32 + j8 * 8);
; #pragma unroll
;       for (int j = 0; j < 8; ++j) xv[j8 * 8 + j] = lact ? (float)t[j] : 0.f;
;     }
;     const int id0 = seli[(size_t)row * NSEL + lane], id1 = seli[(size_t)row * NSEL + 64 + lane];
.Lap0_ntl:
	s_add_u32 s50, s50, 1
	s_add_u32 s1, s1, s44
	s_cmp_lt_u32 s1, 0x8200
	s_cbranch_scc1 .Lap0_ntl
	s_mov_b32 s58, 0
	s_mov_b32 s59, 0
	s_mov_b32 s62, 0
	s_mov_b32 s48, 0
	s_mov_b32 s49, 0
	s_mov_b32 s45, s13
	s_lshl_b32 s15, s45, 12
	s_lshr_b32 s31, s45, 20
	s_add_u32 s20, s4, 0xbe4c000
	s_addc_u32 s21, s5, 0
	s_add_u32 s20, s20, s15
	s_addc_u32 s21, s21, s31
	s_lshl_b32 s15, s45, 9
	s_add_u32 s22, s4, 0x1404c000
	s_addc_u32 s23, s5, 0
	s_add_u32 s22, s22, s15
	s_addc_u32 s23, s23, 0
	global_load_dwordx4 v[200:203], v224, s[20:21]
	global_load_dwordx4 v[204:207], v224, s[20:21] offset:16
	global_load_dwordx4 v[208:211], v224, s[20:21] offset:32
	global_load_dwordx4 v[212:215], v224, s[20:21] offset:48
	global_load_dword v36, v226, s[22:23]
	global_load_dword v37, v226, s[22:23] offset:256
	s_waitcnt vmcnt(0)
	v_cvt_f32_f16_e32 v4, v200
	v_cvt_f32_f16_sdwa v5, v200 dst_sel:DWORD dst_unused:UNUSED_PAD src0_sel:WORD_1
	v_cvt_f32_f16_e32 v6, v201
	v_cvt_f32_f16_sdwa v7, v201 dst_sel:DWORD dst_unused:UNUSED_PAD src0_sel:WORD_1
	v_cvt_f32_f16_e32 v8, v202
	v_cvt_f32_f16_sdwa v9, v202 dst_sel:DWORD dst_unused:UNUSED_PAD src0_sel:WORD_1
	v_cvt_f32_f16_e32 v10, v203
	v_cvt_f32_f16_sdwa v11, v203 dst_sel:DWORD dst_unused:UNUSED_PAD src0_sel:WORD_1
	v_cvt_f32_f16_e32 v12, v204
	v_cvt_f32_f16_sdwa v13, v204 dst_sel:DWORD dst_unused:UNUSED_PAD src0_sel:WORD_1
	v_cvt_f32_f16_e32 v14, v205
	v_cvt_f32_f16_sdwa v15, v205 dst_sel:DWORD dst_unused:UNUSED_PAD src0_sel:WORD_1
	v_cvt_f32_f16_e32 v16, v206
	v_cvt_f32_f16_sdwa v17, v206 dst_sel:DWORD dst_unused:UNUSED_PAD src0_sel:WORD_1
	v_cvt_f32_f16_e32 v18, v207
	v_cvt_f32_f16_sdwa v19, v207 dst_sel:DWORD dst_unused:UNUSED_PAD src0_sel:WORD_1
	v_cvt_f32_f16_e32 v20, v208
	v_cvt_f32_f16_sdwa v21, v208 dst_sel:DWORD dst_unused:UNUSED_PAD src0_sel:WORD_1
	v_cvt_f32_f16_e32 v22, v209
	v_cvt_f32_f16_sdwa v23, v209 dst_sel:DWORD dst_unused:UNUSED_PAD src0_sel:WORD_1
	v_cvt_f32_f16_e32 v24, v210
	v_cvt_f32_f16_sdwa v25, v210 dst_sel:DWORD dst_unused:UNUSED_PAD src0_sel:WORD_1
	v_cvt_f32_f16_e32 v26, v211
	v_cvt_f32_f16_sdwa v27, v211 dst_sel:DWORD dst_unused:UNUSED_PAD src0_sel:WORD_1
	v_cvt_f32_f16_e32 v28, v212
	v_cvt_f32_f16_sdwa v29, v212 dst_sel:DWORD dst_unused:UNUSED_PAD src0_sel:WORD_1
	v_cvt_f32_f16_e32 v30, v213
	v_cvt_f32_f16_sdwa v31, v213 dst_sel:DWORD dst_unused:UNUSED_PAD src0_sel:WORD_1
	v_cvt_f32_f16_e32 v32, v214
	v_cvt_f32_f16_sdwa v33, v214 dst_sel:DWORD dst_unused:UNUSED_PAD src0_sel:WORD_1
	v_cvt_f32_f16_e32 v34, v215
	v_cvt_f32_f16_sdwa v35, v215 dst_sel:DWORD dst_unused:UNUSED_PAD src0_sel:WORD_1
	v_lshrrev_b32_e32 v195, 11, v36
	v_lshrrev_b32_e32 v196, 11, v37
	v_cmp_eq_u32_e64 s[52:53], s58, v195
	v_cmp_eq_u32_e64 s[54:55], s58, v196
	v_mov_b32_e32 v44, v36
	s_mov_b32 s61, 0
	s_mov_b32 s57, 0
	s_lshl_b32 s63, s59, 9
	s_mul_i32 s1, s12, 0x2800
	s_add_u32 s63, s63, s1
	s_lshl_b32 s1, s62, 31
	s_or_b32 s63, s63, s1
	v_mov_b32_e32 v45, 0

; __device__ __forceinline__ void ph_peer_apply(const Params& P, int layer, float* xlat, float* xctx_in, float* xctx_out, int nrows, bool write_next, char* smem, float* xlat_out = nullptr) {
;     ...
;   for (int row = blockIdx.x * (NTHR / 64) + wave; row < nrows; row += gridDim.x * (NTHR / 64)) {
.Lap0_h1p:
	s_cmp_lt_u32 s57, 8
	s_cbranch_scc1 .Lap0_dummyp
	s_cmp_lg_u32 s48, 0
	s_cbranch_scc1 .Lap0_dummyp
	s_add_u32 s59, s59, 1
	s_cmp_lt_u32 s59, s50
	s_cbranch_scc1 .Lap0_advp
	s_mov_b32 s59, 0
	s_add_u32 s58, s58, 1
	s_cmp_lt_u32 s58, 8
	s_cbranch_scc1 .Lap0_advp
	s_mov_b32 s48, 1
	s_branch .Lap0_dummyp

; __device__ __forceinline__ void ph_peer_apply(const Params& P, int layer, float* xlat, float* xctx_in, float* xctx_out, int nrows, bool write_next, char* smem, float* xlat_out = nullptr) {
;     ...
; #pragma unroll
;     for (int j8 = 0; j8 < 4; ++j8) {
;       const h16x8 t = *(const h16x8*)(xq + (size_t)row * D + lb * 32 + j8 * 8);
; #pragma unroll
;       for (int j = 0; j < 8; ++j) xv[j8 * 8 + j] = lact ? (float)t[j] : 0.f;
;     }
;     const int id0 = seli[(size_t)row * NSEL + lane], id1 = seli[(size_t)row * NSEL + 64 + lane];
.Lap0_advwp:
	s_waitcnt vmcnt(21)
	v_mov_b32_e32 v36, v38
	v_mov_b32_e32 v37, v39
	s_xor_b32 s62, s62, 1
	s_cmp_lg_u32 s62, 0
	s_cbranch_scc1 .Lap0_cv1p
	v_cvt_f32_f16_e32 v4, v200
	v_cvt_f32_f16_sdwa v5, v200 dst_sel:DWORD dst_unused:UNUSED_PAD src0_sel:WORD_1
	v_cvt_f32_f16_e32 v6, v201
	v_cvt_f32_f16_sdwa v7, v201 dst_sel:DWORD dst_unused:UNUSED_PAD src0_sel:WORD_1
	v_cvt_f32_f16_e32 v8, v202
	v_cvt_f32_f16_sdwa v9, v202 dst_sel:DWORD dst_unused:UNUSED_PAD src0_sel:WORD_1
	v_cvt_f32_f16_e32 v10, v203
	v_cvt_f32_f16_sdwa v11, v203 dst_sel:DWORD dst_unused:UNUSED_PAD src0_sel:WORD_1
	v_cvt_f32_f16_e32 v12, v204
	v_cvt_f32_f16_sdwa v13, v204 dst_sel:DWORD dst_unused:UNUSED_PAD src0_sel:WORD_1
	v_cvt_f32_f16_e32 v14, v205
	v_cvt_f32_f16_sdwa v15, v205 dst_sel:DWORD dst_unused:UNUSED_PAD src0_sel:WORD_1
	v_cvt_f32_f16_e32 v16, v206
	v_cvt_f32_f16_sdwa v17, v206 dst_sel:DWORD dst_unused:UNUSED_PAD src0_sel:WORD_1
	v_cvt_f32_f16_e32 v18, v207
	v_cvt_f32_f16_sdwa v19, v207 dst_sel:DWORD dst_unused:UNUSED_PAD src0_sel:WORD_1
	v_cvt_f32_f16_e32 v20, v208
	v_cvt_f32_f16_sdwa v21, v208 dst_sel:DWORD dst_unused:UNUSED_PAD src0_sel:WORD_1
	v_cvt_f32_f16_e32 v22, v209
	v_cvt_f32_f16_sdwa v23, v209 dst_sel:DWORD dst_unused:UNUSED_PAD src0_sel:WORD_1
	v_cvt_f32_f16_e32 v24, v210
	v_cvt_f32_f16_sdwa v25, v210 dst_sel:DWORD dst_unused:UNUSED_PAD src0_sel:WORD_1
	v_cvt_f32_f16_e32 v26, v211
	v_cvt_f32_f16_sdwa v27, v211 dst_sel:DWORD dst_unused:UNUSED_PAD src0_sel:WORD_1
	v_cvt_f32_f16_e32 v28, v212
	v_cvt_f32_f16_sdwa v29, v212 dst_sel:DWORD dst_unused:UNUSED_PAD src0_sel:WORD_1
	v_cvt_f32_f16_e32 v30, v213
	v_cvt_f32_f16_sdwa v31, v213 dst_sel:DWORD dst_unused:UNUSED_PAD src0_sel:WORD_1
	v_cvt_f32_f16_e32 v32, v214
	v_cvt_f32_f16_sdwa v33, v214 dst_sel:DWORD dst_unused:UNUSED_PAD src0_sel:WORD_1
	v_cvt_f32_f16_e32 v34, v215
	v_cvt_f32_f16_sdwa v35, v215 dst_sel:DWORD dst_unused:UNUSED_PAD src0_sel:WORD_1
	s_branch .Lap0_cvdp
.Lap0_cv1p:
	v_cvt_f32_f16_e32 v160, v200
	v_cvt_f32_f16_sdwa v161, v200 dst_sel:DWORD dst_unused:UNUSED_PAD src0_sel:WORD_1
	v_cvt_f32_f16_e32 v162, v201
	v_cvt_f32_f16_sdwa v163, v201 dst_sel:DWORD dst_unused:UNUSED_PAD src0_sel:WORD_1
	v_cvt_f32_f16_e32 v164, v202
	v_cvt_f32_f16_sdwa v165, v202 dst_sel:DWORD dst_unused:UNUSED_PAD src0_sel:WORD_1
	v_cvt_f32_f16_e32 v166, v203
	v_cvt_f32_f16_sdwa v167, v203 dst_sel:DWORD dst_unused:UNUSED_PAD src0_sel:WORD_1
	v_cvt_f32_f16_e32 v168, v204
	v_cvt_f32_f16_sdwa v169, v204 dst_sel:DWORD dst_unused:UNUSED_PAD src0_sel:WORD_1
	v_cvt_f32_f16_e32 v170, v205
	v_cvt_f32_f16_sdwa v171, v205 dst_sel:DWORD dst_unused:UNUSED_PAD src0_sel:WORD_1
	v_cvt_f32_f16_e32 v172, v206
	v_cvt_f32_f16_sdwa v173, v206 dst_sel:DWORD dst_unused:UNUSED_PAD src0_sel:WORD_1
	v_cvt_f32_f16_e32 v174, v207
	v_cvt_f32_f16_sdwa v175, v207 dst_sel:DWORD dst_unused:UNUSED_PAD src0_sel:WORD_1
	v_cvt_f32_f16_e32 v176, v208
	v_cvt_f32_f16_sdwa v177, v208 dst_sel:DWORD dst_unused:UNUSED_PAD src0_sel:WORD_1
	v_cvt_f32_f16_e32 v178, v209
	v_cvt_f32_f16_sdwa v179, v209 dst_sel:DWORD dst_unused:UNUSED_PAD src0_sel:WORD_1
	v_cvt_f32_f16_e32 v180, v210
	v_cvt_f32_f16_sdwa v181, v210 dst_sel:DWORD dst_unused:UNUSED_PAD src0_sel:WORD_1
	v_cvt_f32_f16_e32 v182, v211
	v_cvt_f32_f16_sdwa v183, v211 dst_sel:DWORD dst_unused:UNUSED_PAD src0_sel:WORD_1
	v_cvt_f32_f16_e32 v184, v212
	v_cvt_f32_f16_sdwa v185, v212 dst_sel:DWORD dst_unused:UNUSED_PAD src0_sel:WORD_1
	v_cvt_f32_f16_e32 v186, v213
	v_cvt_f32_f16_sdwa v187, v213 dst_sel:DWORD dst_unused:UNUSED_PAD src0_sel:WORD_1
	v_cvt_f32_f16_e32 v188, v214
	v_cvt_f32_f16_sdwa v189, v214 dst_sel:DWORD dst_unused:UNUSED_PAD src0_sel:WORD_1
	v_cvt_f32_f16_e32 v190, v215
	v_cvt_f32_f16_sdwa v191, v215 dst_sel:DWORD dst_unused:UNUSED_PAD src0_sel:WORD_1
.Lap0_cvdp:
	v_lshrrev_b32_e32 v195, 11, v36
	v_lshrrev_b32_e32 v196, 11, v37
	v_cmp_eq_u32_e64 s[52:53], s58, v195
	v_cmp_eq_u32_e64 s[54:55], s58, v196
	v_mov_b32_e32 v44, v36
	s_mov_b32 s61, 0
	s_mov_b32 s57, 0
	s_lshl_b32 s63, s59, 9
	s_mul_i32 s1, s12, 0x2800
	s_add_u32 s63, s63, s1
	s_lshl_b32 s1, s62, 31
	s_or_b32 s63, s63, s1

; __device__ __forceinline__ void ph_peer_apply(const Params& P, int layer, float* xlat, float* xctx_in, float* xctx_out, int nrows, bool write_next, char* smem, float* xlat_out = nullptr) {
;     ...
;       const h16x8 t = *(const h16x8*)(xq + (size_t)row * D + lb * 32 + j8 * 8);
; #pragma unroll
;       for (int j = 0; j < 8; ++j) xv[j8 * 8 + j] = lact ? (float)t[j] : 0.f;
;     }
;     const int id0 = seli[(size_t)row * NSEL + lane], id1 = seli[(size_t)row * NSEL + 64 + lane];
;     const float g0 = selg[(size_t)row * NSEL + lane], g1 = selg[(size_t)row * NSEL + 64 + lane];
.Lap0_pfcp:
	s_add_u32 s1, s59, 1
	s_cmp_lt_u32 s1, s50
	s_cbranch_scc1 .Lap0_pfkp
	s_mov_b32 s1, 0
	s_cmp_lt_u32 s58, 7
	s_cbranch_scc0 .Lap0_pfretp
.Lap0_pfkp:
	s_mul_i32 s1, s1, s44
	s_add_u32 s1, s1, s13
	s_lshl_b32 s15, s1, 12
	s_lshr_b32 s31, s1, 20
	s_add_u32 s20, s4, 0xbe4c000
	s_addc_u32 s21, s5, 0
	s_add_u32 s20, s20, s15
	s_addc_u32 s21, s21, s31
	s_lshl_b32 s15, s1, 9
	s_add_u32 s22, s4, 0x1404c000
	s_addc_u32 s23, s5, 0
	s_add_u32 s22, s22, s15
	s_addc_u32 s23, s23, 0
	global_load_dword v38, v226, s[22:23]
	global_load_dword v39, v226, s[22:23] offset:256
	global_load_dwordx4 v[200:203], v224, s[20:21]
	global_load_dwordx4 v[204:207], v224, s[20:21] offset:16
	global_load_dwordx4 v[208:211], v224, s[20:21] offset:32
	global_load_dwordx4 v[212:215], v224, s[20:21] offset:48

.Lap0_pass:
	s_waitcnt vmcnt(21)
	v_lshlrev_b32_e32 v192, 23, v54
	v_cvt_scalef32_pk32_f32_fp6 v[112:143], v[48:53], v192
	s_bitcmp1_b32 s33, 31
	s_cbranch_scc1 .Lap0_cB0
	v_pk_mul_f32 v[144:145], v[112:113], v[4:5]
	v_pk_fma_f32 v[144:145], v[114:115], v[6:7], v[144:145]
	v_pk_fma_f32 v[144:145], v[116:117], v[8:9], v[144:145]
	v_pk_fma_f32 v[144:145], v[118:119], v[10:11], v[144:145]
	v_pk_fma_f32 v[144:145], v[120:121], v[12:13], v[144:145]
	v_pk_fma_f32 v[144:145], v[122:123], v[14:15], v[144:145]
	v_pk_fma_f32 v[144:145], v[124:125], v[16:17], v[144:145]
	v_pk_fma_f32 v[144:145], v[126:127], v[18:19], v[144:145]
	v_pk_fma_f32 v[144:145], v[128:129], v[20:21], v[144:145]
	v_pk_fma_f32 v[144:145], v[130:131], v[22:23], v[144:145]
	v_pk_fma_f32 v[144:145], v[132:133], v[24:25], v[144:145]
	v_pk_fma_f32 v[144:145], v[134:135], v[26:27], v[144:145]
	v_pk_fma_f32 v[144:145], v[136:137], v[28:29], v[144:145]
	v_pk_fma_f32 v[144:145], v[138:139], v[30:31], v[144:145]
	v_pk_fma_f32 v[144:145], v[140:141], v[32:33], v[144:145]
	v_pk_fma_f32 v[144:145], v[142:143], v[34:35], v[144:145]
	v_add_f32_e32 v146, v144, v145
	s_branch .Lap0_cD0
.Lap0_cB0:
	v_pk_mul_f32 v[144:145], v[112:113], v[160:161]
	v_pk_fma_f32 v[144:145], v[114:115], v[162:163], v[144:145]
	v_pk_fma_f32 v[144:145], v[116:117], v[164:165], v[144:145]
	v_pk_fma_f32 v[144:145], v[118:119], v[166:167], v[144:145]
	v_pk_fma_f32 v[144:145], v[120:121], v[168:169], v[144:145]
	v_pk_fma_f32 v[144:145], v[122:123], v[170:171], v[144:145]
	v_pk_fma_f32 v[144:145], v[124:125], v[172:173], v[144:145]
	v_pk_fma_f32 v[144:145], v[126:127], v[174:175], v[144:145]
	v_pk_fma_f32 v[144:145], v[128:129], v[176:177], v[144:145]
	v_pk_fma_f32 v[144:145], v[130:131], v[178:179], v[144:145]
	v_pk_fma_f32 v[144:145], v[132:133], v[180:181], v[144:145]
	v_pk_fma_f32 v[144:145], v[134:135], v[182:183], v[144:145]
	v_pk_fma_f32 v[144:145], v[136:137], v[184:185], v[144:145]
	v_pk_fma_f32 v[144:145], v[138:139], v[186:187], v[144:145]
	v_pk_fma_f32 v[144:145], v[140:141], v[188:189], v[144:145]
	v_pk_fma_f32 v[144:145], v[142:143], v[190:191], v[144:145]
	v_add_f32_e32 v146, v144, v145

.Lap0_aftl0:
	s_waitcnt vmcnt(21)
	v_lshlrev_b32_e32 v192, 23, v62
	v_cvt_scalef32_pk32_f32_fp6 v[112:143], v[56:61], v192
	s_bitcmp1_b32 s38, 31
	s_cbranch_scc1 .Lap0_cB1
	v_pk_mul_f32 v[144:145], v[112:113], v[4:5]
	v_pk_fma_f32 v[144:145], v[114:115], v[6:7], v[144:145]
	v_pk_fma_f32 v[144:145], v[116:117], v[8:9], v[144:145]
	v_pk_fma_f32 v[144:145], v[118:119], v[10:11], v[144:145]
	v_pk_fma_f32 v[144:145], v[120:121], v[12:13], v[144:145]
	v_pk_fma_f32 v[144:145], v[122:123], v[14:15], v[144:145]
	v_pk_fma_f32 v[144:145], v[124:125], v[16:17], v[144:145]
	v_pk_fma_f32 v[144:145], v[126:127], v[18:19], v[144:145]
	v_pk_fma_f32 v[144:145], v[128:129], v[20:21], v[144:145]
	v_pk_fma_f32 v[144:145], v[130:131], v[22:23], v[144:145]
	v_pk_fma_f32 v[144:145], v[132:133], v[24:25], v[144:145]
	v_pk_fma_f32 v[144:145], v[134:135], v[26:27], v[144:145]
	v_pk_fma_f32 v[144:145], v[136:137], v[28:29], v[144:145]
	v_pk_fma_f32 v[144:145], v[138:139], v[30:31], v[144:145]
	v_pk_fma_f32 v[144:145], v[140:141], v[32:33], v[144:145]
	v_pk_fma_f32 v[144:145], v[142:143], v[34:35], v[144:145]
	v_add_f32_e32 v147, v144, v145
	s_branch .Lap0_cD1
.Lap0_cB1:
	v_pk_mul_f32 v[144:145], v[112:113], v[160:161]
	v_pk_fma_f32 v[144:145], v[114:115], v[162:163], v[144:145]
	v_pk_fma_f32 v[144:145], v[116:117], v[164:165], v[144:145]
	v_pk_fma_f32 v[144:145], v[118:119], v[166:167], v[144:145]
	v_pk_fma_f32 v[144:145], v[120:121], v[168:169], v[144:145]
	v_pk_fma_f32 v[144:145], v[122:123], v[170:171], v[144:145]
	v_pk_fma_f32 v[144:145], v[124:125], v[172:173], v[144:145]
	v_pk_fma_f32 v[144:145], v[126:127], v[174:175], v[144:145]
	v_pk_fma_f32 v[144:145], v[128:129], v[176:177], v[144:145]
	v_pk_fma_f32 v[144:145], v[130:131], v[178:179], v[144:145]
	v_pk_fma_f32 v[144:145], v[132:133], v[180:181], v[144:145]
	v_pk_fma_f32 v[144:145], v[134:135], v[182:183], v[144:145]
	v_pk_fma_f32 v[144:145], v[136:137], v[184:185], v[144:145]
	v_pk_fma_f32 v[144:145], v[138:139], v[186:187], v[144:145]
	v_pk_fma_f32 v[144:145], v[140:141], v[188:189], v[144:145]
	v_pk_fma_f32 v[144:145], v[142:143], v[190:191], v[144:145]
	v_add_f32_e32 v147, v144, v145

.Lap0_aftl1:
	s_waitcnt vmcnt(21)
	v_lshlrev_b32_e32 v192, 23, v70
	v_cvt_scalef32_pk32_f32_fp6 v[112:143], v[64:69], v192
	s_bitcmp1_b32 s39, 31
	s_cbranch_scc1 .Lap0_cB2
	v_pk_mul_f32 v[144:145], v[112:113], v[4:5]
	v_pk_fma_f32 v[144:145], v[114:115], v[6:7], v[144:145]
	v_pk_fma_f32 v[144:145], v[116:117], v[8:9], v[144:145]
	v_pk_fma_f32 v[144:145], v[118:119], v[10:11], v[144:145]
	v_pk_fma_f32 v[144:145], v[120:121], v[12:13], v[144:145]
	v_pk_fma_f32 v[144:145], v[122:123], v[14:15], v[144:145]
	v_pk_fma_f32 v[144:145], v[124:125], v[16:17], v[144:145]
	v_pk_fma_f32 v[144:145], v[126:127], v[18:19], v[144:145]
	v_pk_fma_f32 v[144:145], v[128:129], v[20:21], v[144:145]
	v_pk_fma_f32 v[144:145], v[130:131], v[22:23], v[144:145]
	v_pk_fma_f32 v[144:145], v[132:133], v[24:25], v[144:145]
	v_pk_fma_f32 v[144:145], v[134:135], v[26:27], v[144:145]
	v_pk_fma_f32 v[144:145], v[136:137], v[28:29], v[144:145]
	v_pk_fma_f32 v[144:145], v[138:139], v[30:31], v[144:145]
	v_pk_fma_f32 v[144:145], v[140:141], v[32:33], v[144:145]
	v_pk_fma_f32 v[144:145], v[142:143], v[34:35], v[144:145]
	v_add_f32_e32 v148, v144, v145
	s_branch .Lap0_cD2
.Lap0_cB2:
	v_pk_mul_f32 v[144:145], v[112:113], v[160:161]
	v_pk_fma_f32 v[144:145], v[114:115], v[162:163], v[144:145]
	v_pk_fma_f32 v[144:145], v[116:117], v[164:165], v[144:145]
	v_pk_fma_f32 v[144:145], v[118:119], v[166:167], v[144:145]
	v_pk_fma_f32 v[144:145], v[120:121], v[168:169], v[144:145]
	v_pk_fma_f32 v[144:145], v[122:123], v[170:171], v[144:145]
	v_pk_fma_f32 v[144:145], v[124:125], v[172:173], v[144:145]
	v_pk_fma_f32 v[144:145], v[126:127], v[174:175], v[144:145]
	v_pk_fma_f32 v[144:145], v[128:129], v[176:177], v[144:145]
	v_pk_fma_f32 v[144:145], v[130:131], v[178:179], v[144:145]
	v_pk_fma_f32 v[144:145], v[132:133], v[180:181], v[144:145]
	v_pk_fma_f32 v[144:145], v[134:135], v[182:183], v[144:145]
	v_pk_fma_f32 v[144:145], v[136:137], v[184:185], v[144:145]
	v_pk_fma_f32 v[144:145], v[138:139], v[186:187], v[144:145]
	v_pk_fma_f32 v[144:145], v[140:141], v[188:189], v[144:145]
	v_pk_fma_f32 v[144:145], v[142:143], v[190:191], v[144:145]
	v_add_f32_e32 v148, v144, v145

.Lap0_aftl2:
	s_waitcnt vmcnt(21)
	v_lshlrev_b32_e32 v192, 23, v78
	v_cvt_scalef32_pk32_f32_fp6 v[112:143], v[72:77], v192
	s_bitcmp1_b32 s51, 31
	s_cbranch_scc1 .Lap0_cB3
	v_pk_mul_f32 v[144:145], v[112:113], v[4:5]
	v_pk_fma_f32 v[144:145], v[114:115], v[6:7], v[144:145]
	v_pk_fma_f32 v[144:145], v[116:117], v[8:9], v[144:145]
	v_pk_fma_f32 v[144:145], v[118:119], v[10:11], v[144:145]
	v_pk_fma_f32 v[144:145], v[120:121], v[12:13], v[144:145]
	v_pk_fma_f32 v[144:145], v[122:123], v[14:15], v[144:145]
	v_pk_fma_f32 v[144:145], v[124:125], v[16:17], v[144:145]
	v_pk_fma_f32 v[144:145], v[126:127], v[18:19], v[144:145]
	v_pk_fma_f32 v[144:145], v[128:129], v[20:21], v[144:145]
	v_pk_fma_f32 v[144:145], v[130:131], v[22:23], v[144:145]
	v_pk_fma_f32 v[144:145], v[132:133], v[24:25], v[144:145]
	v_pk_fma_f32 v[144:145], v[134:135], v[26:27], v[144:145]
	v_pk_fma_f32 v[144:145], v[136:137], v[28:29], v[144:145]
	v_pk_fma_f32 v[144:145], v[138:139], v[30:31], v[144:145]
	v_pk_fma_f32 v[144:145], v[140:141], v[32:33], v[144:145]
	v_pk_fma_f32 v[144:145], v[142:143], v[34:35], v[144:145]
	v_add_f32_e32 v149, v144, v145
	s_branch .Lap0_cD3
.Lap0_cB3:
	v_pk_mul_f32 v[144:145], v[112:113], v[160:161]
	v_pk_fma_f32 v[144:145], v[114:115], v[162:163], v[144:145]
	v_pk_fma_f32 v[144:145], v[116:117], v[164:165], v[144:145]
	v_pk_fma_f32 v[144:145], v[118:119], v[166:167], v[144:145]
	v_pk_fma_f32 v[144:145], v[120:121], v[168:169], v[144:145]
	v_pk_fma_f32 v[144:145], v[122:123], v[170:171], v[144:145]
	v_pk_fma_f32 v[144:145], v[124:125], v[172:173], v[144:145]
	v_pk_fma_f32 v[144:145], v[126:127], v[174:175], v[144:145]
	v_pk_fma_f32 v[144:145], v[128:129], v[176:177], v[144:145]
	v_pk_fma_f32 v[144:145], v[130:131], v[178:179], v[144:145]
	v_pk_fma_f32 v[144:145], v[132:133], v[180:181], v[144:145]
	v_pk_fma_f32 v[144:145], v[134:135], v[182:183], v[144:145]
	v_pk_fma_f32 v[144:145], v[136:137], v[184:185], v[144:145]
	v_pk_fma_f32 v[144:145], v[138:139], v[186:187], v[144:145]
	v_pk_fma_f32 v[144:145], v[140:141], v[188:189], v[144:145]
	v_pk_fma_f32 v[144:145], v[142:143], v[190:191], v[144:145]
	v_add_f32_e32 v149, v144, v145

.Lap0_aftl3:
	s_waitcnt vmcnt(21)
	v_lshlrev_b32_e32 v192, 23, v86
	v_cvt_scalef32_pk32_f32_fp6 v[112:143], v[80:85], v192
	s_bitcmp1_b32 s28, 31
	s_cbranch_scc1 .Lap0_cB4
	v_pk_mul_f32 v[144:145], v[112:113], v[4:5]
	v_pk_fma_f32 v[144:145], v[114:115], v[6:7], v[144:145]
	v_pk_fma_f32 v[144:145], v[116:117], v[8:9], v[144:145]
	v_pk_fma_f32 v[144:145], v[118:119], v[10:11], v[144:145]
	v_pk_fma_f32 v[144:145], v[120:121], v[12:13], v[144:145]
	v_pk_fma_f32 v[144:145], v[122:123], v[14:15], v[144:145]
	v_pk_fma_f32 v[144:145], v[124:125], v[16:17], v[144:145]
	v_pk_fma_f32 v[144:145], v[126:127], v[18:19], v[144:145]
	v_pk_fma_f32 v[144:145], v[128:129], v[20:21], v[144:145]
	v_pk_fma_f32 v[144:145], v[130:131], v[22:23], v[144:145]
	v_pk_fma_f32 v[144:145], v[132:133], v[24:25], v[144:145]
	v_pk_fma_f32 v[144:145], v[134:135], v[26:27], v[144:145]
	v_pk_fma_f32 v[144:145], v[136:137], v[28:29], v[144:145]
	v_pk_fma_f32 v[144:145], v[138:139], v[30:31], v[144:145]
	v_pk_fma_f32 v[144:145], v[140:141], v[32:33], v[144:145]
	v_pk_fma_f32 v[144:145], v[142:143], v[34:35], v[144:145]
	v_add_f32_e32 v150, v144, v145
	s_branch .Lap0_cD4
.Lap0_cB4:
	v_pk_mul_f32 v[144:145], v[112:113], v[160:161]
	v_pk_fma_f32 v[144:145], v[114:115], v[162:163], v[144:145]
	v_pk_fma_f32 v[144:145], v[116:117], v[164:165], v[144:145]
	v_pk_fma_f32 v[144:145], v[118:119], v[166:167], v[144:145]
	v_pk_fma_f32 v[144:145], v[120:121], v[168:169], v[144:145]
	v_pk_fma_f32 v[144:145], v[122:123], v[170:171], v[144:145]
	v_pk_fma_f32 v[144:145], v[124:125], v[172:173], v[144:145]
	v_pk_fma_f32 v[144:145], v[126:127], v[174:175], v[144:145]
	v_pk_fma_f32 v[144:145], v[128:129], v[176:177], v[144:145]
	v_pk_fma_f32 v[144:145], v[130:131], v[178:179], v[144:145]
	v_pk_fma_f32 v[144:145], v[132:133], v[180:181], v[144:145]
	v_pk_fma_f32 v[144:145], v[134:135], v[182:183], v[144:145]
	v_pk_fma_f32 v[144:145], v[136:137], v[184:185], v[144:145]
	v_pk_fma_f32 v[144:145], v[138:139], v[186:187], v[144:145]
	v_pk_fma_f32 v[144:145], v[140:141], v[188:189], v[144:145]
	v_pk_fma_f32 v[144:145], v[142:143], v[190:191], v[144:145]
	v_add_f32_e32 v150, v144, v145

.Lap0_aftl4:
	s_waitcnt vmcnt(21)
	v_lshlrev_b32_e32 v192, 23, v94
	v_cvt_scalef32_pk32_f32_fp6 v[112:143], v[88:93], v192
	s_bitcmp1_b32 s30, 31
	s_cbranch_scc1 .Lap0_cB5
	v_pk_mul_f32 v[144:145], v[112:113], v[4:5]
	v_pk_fma_f32 v[144:145], v[114:115], v[6:7], v[144:145]
	v_pk_fma_f32 v[144:145], v[116:117], v[8:9], v[144:145]
	v_pk_fma_f32 v[144:145], v[118:119], v[10:11], v[144:145]
	v_pk_fma_f32 v[144:145], v[120:121], v[12:13], v[144:145]
	v_pk_fma_f32 v[144:145], v[122:123], v[14:15], v[144:145]
	v_pk_fma_f32 v[144:145], v[124:125], v[16:17], v[144:145]
	v_pk_fma_f32 v[144:145], v[126:127], v[18:19], v[144:145]
	v_pk_fma_f32 v[144:145], v[128:129], v[20:21], v[144:145]
	v_pk_fma_f32 v[144:145], v[130:131], v[22:23], v[144:145]
	v_pk_fma_f32 v[144:145], v[132:133], v[24:25], v[144:145]
	v_pk_fma_f32 v[144:145], v[134:135], v[26:27], v[144:145]
	v_pk_fma_f32 v[144:145], v[136:137], v[28:29], v[144:145]
	v_pk_fma_f32 v[144:145], v[138:139], v[30:31], v[144:145]
	v_pk_fma_f32 v[144:145], v[140:141], v[32:33], v[144:145]
	v_pk_fma_f32 v[144:145], v[142:143], v[34:35], v[144:145]
	v_add_f32_e32 v151, v144, v145
	s_branch .Lap0_cD5
.Lap0_cB5:
	v_pk_mul_f32 v[144:145], v[112:113], v[160:161]
	v_pk_fma_f32 v[144:145], v[114:115], v[162:163], v[144:145]
	v_pk_fma_f32 v[144:145], v[116:117], v[164:165], v[144:145]
	v_pk_fma_f32 v[144:145], v[118:119], v[166:167], v[144:145]
	v_pk_fma_f32 v[144:145], v[120:121], v[168:169], v[144:145]
	v_pk_fma_f32 v[144:145], v[122:123], v[170:171], v[144:145]
	v_pk_fma_f32 v[144:145], v[124:125], v[172:173], v[144:145]
	v_pk_fma_f32 v[144:145], v[126:127], v[174:175], v[144:145]
	v_pk_fma_f32 v[144:145], v[128:129], v[176:177], v[144:145]
	v_pk_fma_f32 v[144:145], v[130:131], v[178:179], v[144:145]
	v_pk_fma_f32 v[144:145], v[132:133], v[180:181], v[144:145]
	v_pk_fma_f32 v[144:145], v[134:135], v[182:183], v[144:145]
	v_pk_fma_f32 v[144:145], v[136:137], v[184:185], v[144:145]
	v_pk_fma_f32 v[144:145], v[138:139], v[186:187], v[144:145]
	v_pk_fma_f32 v[144:145], v[140:141], v[188:189], v[144:145]
	v_pk_fma_f32 v[144:145], v[142:143], v[190:191], v[144:145]
	v_add_f32_e32 v151, v144, v145

.Lap0_aftl5:
	s_waitcnt vmcnt(21)
	v_lshlrev_b32_e32 v192, 23, v102
	v_cvt_scalef32_pk32_f32_fp6 v[112:143], v[96:101], v192
	s_bitcmp1_b32 s36, 31
	s_cbranch_scc1 .Lap0_cB6
	v_pk_mul_f32 v[144:145], v[112:113], v[4:5]
	v_pk_fma_f32 v[144:145], v[114:115], v[6:7], v[144:145]
	v_pk_fma_f32 v[144:145], v[116:117], v[8:9], v[144:145]
	v_pk_fma_f32 v[144:145], v[118:119], v[10:11], v[144:145]
	v_pk_fma_f32 v[144:145], v[120:121], v[12:13], v[144:145]
	v_pk_fma_f32 v[144:145], v[122:123], v[14:15], v[144:145]
	v_pk_fma_f32 v[144:145], v[124:125], v[16:17], v[144:145]
	v_pk_fma_f32 v[144:145], v[126:127], v[18:19], v[144:145]
	v_pk_fma_f32 v[144:145], v[128:129], v[20:21], v[144:145]
	v_pk_fma_f32 v[144:145], v[130:131], v[22:23], v[144:145]
	v_pk_fma_f32 v[144:145], v[132:133], v[24:25], v[144:145]
	v_pk_fma_f32 v[144:145], v[134:135], v[26:27], v[144:145]
	v_pk_fma_f32 v[144:145], v[136:137], v[28:29], v[144:145]
	v_pk_fma_f32 v[144:145], v[138:139], v[30:31], v[144:145]
	v_pk_fma_f32 v[144:145], v[140:141], v[32:33], v[144:145]
	v_pk_fma_f32 v[144:145], v[142:143], v[34:35], v[144:145]
	v_add_f32_e32 v152, v144, v145
	s_branch .Lap0_cD6
.Lap0_cB6:
	v_pk_mul_f32 v[144:145], v[112:113], v[160:161]
	v_pk_fma_f32 v[144:145], v[114:115], v[162:163], v[144:145]
	v_pk_fma_f32 v[144:145], v[116:117], v[164:165], v[144:145]
	v_pk_fma_f32 v[144:145], v[118:119], v[166:167], v[144:145]
	v_pk_fma_f32 v[144:145], v[120:121], v[168:169], v[144:145]
	v_pk_fma_f32 v[144:145], v[122:123], v[170:171], v[144:145]
	v_pk_fma_f32 v[144:145], v[124:125], v[172:173], v[144:145]
	v_pk_fma_f32 v[144:145], v[126:127], v[174:175], v[144:145]
	v_pk_fma_f32 v[144:145], v[128:129], v[176:177], v[144:145]
	v_pk_fma_f32 v[144:145], v[130:131], v[178:179], v[144:145]
	v_pk_fma_f32 v[144:145], v[132:133], v[180:181], v[144:145]
	v_pk_fma_f32 v[144:145], v[134:135], v[182:183], v[144:145]
	v_pk_fma_f32 v[144:145], v[136:137], v[184:185], v[144:145]
	v_pk_fma_f32 v[144:145], v[138:139], v[186:187], v[144:145]
	v_pk_fma_f32 v[144:145], v[140:141], v[188:189], v[144:145]
	v_pk_fma_f32 v[144:145], v[142:143], v[190:191], v[144:145]
	v_add_f32_e32 v152, v144, v145

.Lap0_aftl6:
	s_waitcnt vmcnt(21)
	v_lshlrev_b32_e32 v192, 23, v110
	v_cvt_scalef32_pk32_f32_fp6 v[112:143], v[104:109], v192
	s_bitcmp1_b32 s37, 31
	s_cbranch_scc1 .Lap0_cB7
	v_pk_mul_f32 v[144:145], v[112:113], v[4:5]
	v_pk_fma_f32 v[144:145], v[114:115], v[6:7], v[144:145]
	v_pk_fma_f32 v[144:145], v[116:117], v[8:9], v[144:145]
	v_pk_fma_f32 v[144:145], v[118:119], v[10:11], v[144:145]
	v_pk_fma_f32 v[144:145], v[120:121], v[12:13], v[144:145]
	v_pk_fma_f32 v[144:145], v[122:123], v[14:15], v[144:145]
	v_pk_fma_f32 v[144:145], v[124:125], v[16:17], v[144:145]
	v_pk_fma_f32 v[144:145], v[126:127], v[18:19], v[144:145]
	v_pk_fma_f32 v[144:145], v[128:129], v[20:21], v[144:145]
	v_pk_fma_f32 v[144:145], v[130:131], v[22:23], v[144:145]
	v_pk_fma_f32 v[144:145], v[132:133], v[24:25], v[144:145]
	v_pk_fma_f32 v[144:145], v[134:135], v[26:27], v[144:145]
	v_pk_fma_f32 v[144:145], v[136:137], v[28:29], v[144:145]
	v_pk_fma_f32 v[144:145], v[138:139], v[30:31], v[144:145]
	v_pk_fma_f32 v[144:145], v[140:141], v[32:33], v[144:145]
	v_pk_fma_f32 v[144:145], v[142:143], v[34:35], v[144:145]
	v_add_f32_e32 v153, v144, v145
	s_branch .Lap0_cD7
.Lap0_cB7:
	v_pk_mul_f32 v[144:145], v[112:113], v[160:161]
	v_pk_fma_f32 v[144:145], v[114:115], v[162:163], v[144:145]
	v_pk_fma_f32 v[144:145], v[116:117], v[164:165], v[144:145]
	v_pk_fma_f32 v[144:145], v[118:119], v[166:167], v[144:145]
	v_pk_fma_f32 v[144:145], v[120:121], v[168:169], v[144:145]
	v_pk_fma_f32 v[144:145], v[122:123], v[170:171], v[144:145]
	v_pk_fma_f32 v[144:145], v[124:125], v[172:173], v[144:145]
	v_pk_fma_f32 v[144:145], v[126:127], v[174:175], v[144:145]
	v_pk_fma_f32 v[144:145], v[128:129], v[176:177], v[144:145]
	v_pk_fma_f32 v[144:145], v[130:131], v[178:179], v[144:145]
	v_pk_fma_f32 v[144:145], v[132:133], v[180:181], v[144:145]
	v_pk_fma_f32 v[144:145], v[134:135], v[182:183], v[144:145]
	v_pk_fma_f32 v[144:145], v[136:137], v[184:185], v[144:145]
	v_pk_fma_f32 v[144:145], v[138:139], v[186:187], v[144:145]
	v_pk_fma_f32 v[144:145], v[140:141], v[188:189], v[144:145]
	v_pk_fma_f32 v[144:145], v[142:143], v[190:191], v[144:145]
	v_add_f32_e32 v153, v144, v145

; #define PB_FENCE asm volatile("" ::: "memory")
; __device__ __forceinline__ void ph_peer_apply(const Params& P, int layer, float* xlat, float* xctx_in, float* xctx_out, int nrows, bool write_next, char* smem, float* xlat_out = nullptr) {
;     ...
;     PB_LOAD(bufA, tv, 0);
;     for (int gq = 0; gq < NG; gq += 2) {
;       PB_LOAD(bufB, tv, gq + 1); PB_FENCE;
;       PB_ACC(bufA, gq);
;       if (gq + 2 < NG) PB_LOAD(bufA, tv, gq + 2);
;       PB_FENCE;
;       PB_ACC(bufB, gq + 1);
;     }
.Lap0_s2_loop3:
	v_readlane_b32 s36, v42, s37
	s_add_u32 s37, s37, 1
	s_waitcnt vmcnt(21)
	v_lshlrev_b32_e32 v192, 23, v54
	v_cvt_scalef32_pk32_f32_fp6 v[112:143], v[48:53], v192
	v_pk_fma_f32 v[160:161], v[112:113], s[36:37], v[160:161] op_sel_hi:[1,0,1]
	v_pk_fma_f32 v[162:163], v[114:115], s[36:37], v[162:163] op_sel_hi:[1,0,1]
	v_pk_fma_f32 v[164:165], v[116:117], s[36:37], v[164:165] op_sel_hi:[1,0,1]
	v_pk_fma_f32 v[166:167], v[118:119], s[36:37], v[166:167] op_sel_hi:[1,0,1]
	v_pk_fma_f32 v[168:169], v[120:121], s[36:37], v[168:169] op_sel_hi:[1,0,1]
	v_pk_fma_f32 v[170:171], v[122:123], s[36:37], v[170:171] op_sel_hi:[1,0,1]
	v_pk_fma_f32 v[172:173], v[124:125], s[36:37], v[172:173] op_sel_hi:[1,0,1]
	v_pk_fma_f32 v[174:175], v[126:127], s[36:37], v[174:175] op_sel_hi:[1,0,1]
	v_pk_fma_f32 v[176:177], v[128:129], s[36:37], v[176:177] op_sel_hi:[1,0,1]
	v_pk_fma_f32 v[178:179], v[130:131], s[36:37], v[178:179] op_sel_hi:[1,0,1]
	v_pk_fma_f32 v[180:181], v[132:133], s[36:37], v[180:181] op_sel_hi:[1,0,1]
	v_pk_fma_f32 v[182:183], v[134:135], s[36:37], v[182:183] op_sel_hi:[1,0,1]
	v_pk_fma_f32 v[184:185], v[136:137], s[36:37], v[184:185] op_sel_hi:[1,0,1]
	v_pk_fma_f32 v[186:187], v[138:139], s[36:37], v[186:187] op_sel_hi:[1,0,1]
	v_pk_fma_f32 v[188:189], v[140:141], s[36:37], v[188:189] op_sel_hi:[1,0,1]
	v_pk_fma_f32 v[190:191], v[142:143], s[36:37], v[190:191] op_sel_hi:[1,0,1]
	v_readlane_b32 s29, v36, s28
	s_add_u32 s28, s28, 1
	s_mul_hi_u32 s27, s29, 0x640
	s_mul_i32 s26, s29, 0x640
	s_add_u32 s26, s18, s26
	s_addc_u32 s27, s19, s27
	global_load_dwordx4 v[48:51], v2, s[26:27]
	global_load_dwordx2 v[52:53], v2, s[26:27] offset:16
	global_load_ubyte v54, v3, s[26:27]
	v_readlane_b32 s36, v42, s37
	s_add_u32 s37, s37, 1
	s_waitcnt vmcnt(21)
	v_lshlrev_b32_e32 v192, 23, v62
	v_cvt_scalef32_pk32_f32_fp6 v[112:143], v[56:61], v192
	v_pk_fma_f32 v[160:161], v[112:113], s[36:37], v[160:161] op_sel_hi:[1,0,1]
	v_pk_fma_f32 v[162:163], v[114:115], s[36:37], v[162:163] op_sel_hi:[1,0,1]
	v_pk_fma_f32 v[164:165], v[116:117], s[36:37], v[164:165] op_sel_hi:[1,0,1]
	v_pk_fma_f32 v[166:167], v[118:119], s[36:37], v[166:167] op_sel_hi:[1,0,1]
	v_pk_fma_f32 v[168:169], v[120:121], s[36:37], v[168:169] op_sel_hi:[1,0,1]
	v_pk_fma_f32 v[170:171], v[122:123], s[36:37], v[170:171] op_sel_hi:[1,0,1]
	v_pk_fma_f32 v[172:173], v[124:125], s[36:37], v[172:173] op_sel_hi:[1,0,1]
	v_pk_fma_f32 v[174:175], v[126:127], s[36:37], v[174:175] op_sel_hi:[1,0,1]
	v_pk_fma_f32 v[176:177], v[128:129], s[36:37], v[176:177] op_sel_hi:[1,0,1]
	v_pk_fma_f32 v[178:179], v[130:131], s[36:37], v[178:179] op_sel_hi:[1,0,1]
	v_pk_fma_f32 v[180:181], v[132:133], s[36:37], v[180:181] op_sel_hi:[1,0,1]
	v_pk_fma_f32 v[182:183], v[134:135], s[36:37], v[182:183] op_sel_hi:[1,0,1]
	v_pk_fma_f32 v[184:185], v[136:137], s[36:37], v[184:185] op_sel_hi:[1,0,1]
	v_pk_fma_f32 v[186:187], v[138:139], s[36:37], v[186:187] op_sel_hi:[1,0,1]
	v_pk_fma_f32 v[188:189], v[140:141], s[36:37], v[188:189] op_sel_hi:[1,0,1]
	v_pk_fma_f32 v[190:191], v[142:143], s[36:37], v[190:191] op_sel_hi:[1,0,1]
	v_readlane_b32 s29, v36, s28
	s_add_u32 s28, s28, 1
	s_mul_hi_u32 s27, s29, 0x640
	s_mul_i32 s26, s29, 0x640
	s_add_u32 s26, s18, s26
	s_addc_u32 s27, s19, s27
	global_load_dwordx4 v[56:59], v2, s[26:27]
	global_load_dwordx2 v[60:61], v2, s[26:27] offset:16
	global_load_ubyte v62, v3, s[26:27]
	v_readlane_b32 s36, v42, s37
	s_add_u32 s37, s37, 1
	s_waitcnt vmcnt(21)
	v_lshlrev_b32_e32 v192, 23, v70
	v_cvt_scalef32_pk32_f32_fp6 v[112:143], v[64:69], v192
	v_pk_fma_f32 v[160:161], v[112:113], s[36:37], v[160:161] op_sel_hi:[1,0,1]
	v_pk_fma_f32 v[162:163], v[114:115], s[36:37], v[162:163] op_sel_hi:[1,0,1]
	v_pk_fma_f32 v[164:165], v[116:117], s[36:37], v[164:165] op_sel_hi:[1,0,1]
	v_pk_fma_f32 v[166:167], v[118:119], s[36:37], v[166:167] op_sel_hi:[1,0,1]
	v_pk_fma_f32 v[168:169], v[120:121], s[36:37], v[168:169] op_sel_hi:[1,0,1]
	v_pk_fma_f32 v[170:171], v[122:123], s[36:37], v[170:171] op_sel_hi:[1,0,1]
	v_pk_fma_f32 v[172:173], v[124:125], s[36:37], v[172:173] op_sel_hi:[1,0,1]
	v_pk_fma_f32 v[174:175], v[126:127], s[36:37], v[174:175] op_sel_hi:[1,0,1]
	v_pk_fma_f32 v[176:177], v[128:129], s[36:37], v[176:177] op_sel_hi:[1,0,1]
	v_pk_fma_f32 v[178:179], v[130:131], s[36:37], v[178:179] op_sel_hi:[1,0,1]
	v_pk_fma_f32 v[180:181], v[132:133], s[36:37], v[180:181] op_sel_hi:[1,0,1]
	v_pk_fma_f32 v[182:183], v[134:135], s[36:37], v[182:183] op_sel_hi:[1,0,1]
	v_pk_fma_f32 v[184:185], v[136:137], s[36:37], v[184:185] op_sel_hi:[1,0,1]
	v_pk_fma_f32 v[186:187], v[138:139], s[36:37], v[186:187] op_sel_hi:[1,0,1]
	v_pk_fma_f32 v[188:189], v[140:141], s[36:37], v[188:189] op_sel_hi:[1,0,1]
	v_pk_fma_f32 v[190:191], v[142:143], s[36:37], v[190:191] op_sel_hi:[1,0,1]
	v_readlane_b32 s29, v36, s28
	s_add_u32 s28, s28, 1
	s_mul_hi_u32 s27, s29, 0x640
	s_mul_i32 s26, s29, 0x640
	s_add_u32 s26, s18, s26
	s_addc_u32 s27, s19, s27
	global_load_dwordx4 v[64:67], v2, s[26:27]
	global_load_dwordx2 v[68:69], v2, s[26:27] offset:16
	global_load_ubyte v70, v3, s[26:27]
	v_readlane_b32 s36, v42, s37
	s_add_u32 s37, s37, 1
	s_waitcnt vmcnt(21)
; #define PB_FENCE asm volatile("" ::: "memory")
; __device__ __forceinline__ void ph_peer_apply(const Params& P, int layer, float* xlat, float* xctx_in, float* xctx_out, int nrows, bool write_next, char* smem, float* xlat_out = nullptr) {
;     ...
;     PB_LOAD(bufA, tv, 0);
;     for (int gq = 0; gq < NG; gq += 2) {
;       PB_LOAD(bufB, tv, gq + 1); PB_FENCE;
;       PB_ACC(bufA, gq);
;       if (gq + 2 < NG) PB_LOAD(bufA, tv, gq + 2);
;       PB_FENCE;
;       PB_ACC(bufB, gq + 1);
;     }
	v_lshlrev_b32_e32 v192, 23, v78
	v_cvt_scalef32_pk32_f32_fp6 v[112:143], v[72:77], v192
	v_pk_fma_f32 v[160:161], v[112:113], s[36:37], v[160:161] op_sel_hi:[1,0,1]
	v_pk_fma_f32 v[162:163], v[114:115], s[36:37], v[162:163] op_sel_hi:[1,0,1]
	v_pk_fma_f32 v[164:165], v[116:117], s[36:37], v[164:165] op_sel_hi:[1,0,1]
	v_pk_fma_f32 v[166:167], v[118:119], s[36:37], v[166:167] op_sel_hi:[1,0,1]
	v_pk_fma_f32 v[168:169], v[120:121], s[36:37], v[168:169] op_sel_hi:[1,0,1]
	v_pk_fma_f32 v[170:171], v[122:123], s[36:37], v[170:171] op_sel_hi:[1,0,1]
	v_pk_fma_f32 v[172:173], v[124:125], s[36:37], v[172:173] op_sel_hi:[1,0,1]
	v_pk_fma_f32 v[174:175], v[126:127], s[36:37], v[174:175] op_sel_hi:[1,0,1]
	v_pk_fma_f32 v[176:177], v[128:129], s[36:37], v[176:177] op_sel_hi:[1,0,1]
	v_pk_fma_f32 v[178:179], v[130:131], s[36:37], v[178:179] op_sel_hi:[1,0,1]
	v_pk_fma_f32 v[180:181], v[132:133], s[36:37], v[180:181] op_sel_hi:[1,0,1]
	v_pk_fma_f32 v[182:183], v[134:135], s[36:37], v[182:183] op_sel_hi:[1,0,1]
	v_pk_fma_f32 v[184:185], v[136:137], s[36:37], v[184:185] op_sel_hi:[1,0,1]
	v_pk_fma_f32 v[186:187], v[138:139], s[36:37], v[186:187] op_sel_hi:[1,0,1]
	v_pk_fma_f32 v[188:189], v[140:141], s[36:37], v[188:189] op_sel_hi:[1,0,1]
	v_pk_fma_f32 v[190:191], v[142:143], s[36:37], v[190:191] op_sel_hi:[1,0,1]
	v_readlane_b32 s29, v36, s28
	s_add_u32 s28, s28, 1
	s_mul_hi_u32 s27, s29, 0x640
	s_mul_i32 s26, s29, 0x640
	s_add_u32 s26, s18, s26
	s_addc_u32 s27, s19, s27
	global_load_dwordx4 v[72:75], v2, s[26:27]
	global_load_dwordx2 v[76:77], v2, s[26:27] offset:16
	global_load_ubyte v78, v3, s[26:27]
	v_readlane_b32 s36, v42, s37
	s_add_u32 s37, s37, 1
	s_waitcnt vmcnt(21)
	v_lshlrev_b32_e32 v192, 23, v86
	v_cvt_scalef32_pk32_f32_fp6 v[112:143], v[80:85], v192
	v_pk_fma_f32 v[160:161], v[112:113], s[36:37], v[160:161] op_sel_hi:[1,0,1]
	v_pk_fma_f32 v[162:163], v[114:115], s[36:37], v[162:163] op_sel_hi:[1,0,1]
	v_pk_fma_f32 v[164:165], v[116:117], s[36:37], v[164:165] op_sel_hi:[1,0,1]
	v_pk_fma_f32 v[166:167], v[118:119], s[36:37], v[166:167] op_sel_hi:[1,0,1]
	v_pk_fma_f32 v[168:169], v[120:121], s[36:37], v[168:169] op_sel_hi:[1,0,1]
	v_pk_fma_f32 v[170:171], v[122:123], s[36:37], v[170:171] op_sel_hi:[1,0,1]
	v_pk_fma_f32 v[172:173], v[124:125], s[36:37], v[172:173] op_sel_hi:[1,0,1]
	v_pk_fma_f32 v[174:175], v[126:127], s[36:37], v[174:175] op_sel_hi:[1,0,1]
	v_pk_fma_f32 v[176:177], v[128:129], s[36:37], v[176:177] op_sel_hi:[1,0,1]
	v_pk_fma_f32 v[178:179], v[130:131], s[36:37], v[178:179] op_sel_hi:[1,0,1]
	v_pk_fma_f32 v[180:181], v[132:133], s[36:37], v[180:181] op_sel_hi:[1,0,1]
	v_pk_fma_f32 v[182:183], v[134:135], s[36:37], v[182:183] op_sel_hi:[1,0,1]
	v_pk_fma_f32 v[184:185], v[136:137], s[36:37], v[184:185] op_sel_hi:[1,0,1]
	v_pk_fma_f32 v[186:187], v[138:139], s[36:37], v[186:187] op_sel_hi:[1,0,1]
	v_pk_fma_f32 v[188:189], v[140:141], s[36:37], v[188:189] op_sel_hi:[1,0,1]
	v_pk_fma_f32 v[190:191], v[142:143], s[36:37], v[190:191] op_sel_hi:[1,0,1]
	v_readlane_b32 s29, v36, s28
	s_add_u32 s28, s28, 1
	s_mul_hi_u32 s27, s29, 0x640
	s_mul_i32 s26, s29, 0x640
	s_add_u32 s26, s18, s26
	s_addc_u32 s27, s19, s27
	global_load_dwordx4 v[80:83], v2, s[26:27]
	global_load_dwordx2 v[84:85], v2, s[26:27] offset:16
	global_load_ubyte v86, v3, s[26:27]
	v_readlane_b32 s36, v42, s37
	s_add_u32 s37, s37, 1
	s_waitcnt vmcnt(21)
	v_lshlrev_b32_e32 v192, 23, v94
	v_cvt_scalef32_pk32_f32_fp6 v[112:143], v[88:93], v192
	v_pk_fma_f32 v[160:161], v[112:113], s[36:37], v[160:161] op_sel_hi:[1,0,1]
	v_pk_fma_f32 v[162:163], v[114:115], s[36:37], v[162:163] op_sel_hi:[1,0,1]
	v_pk_fma_f32 v[164:165], v[116:117], s[36:37], v[164:165] op_sel_hi:[1,0,1]
	v_pk_fma_f32 v[166:167], v[118:119], s[36:37], v[166:167] op_sel_hi:[1,0,1]
	v_pk_fma_f32 v[168:169], v[120:121], s[36:37], v[168:169] op_sel_hi:[1,0,1]
	v_pk_fma_f32 v[170:171], v[122:123], s[36:37], v[170:171] op_sel_hi:[1,0,1]
	v_pk_fma_f32 v[172:173], v[124:125], s[36:37], v[172:173] op_sel_hi:[1,0,1]
	v_pk_fma_f32 v[174:175], v[126:127], s[36:37], v[174:175] op_sel_hi:[1,0,1]
	v_pk_fma_f32 v[176:177], v[128:129], s[36:37], v[176:177] op_sel_hi:[1,0,1]
	v_pk_fma_f32 v[178:179], v[130:131], s[36:37], v[178:179] op_sel_hi:[1,0,1]
	v_pk_fma_f32 v[180:181], v[132:133], s[36:37], v[180:181] op_sel_hi:[1,0,1]
	v_pk_fma_f32 v[182:183], v[134:135], s[36:37], v[182:183] op_sel_hi:[1,0,1]
	v_pk_fma_f32 v[184:185], v[136:137], s[36:37], v[184:185] op_sel_hi:[1,0,1]
	v_pk_fma_f32 v[186:187], v[138:139], s[36:37], v[186:187] op_sel_hi:[1,0,1]
	v_pk_fma_f32 v[188:189], v[140:141], s[36:37], v[188:189] op_sel_hi:[1,0,1]
	v_pk_fma_f32 v[190:191], v[142:143], s[36:37], v[190:191] op_sel_hi:[1,0,1]
	v_readlane_b32 s29, v36, s28
	s_add_u32 s28, s28, 1
	s_mul_hi_u32 s27, s29, 0x640
	s_mul_i32 s26, s29, 0x640
	s_add_u32 s26, s18, s26
	s_addc_u32 s27, s19, s27
	global_load_dwordx4 v[88:91], v2, s[26:27]
	global_load_dwordx2 v[92:93], v2, s[26:27] offset:16
	global_load_ubyte v94, v3, s[26:27]
	v_readlane_b32 s36, v42, s37
	s_add_u32 s37, s37, 1
	s_waitcnt vmcnt(21)
; #define PB_FENCE asm volatile("" ::: "memory")
; __device__ __forceinline__ void ph_peer_apply(const Params& P, int layer, float* xlat, float* xctx_in, float* xctx_out, int nrows, bool write_next, char* smem, float* xlat_out = nullptr) {
;     ...
;     PB_LOAD(bufA, tv, 0);
;     for (int gq = 0; gq < NG; gq += 2) {
;       PB_LOAD(bufB, tv, gq + 1); PB_FENCE;
;       PB_ACC(bufA, gq);
;       if (gq + 2 < NG) PB_LOAD(bufA, tv, gq + 2);
;       PB_FENCE;
;       PB_ACC(bufB, gq + 1);
;     }
	v_lshlrev_b32_e32 v192, 23, v102
	v_cvt_scalef32_pk32_f32_fp6 v[112:143], v[96:101], v192
	v_pk_fma_f32 v[160:161], v[112:113], s[36:37], v[160:161] op_sel_hi:[1,0,1]
	v_pk_fma_f32 v[162:163], v[114:115], s[36:37], v[162:163] op_sel_hi:[1,0,1]
	v_pk_fma_f32 v[164:165], v[116:117], s[36:37], v[164:165] op_sel_hi:[1,0,1]
	v_pk_fma_f32 v[166:167], v[118:119], s[36:37], v[166:167] op_sel_hi:[1,0,1]
	v_pk_fma_f32 v[168:169], v[120:121], s[36:37], v[168:169] op_sel_hi:[1,0,1]
	v_pk_fma_f32 v[170:171], v[122:123], s[36:37], v[170:171] op_sel_hi:[1,0,1]
	v_pk_fma_f32 v[172:173], v[124:125], s[36:37], v[172:173] op_sel_hi:[1,0,1]
	v_pk_fma_f32 v[174:175], v[126:127], s[36:37], v[174:175] op_sel_hi:[1,0,1]
	v_pk_fma_f32 v[176:177], v[128:129], s[36:37], v[176:177] op_sel_hi:[1,0,1]
	v_pk_fma_f32 v[178:179], v[130:131], s[36:37], v[178:179] op_sel_hi:[1,0,1]
	v_pk_fma_f32 v[180:181], v[132:133], s[36:37], v[180:181] op_sel_hi:[1,0,1]
	v_pk_fma_f32 v[182:183], v[134:135], s[36:37], v[182:183] op_sel_hi:[1,0,1]
	v_pk_fma_f32 v[184:185], v[136:137], s[36:37], v[184:185] op_sel_hi:[1,0,1]
	v_pk_fma_f32 v[186:187], v[138:139], s[36:37], v[186:187] op_sel_hi:[1,0,1]
	v_pk_fma_f32 v[188:189], v[140:141], s[36:37], v[188:189] op_sel_hi:[1,0,1]
	v_pk_fma_f32 v[190:191], v[142:143], s[36:37], v[190:191] op_sel_hi:[1,0,1]
	v_readlane_b32 s29, v36, s28
	s_add_u32 s28, s28, 1
	s_mul_hi_u32 s27, s29, 0x640
	s_mul_i32 s26, s29, 0x640
	s_add_u32 s26, s18, s26
	s_addc_u32 s27, s19, s27
	global_load_dwordx4 v[96:99], v2, s[26:27]
	global_load_dwordx2 v[100:101], v2, s[26:27] offset:16
	global_load_ubyte v102, v3, s[26:27]
	v_readlane_b32 s36, v42, s37
	s_add_u32 s37, s37, 1
	s_waitcnt vmcnt(21)
	v_lshlrev_b32_e32 v192, 23, v110
	v_cvt_scalef32_pk32_f32_fp6 v[112:143], v[104:109], v192
	v_pk_fma_f32 v[160:161], v[112:113], s[36:37], v[160:161] op_sel_hi:[1,0,1]
	v_pk_fma_f32 v[162:163], v[114:115], s[36:37], v[162:163] op_sel_hi:[1,0,1]
	v_pk_fma_f32 v[164:165], v[116:117], s[36:37], v[164:165] op_sel_hi:[1,0,1]
	v_pk_fma_f32 v[166:167], v[118:119], s[36:37], v[166:167] op_sel_hi:[1,0,1]
	v_pk_fma_f32 v[168:169], v[120:121], s[36:37], v[168:169] op_sel_hi:[1,0,1]
	v_pk_fma_f32 v[170:171], v[122:123], s[36:37], v[170:171] op_sel_hi:[1,0,1]
	v_pk_fma_f32 v[172:173], v[124:125], s[36:37], v[172:173] op_sel_hi:[1,0,1]
	v_pk_fma_f32 v[174:175], v[126:127], s[36:37], v[174:175] op_sel_hi:[1,0,1]
	v_pk_fma_f32 v[176:177], v[128:129], s[36:37], v[176:177] op_sel_hi:[1,0,1]
	v_pk_fma_f32 v[178:179], v[130:131], s[36:37], v[178:179] op_sel_hi:[1,0,1]
	v_pk_fma_f32 v[180:181], v[132:133], s[36:37], v[180:181] op_sel_hi:[1,0,1]
	v_pk_fma_f32 v[182:183], v[134:135], s[36:37], v[182:183] op_sel_hi:[1,0,1]
	v_pk_fma_f32 v[184:185], v[136:137], s[36:37], v[184:185] op_sel_hi:[1,0,1]
	v_pk_fma_f32 v[186:187], v[138:139], s[36:37], v[186:187] op_sel_hi:[1,0,1]
	v_pk_fma_f32 v[188:189], v[140:141], s[36:37], v[188:189] op_sel_hi:[1,0,1]
	v_pk_fma_f32 v[190:191], v[142:143], s[36:37], v[190:191] op_sel_hi:[1,0,1]
	v_readlane_b32 s29, v36, s28
	s_add_u32 s28, s28, 1
	s_mul_hi_u32 s27, s29, 0x640
	s_mul_i32 s26, s29, 0x640
	s_add_u32 s26, s18, s26
	s_addc_u32 s27, s19, s27
	global_load_dwordx4 v[104:107], v2, s[26:27]
	global_load_dwordx2 v[108:109], v2, s[26:27] offset:16
	global_load_ubyte v110, v3, s[26:27]
	s_sub_u32 s30, s30, 1
	s_cmp_lg_u32 s30, 0
	s_cbranch_scc1 .Lap0_s2_loop3
	v_readlane_b32 s36, v42, s37
	s_add_u32 s37, s37, 1
	s_waitcnt vmcnt(21)
	v_lshlrev_b32_e32 v192, 23, v54
	v_cvt_scalef32_pk32_f32_fp6 v[112:143], v[48:53], v192
	v_pk_fma_f32 v[160:161], v[112:113], s[36:37], v[160:161] op_sel_hi:[1,0,1]
	v_pk_fma_f32 v[162:163], v[114:115], s[36:37], v[162:163] op_sel_hi:[1,0,1]
	v_pk_fma_f32 v[164:165], v[116:117], s[36:37], v[164:165] op_sel_hi:[1,0,1]
	v_pk_fma_f32 v[166:167], v[118:119], s[36:37], v[166:167] op_sel_hi:[1,0,1]
	v_pk_fma_f32 v[168:169], v[120:121], s[36:37], v[168:169] op_sel_hi:[1,0,1]
	v_pk_fma_f32 v[170:171], v[122:123], s[36:37], v[170:171] op_sel_hi:[1,0,1]
	v_pk_fma_f32 v[172:173], v[124:125], s[36:37], v[172:173] op_sel_hi:[1,0,1]
	v_pk_fma_f32 v[174:175], v[126:127], s[36:37], v[174:175] op_sel_hi:[1,0,1]
	v_pk_fma_f32 v[176:177], v[128:129], s[36:37], v[176:177] op_sel_hi:[1,0,1]
	v_pk_fma_f32 v[178:179], v[130:131], s[36:37], v[178:179] op_sel_hi:[1,0,1]
	v_pk_fma_f32 v[180:181], v[132:133], s[36:37], v[180:181] op_sel_hi:[1,0,1]
	v_pk_fma_f32 v[182:183], v[134:135], s[36:37], v[182:183] op_sel_hi:[1,0,1]
	v_pk_fma_f32 v[184:185], v[136:137], s[36:37], v[184:185] op_sel_hi:[1,0,1]
	v_pk_fma_f32 v[186:187], v[138:139], s[36:37], v[186:187] op_sel_hi:[1,0,1]
	v_pk_fma_f32 v[188:189], v[140:141], s[36:37], v[188:189] op_sel_hi:[1,0,1]
	v_pk_fma_f32 v[190:191], v[142:143], s[36:37], v[190:191] op_sel_hi:[1,0,1]
	v_readlane_b32 s36, v42, s37
	s_add_u32 s37, s37, 1
	s_waitcnt vmcnt(18)
	v_lshlrev_b32_e32 v192, 23, v62
	v_cvt_scalef32_pk32_f32_fp6 v[112:143], v[56:61], v192
	v_pk_fma_f32 v[160:161], v[112:113], s[36:37], v[160:161] op_sel_hi:[1,0,1]
	v_pk_fma_f32 v[162:163], v[114:115], s[36:37], v[162:163] op_sel_hi:[1,0,1]
	v_pk_fma_f32 v[164:165], v[116:117], s[36:37], v[164:165] op_sel_hi:[1,0,1]
	v_pk_fma_f32 v[166:167], v[118:119], s[36:37], v[166:167] op_sel_hi:[1,0,1]
	v_pk_fma_f32 v[168:169], v[120:121], s[36:37], v[168:169] op_sel_hi:[1,0,1]
	v_pk_fma_f32 v[170:171], v[122:123], s[36:37], v[170:171] op_sel_hi:[1,0,1]
	v_pk_fma_f32 v[172:173], v[124:125], s[36:37], v[172:173] op_sel_hi:[1,0,1]
	v_pk_fma_f32 v[174:175], v[126:127], s[36:37], v[174:175] op_sel_hi:[1,0,1]
	v_pk_fma_f32 v[176:177], v[128:129], s[36:37], v[176:177] op_sel_hi:[1,0,1]
	v_pk_fma_f32 v[178:179], v[130:131], s[36:37], v[178:179] op_sel_hi:[1,0,1]
	v_pk_fma_f32 v[180:181], v[132:133], s[36:37], v[180:181] op_sel_hi:[1,0,1]
	v_pk_fma_f32 v[182:183], v[134:135], s[36:37], v[182:183] op_sel_hi:[1,0,1]
	v_pk_fma_f32 v[184:185], v[136:137], s[36:37], v[184:185] op_sel_hi:[1,0,1]
	v_pk_fma_f32 v[186:187], v[138:139], s[36:37], v[186:187] op_sel_hi:[1,0,1]
	v_pk_fma_f32 v[188:189], v[140:141], s[36:37], v[188:189] op_sel_hi:[1,0,1]
	v_pk_fma_f32 v[190:191], v[142:143], s[36:37], v[190:191] op_sel_hi:[1,0,1]
	v_readlane_b32 s36, v42, s37
	s_add_u32 s37, s37, 1
	s_waitcnt vmcnt(15)
; #define PB_FENCE asm volatile("" ::: "memory")
; __device__ __forceinline__ void ph_peer_apply(const Params& P, int layer, float* xlat, float* xctx_in, float* xctx_out, int nrows, bool write_next, char* smem, float* xlat_out = nullptr) {
;     ...
;     PB_LOAD(bufA, tv, 0);
;     for (int gq = 0; gq < NG; gq += 2) {
;       PB_LOAD(bufB, tv, gq + 1); PB_FENCE;
;       PB_ACC(bufA, gq);
;       if (gq + 2 < NG) PB_LOAD(bufA, tv, gq + 2);
;       PB_FENCE;
;       PB_ACC(bufB, gq + 1);
;     }
	v_lshlrev_b32_e32 v192, 23, v70
	v_cvt_scalef32_pk32_f32_fp6 v[112:143], v[64:69], v192
	v_pk_fma_f32 v[160:161], v[112:113], s[36:37], v[160:161] op_sel_hi:[1,0,1]
	v_pk_fma_f32 v[162:163], v[114:115], s[36:37], v[162:163] op_sel_hi:[1,0,1]
	v_pk_fma_f32 v[164:165], v[116:117], s[36:37], v[164:165] op_sel_hi:[1,0,1]
	v_pk_fma_f32 v[166:167], v[118:119], s[36:37], v[166:167] op_sel_hi:[1,0,1]
	v_pk_fma_f32 v[168:169], v[120:121], s[36:37], v[168:169] op_sel_hi:[1,0,1]
	v_pk_fma_f32 v[170:171], v[122:123], s[36:37], v[170:171] op_sel_hi:[1,0,1]
	v_pk_fma_f32 v[172:173], v[124:125], s[36:37], v[172:173] op_sel_hi:[1,0,1]
	v_pk_fma_f32 v[174:175], v[126:127], s[36:37], v[174:175] op_sel_hi:[1,0,1]
	v_pk_fma_f32 v[176:177], v[128:129], s[36:37], v[176:177] op_sel_hi:[1,0,1]
	v_pk_fma_f32 v[178:179], v[130:131], s[36:37], v[178:179] op_sel_hi:[1,0,1]
	v_pk_fma_f32 v[180:181], v[132:133], s[36:37], v[180:181] op_sel_hi:[1,0,1]
	v_pk_fma_f32 v[182:183], v[134:135], s[36:37], v[182:183] op_sel_hi:[1,0,1]
	v_pk_fma_f32 v[184:185], v[136:137], s[36:37], v[184:185] op_sel_hi:[1,0,1]
	v_pk_fma_f32 v[186:187], v[138:139], s[36:37], v[186:187] op_sel_hi:[1,0,1]
	v_pk_fma_f32 v[188:189], v[140:141], s[36:37], v[188:189] op_sel_hi:[1,0,1]
	v_pk_fma_f32 v[190:191], v[142:143], s[36:37], v[190:191] op_sel_hi:[1,0,1]
	v_readlane_b32 s36, v42, s37
	s_add_u32 s37, s37, 1
	s_waitcnt vmcnt(12)
	v_lshlrev_b32_e32 v192, 23, v78
	v_cvt_scalef32_pk32_f32_fp6 v[112:143], v[72:77], v192
	v_pk_fma_f32 v[160:161], v[112:113], s[36:37], v[160:161] op_sel_hi:[1,0,1]
	v_pk_fma_f32 v[162:163], v[114:115], s[36:37], v[162:163] op_sel_hi:[1,0,1]
	v_pk_fma_f32 v[164:165], v[116:117], s[36:37], v[164:165] op_sel_hi:[1,0,1]
	v_pk_fma_f32 v[166:167], v[118:119], s[36:37], v[166:167] op_sel_hi:[1,0,1]
	v_pk_fma_f32 v[168:169], v[120:121], s[36:37], v[168:169] op_sel_hi:[1,0,1]
	v_pk_fma_f32 v[170:171], v[122:123], s[36:37], v[170:171] op_sel_hi:[1,0,1]
	v_pk_fma_f32 v[172:173], v[124:125], s[36:37], v[172:173] op_sel_hi:[1,0,1]
	v_pk_fma_f32 v[174:175], v[126:127], s[36:37], v[174:175] op_sel_hi:[1,0,1]
	v_pk_fma_f32 v[176:177], v[128:129], s[36:37], v[176:177] op_sel_hi:[1,0,1]
	v_pk_fma_f32 v[178:179], v[130:131], s[36:37], v[178:179] op_sel_hi:[1,0,1]
	v_pk_fma_f32 v[180:181], v[132:133], s[36:37], v[180:181] op_sel_hi:[1,0,1]
	v_pk_fma_f32 v[182:183], v[134:135], s[36:37], v[182:183] op_sel_hi:[1,0,1]
	v_pk_fma_f32 v[184:185], v[136:137], s[36:37], v[184:185] op_sel_hi:[1,0,1]
	v_pk_fma_f32 v[186:187], v[138:139], s[36:37], v[186:187] op_sel_hi:[1,0,1]
	v_pk_fma_f32 v[188:189], v[140:141], s[36:37], v[188:189] op_sel_hi:[1,0,1]
	v_pk_fma_f32 v[190:191], v[142:143], s[36:37], v[190:191] op_sel_hi:[1,0,1]
	v_readlane_b32 s36, v42, s37
	s_add_u32 s37, s37, 1
	s_waitcnt vmcnt(9)
	v_lshlrev_b32_e32 v192, 23, v86
	v_cvt_scalef32_pk32_f32_fp6 v[112:143], v[80:85], v192
	v_pk_fma_f32 v[160:161], v[112:113], s[36:37], v[160:161] op_sel_hi:[1,0,1]
	v_pk_fma_f32 v[162:163], v[114:115], s[36:37], v[162:163] op_sel_hi:[1,0,1]
	v_pk_fma_f32 v[164:165], v[116:117], s[36:37], v[164:165] op_sel_hi:[1,0,1]
	v_pk_fma_f32 v[166:167], v[118:119], s[36:37], v[166:167] op_sel_hi:[1,0,1]
	v_pk_fma_f32 v[168:169], v[120:121], s[36:37], v[168:169] op_sel_hi:[1,0,1]
	v_pk_fma_f32 v[170:171], v[122:123], s[36:37], v[170:171] op_sel_hi:[1,0,1]
	v_pk_fma_f32 v[172:173], v[124:125], s[36:37], v[172:173] op_sel_hi:[1,0,1]
	v_pk_fma_f32 v[174:175], v[126:127], s[36:37], v[174:175] op_sel_hi:[1,0,1]
	v_pk_fma_f32 v[176:177], v[128:129], s[36:37], v[176:177] op_sel_hi:[1,0,1]
	v_pk_fma_f32 v[178:179], v[130:131], s[36:37], v[178:179] op_sel_hi:[1,0,1]
	v_pk_fma_f32 v[180:181], v[132:133], s[36:37], v[180:181] op_sel_hi:[1,0,1]
	v_pk_fma_f32 v[182:183], v[134:135], s[36:37], v[182:183] op_sel_hi:[1,0,1]
	v_pk_fma_f32 v[184:185], v[136:137], s[36:37], v[184:185] op_sel_hi:[1,0,1]
	v_pk_fma_f32 v[186:187], v[138:139], s[36:37], v[186:187] op_sel_hi:[1,0,1]
	v_pk_fma_f32 v[188:189], v[140:141], s[36:37], v[188:189] op_sel_hi:[1,0,1]
	v_pk_fma_f32 v[190:191], v[142:143], s[36:37], v[190:191] op_sel_hi:[1,0,1]
	v_readlane_b32 s36, v42, s37
	s_add_u32 s37, s37, 1
	s_waitcnt vmcnt(6)
	v_lshlrev_b32_e32 v192, 23, v94
	v_cvt_scalef32_pk32_f32_fp6 v[112:143], v[88:93], v192
	v_pk_fma_f32 v[160:161], v[112:113], s[36:37], v[160:161] op_sel_hi:[1,0,1]
	v_pk_fma_f32 v[162:163], v[114:115], s[36:37], v[162:163] op_sel_hi:[1,0,1]
	v_pk_fma_f32 v[164:165], v[116:117], s[36:37], v[164:165] op_sel_hi:[1,0,1]
	v_pk_fma_f32 v[166:167], v[118:119], s[36:37], v[166:167] op_sel_hi:[1,0,1]
	v_pk_fma_f32 v[168:169], v[120:121], s[36:37], v[168:169] op_sel_hi:[1,0,1]
	v_pk_fma_f32 v[170:171], v[122:123], s[36:37], v[170:171] op_sel_hi:[1,0,1]
	v_pk_fma_f32 v[172:173], v[124:125], s[36:37], v[172:173] op_sel_hi:[1,0,1]
	v_pk_fma_f32 v[174:175], v[126:127], s[36:37], v[174:175] op_sel_hi:[1,0,1]
	v_pk_fma_f32 v[176:177], v[128:129], s[36:37], v[176:177] op_sel_hi:[1,0,1]
	v_pk_fma_f32 v[178:179], v[130:131], s[36:37], v[178:179] op_sel_hi:[1,0,1]
	v_pk_fma_f32 v[180:181], v[132:133], s[36:37], v[180:181] op_sel_hi:[1,0,1]
	v_pk_fma_f32 v[182:183], v[134:135], s[36:37], v[182:183] op_sel_hi:[1,0,1]
	v_pk_fma_f32 v[184:185], v[136:137], s[36:37], v[184:185] op_sel_hi:[1,0,1]
	v_pk_fma_f32 v[186:187], v[138:139], s[36:37], v[186:187] op_sel_hi:[1,0,1]
	v_pk_fma_f32 v[188:189], v[140:141], s[36:37], v[188:189] op_sel_hi:[1,0,1]
	v_pk_fma_f32 v[190:191], v[142:143], s[36:37], v[190:191] op_sel_hi:[1,0,1]
	v_readlane_b32 s36, v42, s37
	s_add_u32 s37, s37, 1
	s_waitcnt vmcnt(3)
; #define PB_FENCE asm volatile("" ::: "memory")
; __device__ __forceinline__ void ph_peer_apply(const Params& P, int layer, float* xlat, float* xctx_in, float* xctx_out, int nrows, bool write_next, char* smem, float* xlat_out = nullptr) {
;     ...
;     PB_LOAD(bufA, tv, 0);
;     for (int gq = 0; gq < NG; gq += 2) {
;       PB_LOAD(bufB, tv, gq + 1); PB_FENCE;
;       PB_ACC(bufA, gq);
;       if (gq + 2 < NG) PB_LOAD(bufA, tv, gq + 2);
;       PB_FENCE;
;       PB_ACC(bufB, gq + 1);
;     }
	v_lshlrev_b32_e32 v192, 23, v102
	v_cvt_scalef32_pk32_f32_fp6 v[112:143], v[96:101], v192
	v_pk_fma_f32 v[160:161], v[112:113], s[36:37], v[160:161] op_sel_hi:[1,0,1]
	v_pk_fma_f32 v[162:163], v[114:115], s[36:37], v[162:163] op_sel_hi:[1,0,1]
	v_pk_fma_f32 v[164:165], v[116:117], s[36:37], v[164:165] op_sel_hi:[1,0,1]
	v_pk_fma_f32 v[166:167], v[118:119], s[36:37], v[166:167] op_sel_hi:[1,0,1]
	v_pk_fma_f32 v[168:169], v[120:121], s[36:37], v[168:169] op_sel_hi:[1,0,1]
	v_pk_fma_f32 v[170:171], v[122:123], s[36:37], v[170:171] op_sel_hi:[1,0,1]
	v_pk_fma_f32 v[172:173], v[124:125], s[36:37], v[172:173] op_sel_hi:[1,0,1]
	v_pk_fma_f32 v[174:175], v[126:127], s[36:37], v[174:175] op_sel_hi:[1,0,1]
	v_pk_fma_f32 v[176:177], v[128:129], s[36:37], v[176:177] op_sel_hi:[1,0,1]
	v_pk_fma_f32 v[178:179], v[130:131], s[36:37], v[178:179] op_sel_hi:[1,0,1]
	v_pk_fma_f32 v[180:181], v[132:133], s[36:37], v[180:181] op_sel_hi:[1,0,1]
	v_pk_fma_f32 v[182:183], v[134:135], s[36:37], v[182:183] op_sel_hi:[1,0,1]
	v_pk_fma_f32 v[184:185], v[136:137], s[36:37], v[184:185] op_sel_hi:[1,0,1]
	v_pk_fma_f32 v[186:187], v[138:139], s[36:37], v[186:187] op_sel_hi:[1,0,1]
	v_pk_fma_f32 v[188:189], v[140:141], s[36:37], v[188:189] op_sel_hi:[1,0,1]
	v_pk_fma_f32 v[190:191], v[142:143], s[36:37], v[190:191] op_sel_hi:[1,0,1]
	v_readlane_b32 s36, v42, s37
	s_add_u32 s37, s37, 1
	s_waitcnt vmcnt(0)
	v_lshlrev_b32_e32 v192, 23, v110
	v_cvt_scalef32_pk32_f32_fp6 v[112:143], v[104:109], v192
	v_pk_fma_f32 v[160:161], v[112:113], s[36:37], v[160:161] op_sel_hi:[1,0,1]
	v_pk_fma_f32 v[162:163], v[114:115], s[36:37], v[162:163] op_sel_hi:[1,0,1]
	v_pk_fma_f32 v[164:165], v[116:117], s[36:37], v[164:165] op_sel_hi:[1,0,1]
	v_pk_fma_f32 v[166:167], v[118:119], s[36:37], v[166:167] op_sel_hi:[1,0,1]
	v_pk_fma_f32 v[168:169], v[120:121], s[36:37], v[168:169] op_sel_hi:[1,0,1]
	v_pk_fma_f32 v[170:171], v[122:123], s[36:37], v[170:171] op_sel_hi:[1,0,1]
	v_pk_fma_f32 v[172:173], v[124:125], s[36:37], v[172:173] op_sel_hi:[1,0,1]
	v_pk_fma_f32 v[174:175], v[126:127], s[36:37], v[174:175] op_sel_hi:[1,0,1]
	v_pk_fma_f32 v[176:177], v[128:129], s[36:37], v[176:177] op_sel_hi:[1,0,1]
	v_pk_fma_f32 v[178:179], v[130:131], s[36:37], v[178:179] op_sel_hi:[1,0,1]
	v_pk_fma_f32 v[180:181], v[132:133], s[36:37], v[180:181] op_sel_hi:[1,0,1]
	v_pk_fma_f32 v[182:183], v[134:135], s[36:37], v[182:183] op_sel_hi:[1,0,1]
	v_pk_fma_f32 v[184:185], v[136:137], s[36:37], v[184:185] op_sel_hi:[1,0,1]
	v_pk_fma_f32 v[186:187], v[138:139], s[36:37], v[186:187] op_sel_hi:[1,0,1]
	v_pk_fma_f32 v[188:189], v[140:141], s[36:37], v[188:189] op_sel_hi:[1,0,1]
	v_pk_fma_f32 v[190:191], v[142:143], s[36:37], v[190:191] op_sel_hi:[1,0,1]
	s_mov_b32 s28, 0
	s_mov_b32 s37, 0
	v_readlane_b32 s29, v37, s28
	s_add_u32 s28, s28, 1
	s_mul_hi_u32 s27, s29, 0x640
	s_mul_i32 s26, s29, 0x640
	s_add_u32 s26, s18, s26
	s_addc_u32 s27, s19, s27
	global_load_dwordx4 v[48:51], v2, s[26:27]
	global_load_dwordx2 v[52:53], v2, s[26:27] offset:16
	global_load_ubyte v54, v3, s[26:27]
	v_readlane_b32 s29, v37, s28
	s_add_u32 s28, s28, 1
	s_mul_hi_u32 s27, s29, 0x640
	s_mul_i32 s26, s29, 0x640
	s_add_u32 s26, s18, s26
	s_addc_u32 s27, s19, s27
	global_load_dwordx4 v[56:59], v2, s[26:27]
	global_load_dwordx2 v[60:61], v2, s[26:27] offset:16
	global_load_ubyte v62, v3, s[26:27]
	v_readlane_b32 s29, v37, s28
	s_add_u32 s28, s28, 1
	s_mul_hi_u32 s27, s29, 0x640
	s_mul_i32 s26, s29, 0x640
	s_add_u32 s26, s18, s26
	s_addc_u32 s27, s19, s27
	global_load_dwordx4 v[64:67], v2, s[26:27]
	global_load_dwordx2 v[68:69], v2, s[26:27] offset:16
	global_load_ubyte v70, v3, s[26:27]
	v_readlane_b32 s29, v37, s28
	s_add_u32 s28, s28, 1
	s_mul_hi_u32 s27, s29, 0x640
	s_mul_i32 s26, s29, 0x640
	s_add_u32 s26, s18, s26
	s_addc_u32 s27, s19, s27
	global_load_dwordx4 v[72:75], v2, s[26:27]
	global_load_dwordx2 v[76:77], v2, s[26:27] offset:16
	global_load_ubyte v78, v3, s[26:27]
	v_readlane_b32 s29, v37, s28
	s_add_u32 s28, s28, 1
	s_mul_hi_u32 s27, s29, 0x640
	s_mul_i32 s26, s29, 0x640
	s_add_u32 s26, s18, s26
	s_addc_u32 s27, s19, s27
	global_load_dwordx4 v[80:83], v2, s[26:27]
	global_load_dwordx2 v[84:85], v2, s[26:27] offset:16
	global_load_ubyte v86, v3, s[26:27]
	v_readlane_b32 s29, v37, s28
	s_add_u32 s28, s28, 1
	s_mul_hi_u32 s27, s29, 0x640
	s_mul_i32 s26, s29, 0x640
	s_add_u32 s26, s18, s26
	s_addc_u32 s27, s19, s27
	global_load_dwordx4 v[88:91], v2, s[26:27]
	global_load_dwordx2 v[92:93], v2, s[26:27] offset:16
	global_load_ubyte v94, v3, s[26:27]
	v_readlane_b32 s29, v37, s28
	s_add_u32 s28, s28, 1
	s_mul_hi_u32 s27, s29, 0x640
	s_mul_i32 s26, s29, 0x640
	s_add_u32 s26, s18, s26
	s_addc_u32 s27, s19, s27
	global_load_dwordx4 v[96:99], v2, s[26:27]
	global_load_dwordx2 v[100:101], v2, s[26:27] offset:16
	global_load_ubyte v102, v3, s[26:27]
	v_readlane_b32 s29, v37, s28
	s_add_u32 s28, s28, 1
	s_mul_hi_u32 s27, s29, 0x640
	s_mul_i32 s26, s29, 0x640
	s_add_u32 s26, s18, s26
	s_addc_u32 s27, s19, s27
	global_load_dwordx4 v[104:107], v2, s[26:27]
	global_load_dwordx2 v[108:109], v2, s[26:27] offset:16
	global_load_ubyte v110, v3, s[26:27]
	s_mov_b32 s30, 7
; #define PB_FENCE asm volatile("" ::: "memory")
; __device__ __forceinline__ void ph_peer_apply(const Params& P, int layer, float* xlat, float* xctx_in, float* xctx_out, int nrows, bool write_next, char* smem, float* xlat_out = nullptr) {
;     ...
;     PB_LOAD(bufA, tv, 0);
;     for (int gq = 0; gq < NG; gq += 2) {
;       PB_LOAD(bufB, tv, gq + 1); PB_FENCE;
;       PB_ACC(bufA, gq);
;       if (gq + 2 < NG) PB_LOAD(bufA, tv, gq + 2);
;       PB_FENCE;
;       PB_ACC(bufB, gq + 1);
;     }
.Lap0_s2_loop4:
	v_readlane_b32 s36, v43, s37
	s_add_u32 s37, s37, 1
	s_waitcnt vmcnt(21)
	v_lshlrev_b32_e32 v192, 23, v54
	v_cvt_scalef32_pk32_f32_fp6 v[112:143], v[48:53], v192
	v_pk_fma_f32 v[160:161], v[112:113], s[36:37], v[160:161] op_sel_hi:[1,0,1]
	v_pk_fma_f32 v[162:163], v[114:115], s[36:37], v[162:163] op_sel_hi:[1,0,1]
	v_pk_fma_f32 v[164:165], v[116:117], s[36:37], v[164:165] op_sel_hi:[1,0,1]
	v_pk_fma_f32 v[166:167], v[118:119], s[36:37], v[166:167] op_sel_hi:[1,0,1]
	v_pk_fma_f32 v[168:169], v[120:121], s[36:37], v[168:169] op_sel_hi:[1,0,1]
	v_pk_fma_f32 v[170:171], v[122:123], s[36:37], v[170:171] op_sel_hi:[1,0,1]
	v_pk_fma_f32 v[172:173], v[124:125], s[36:37], v[172:173] op_sel_hi:[1,0,1]
	v_pk_fma_f32 v[174:175], v[126:127], s[36:37], v[174:175] op_sel_hi:[1,0,1]
	v_pk_fma_f32 v[176:177], v[128:129], s[36:37], v[176:177] op_sel_hi:[1,0,1]
	v_pk_fma_f32 v[178:179], v[130:131], s[36:37], v[178:179] op_sel_hi:[1,0,1]
	v_pk_fma_f32 v[180:181], v[132:133], s[36:37], v[180:181] op_sel_hi:[1,0,1]
	v_pk_fma_f32 v[182:183], v[134:135], s[36:37], v[182:183] op_sel_hi:[1,0,1]
	v_pk_fma_f32 v[184:185], v[136:137], s[36:37], v[184:185] op_sel_hi:[1,0,1]
	v_pk_fma_f32 v[186:187], v[138:139], s[36:37], v[186:187] op_sel_hi:[1,0,1]
	v_pk_fma_f32 v[188:189], v[140:141], s[36:37], v[188:189] op_sel_hi:[1,0,1]
	v_pk_fma_f32 v[190:191], v[142:143], s[36:37], v[190:191] op_sel_hi:[1,0,1]
	v_readlane_b32 s29, v37, s28
	s_add_u32 s28, s28, 1
	s_mul_hi_u32 s27, s29, 0x640
	s_mul_i32 s26, s29, 0x640
	s_add_u32 s26, s18, s26
	s_addc_u32 s27, s19, s27
	global_load_dwordx4 v[48:51], v2, s[26:27]
	global_load_dwordx2 v[52:53], v2, s[26:27] offset:16
	global_load_ubyte v54, v3, s[26:27]
	v_readlane_b32 s36, v43, s37
	s_add_u32 s37, s37, 1
	s_waitcnt vmcnt(21)
	v_lshlrev_b32_e32 v192, 23, v62
	v_cvt_scalef32_pk32_f32_fp6 v[112:143], v[56:61], v192
	v_pk_fma_f32 v[160:161], v[112:113], s[36:37], v[160:161] op_sel_hi:[1,0,1]
	v_pk_fma_f32 v[162:163], v[114:115], s[36:37], v[162:163] op_sel_hi:[1,0,1]
	v_pk_fma_f32 v[164:165], v[116:117], s[36:37], v[164:165] op_sel_hi:[1,0,1]
	v_pk_fma_f32 v[166:167], v[118:119], s[36:37], v[166:167] op_sel_hi:[1,0,1]
	v_pk_fma_f32 v[168:169], v[120:121], s[36:37], v[168:169] op_sel_hi:[1,0,1]
	v_pk_fma_f32 v[170:171], v[122:123], s[36:37], v[170:171] op_sel_hi:[1,0,1]
	v_pk_fma_f32 v[172:173], v[124:125], s[36:37], v[172:173] op_sel_hi:[1,0,1]
	v_pk_fma_f32 v[174:175], v[126:127], s[36:37], v[174:175] op_sel_hi:[1,0,1]
	v_pk_fma_f32 v[176:177], v[128:129], s[36:37], v[176:177] op_sel_hi:[1,0,1]
	v_pk_fma_f32 v[178:179], v[130:131], s[36:37], v[178:179] op_sel_hi:[1,0,1]
	v_pk_fma_f32 v[180:181], v[132:133], s[36:37], v[180:181] op_sel_hi:[1,0,1]
	v_pk_fma_f32 v[182:183], v[134:135], s[36:37], v[182:183] op_sel_hi:[1,0,1]
	v_pk_fma_f32 v[184:185], v[136:137], s[36:37], v[184:185] op_sel_hi:[1,0,1]
	v_pk_fma_f32 v[186:187], v[138:139], s[36:37], v[186:187] op_sel_hi:[1,0,1]
	v_pk_fma_f32 v[188:189], v[140:141], s[36:37], v[188:189] op_sel_hi:[1,0,1]
	v_pk_fma_f32 v[190:191], v[142:143], s[36:37], v[190:191] op_sel_hi:[1,0,1]
	v_readlane_b32 s29, v37, s28
	s_add_u32 s28, s28, 1
	s_mul_hi_u32 s27, s29, 0x640
	s_mul_i32 s26, s29, 0x640
	s_add_u32 s26, s18, s26
	s_addc_u32 s27, s19, s27
	global_load_dwordx4 v[56:59], v2, s[26:27]
	global_load_dwordx2 v[60:61], v2, s[26:27] offset:16
	global_load_ubyte v62, v3, s[26:27]
	v_readlane_b32 s36, v43, s37
	s_add_u32 s37, s37, 1
	s_waitcnt vmcnt(21)
	v_lshlrev_b32_e32 v192, 23, v70
	v_cvt_scalef32_pk32_f32_fp6 v[112:143], v[64:69], v192
	v_pk_fma_f32 v[160:161], v[112:113], s[36:37], v[160:161] op_sel_hi:[1,0,1]
	v_pk_fma_f32 v[162:163], v[114:115], s[36:37], v[162:163] op_sel_hi:[1,0,1]
	v_pk_fma_f32 v[164:165], v[116:117], s[36:37], v[164:165] op_sel_hi:[1,0,1]
	v_pk_fma_f32 v[166:167], v[118:119], s[36:37], v[166:167] op_sel_hi:[1,0,1]
	v_pk_fma_f32 v[168:169], v[120:121], s[36:37], v[168:169] op_sel_hi:[1,0,1]
	v_pk_fma_f32 v[170:171], v[122:123], s[36:37], v[170:171] op_sel_hi:[1,0,1]
	v_pk_fma_f32 v[172:173], v[124:125], s[36:37], v[172:173] op_sel_hi:[1,0,1]
	v_pk_fma_f32 v[174:175], v[126:127], s[36:37], v[174:175] op_sel_hi:[1,0,1]
	v_pk_fma_f32 v[176:177], v[128:129], s[36:37], v[176:177] op_sel_hi:[1,0,1]
	v_pk_fma_f32 v[178:179], v[130:131], s[36:37], v[178:179] op_sel_hi:[1,0,1]
	v_pk_fma_f32 v[180:181], v[132:133], s[36:37], v[180:181] op_sel_hi:[1,0,1]
	v_pk_fma_f32 v[182:183], v[134:135], s[36:37], v[182:183] op_sel_hi:[1,0,1]
	v_pk_fma_f32 v[184:185], v[136:137], s[36:37], v[184:185] op_sel_hi:[1,0,1]
	v_pk_fma_f32 v[186:187], v[138:139], s[36:37], v[186:187] op_sel_hi:[1,0,1]
	v_pk_fma_f32 v[188:189], v[140:141], s[36:37], v[188:189] op_sel_hi:[1,0,1]
	v_pk_fma_f32 v[190:191], v[142:143], s[36:37], v[190:191] op_sel_hi:[1,0,1]
	v_readlane_b32 s29, v37, s28
	s_add_u32 s28, s28, 1
	s_mul_hi_u32 s27, s29, 0x640
	s_mul_i32 s26, s29, 0x640
	s_add_u32 s26, s18, s26
	s_addc_u32 s27, s19, s27
	global_load_dwordx4 v[64:67], v2, s[26:27]
	global_load_dwordx2 v[68:69], v2, s[26:27] offset:16
	global_load_ubyte v70, v3, s[26:27]
	v_readlane_b32 s36, v43, s37
	s_add_u32 s37, s37, 1
	s_waitcnt vmcnt(21)
; #define PB_FENCE asm volatile("" ::: "memory")
; __device__ __forceinline__ void ph_peer_apply(const Params& P, int layer, float* xlat, float* xctx_in, float* xctx_out, int nrows, bool write_next, char* smem, float* xlat_out = nullptr) {
;     ...
;     PB_LOAD(bufA, tv, 0);
;     for (int gq = 0; gq < NG; gq += 2) {
;       PB_LOAD(bufB, tv, gq + 1); PB_FENCE;
;       PB_ACC(bufA, gq);
;       if (gq + 2 < NG) PB_LOAD(bufA, tv, gq + 2);
;       PB_FENCE;
;       PB_ACC(bufB, gq + 1);
;     }
	v_lshlrev_b32_e32 v192, 23, v78
	v_cvt_scalef32_pk32_f32_fp6 v[112:143], v[72:77], v192
	v_pk_fma_f32 v[160:161], v[112:113], s[36:37], v[160:161] op_sel_hi:[1,0,1]
	v_pk_fma_f32 v[162:163], v[114:115], s[36:37], v[162:163] op_sel_hi:[1,0,1]
	v_pk_fma_f32 v[164:165], v[116:117], s[36:37], v[164:165] op_sel_hi:[1,0,1]
	v_pk_fma_f32 v[166:167], v[118:119], s[36:37], v[166:167] op_sel_hi:[1,0,1]
	v_pk_fma_f32 v[168:169], v[120:121], s[36:37], v[168:169] op_sel_hi:[1,0,1]
	v_pk_fma_f32 v[170:171], v[122:123], s[36:37], v[170:171] op_sel_hi:[1,0,1]
	v_pk_fma_f32 v[172:173], v[124:125], s[36:37], v[172:173] op_sel_hi:[1,0,1]
	v_pk_fma_f32 v[174:175], v[126:127], s[36:37], v[174:175] op_sel_hi:[1,0,1]
	v_pk_fma_f32 v[176:177], v[128:129], s[36:37], v[176:177] op_sel_hi:[1,0,1]
	v_pk_fma_f32 v[178:179], v[130:131], s[36:37], v[178:179] op_sel_hi:[1,0,1]
	v_pk_fma_f32 v[180:181], v[132:133], s[36:37], v[180:181] op_sel_hi:[1,0,1]
	v_pk_fma_f32 v[182:183], v[134:135], s[36:37], v[182:183] op_sel_hi:[1,0,1]
	v_pk_fma_f32 v[184:185], v[136:137], s[36:37], v[184:185] op_sel_hi:[1,0,1]
	v_pk_fma_f32 v[186:187], v[138:139], s[36:37], v[186:187] op_sel_hi:[1,0,1]
	v_pk_fma_f32 v[188:189], v[140:141], s[36:37], v[188:189] op_sel_hi:[1,0,1]
	v_pk_fma_f32 v[190:191], v[142:143], s[36:37], v[190:191] op_sel_hi:[1,0,1]
	v_readlane_b32 s29, v37, s28
	s_add_u32 s28, s28, 1
	s_mul_hi_u32 s27, s29, 0x640
	s_mul_i32 s26, s29, 0x640
	s_add_u32 s26, s18, s26
	s_addc_u32 s27, s19, s27
	global_load_dwordx4 v[72:75], v2, s[26:27]
	global_load_dwordx2 v[76:77], v2, s[26:27] offset:16
	global_load_ubyte v78, v3, s[26:27]
	v_readlane_b32 s36, v43, s37
	s_add_u32 s37, s37, 1
	s_waitcnt vmcnt(21)
	v_lshlrev_b32_e32 v192, 23, v86
	v_cvt_scalef32_pk32_f32_fp6 v[112:143], v[80:85], v192
	v_pk_fma_f32 v[160:161], v[112:113], s[36:37], v[160:161] op_sel_hi:[1,0,1]
	v_pk_fma_f32 v[162:163], v[114:115], s[36:37], v[162:163] op_sel_hi:[1,0,1]
	v_pk_fma_f32 v[164:165], v[116:117], s[36:37], v[164:165] op_sel_hi:[1,0,1]
	v_pk_fma_f32 v[166:167], v[118:119], s[36:37], v[166:167] op_sel_hi:[1,0,1]
	v_pk_fma_f32 v[168:169], v[120:121], s[36:37], v[168:169] op_sel_hi:[1,0,1]
	v_pk_fma_f32 v[170:171], v[122:123], s[36:37], v[170:171] op_sel_hi:[1,0,1]
	v_pk_fma_f32 v[172:173], v[124:125], s[36:37], v[172:173] op_sel_hi:[1,0,1]
	v_pk_fma_f32 v[174:175], v[126:127], s[36:37], v[174:175] op_sel_hi:[1,0,1]
	v_pk_fma_f32 v[176:177], v[128:129], s[36:37], v[176:177] op_sel_hi:[1,0,1]
	v_pk_fma_f32 v[178:179], v[130:131], s[36:37], v[178:179] op_sel_hi:[1,0,1]
	v_pk_fma_f32 v[180:181], v[132:133], s[36:37], v[180:181] op_sel_hi:[1,0,1]
	v_pk_fma_f32 v[182:183], v[134:135], s[36:37], v[182:183] op_sel_hi:[1,0,1]
	v_pk_fma_f32 v[184:185], v[136:137], s[36:37], v[184:185] op_sel_hi:[1,0,1]
	v_pk_fma_f32 v[186:187], v[138:139], s[36:37], v[186:187] op_sel_hi:[1,0,1]
	v_pk_fma_f32 v[188:189], v[140:141], s[36:37], v[188:189] op_sel_hi:[1,0,1]
	v_pk_fma_f32 v[190:191], v[142:143], s[36:37], v[190:191] op_sel_hi:[1,0,1]
	v_readlane_b32 s29, v37, s28
	s_add_u32 s28, s28, 1
	s_mul_hi_u32 s27, s29, 0x640
	s_mul_i32 s26, s29, 0x640
	s_add_u32 s26, s18, s26
	s_addc_u32 s27, s19, s27
	global_load_dwordx4 v[80:83], v2, s[26:27]
	global_load_dwordx2 v[84:85], v2, s[26:27] offset:16
	global_load_ubyte v86, v3, s[26:27]
	v_readlane_b32 s36, v43, s37
	s_add_u32 s37, s37, 1
	s_waitcnt vmcnt(21)
	v_lshlrev_b32_e32 v192, 23, v94
	v_cvt_scalef32_pk32_f32_fp6 v[112:143], v[88:93], v192
	v_pk_fma_f32 v[160:161], v[112:113], s[36:37], v[160:161] op_sel_hi:[1,0,1]
	v_pk_fma_f32 v[162:163], v[114:115], s[36:37], v[162:163] op_sel_hi:[1,0,1]
	v_pk_fma_f32 v[164:165], v[116:117], s[36:37], v[164:165] op_sel_hi:[1,0,1]
	v_pk_fma_f32 v[166:167], v[118:119], s[36:37], v[166:167] op_sel_hi:[1,0,1]
	v_pk_fma_f32 v[168:169], v[120:121], s[36:37], v[168:169] op_sel_hi:[1,0,1]
	v_pk_fma_f32 v[170:171], v[122:123], s[36:37], v[170:171] op_sel_hi:[1,0,1]
	v_pk_fma_f32 v[172:173], v[124:125], s[36:37], v[172:173] op_sel_hi:[1,0,1]
	v_pk_fma_f32 v[174:175], v[126:127], s[36:37], v[174:175] op_sel_hi:[1,0,1]
	v_pk_fma_f32 v[176:177], v[128:129], s[36:37], v[176:177] op_sel_hi:[1,0,1]
	v_pk_fma_f32 v[178:179], v[130:131], s[36:37], v[178:179] op_sel_hi:[1,0,1]
	v_pk_fma_f32 v[180:181], v[132:133], s[36:37], v[180:181] op_sel_hi:[1,0,1]
	v_pk_fma_f32 v[182:183], v[134:135], s[36:37], v[182:183] op_sel_hi:[1,0,1]
	v_pk_fma_f32 v[184:185], v[136:137], s[36:37], v[184:185] op_sel_hi:[1,0,1]
	v_pk_fma_f32 v[186:187], v[138:139], s[36:37], v[186:187] op_sel_hi:[1,0,1]
	v_pk_fma_f32 v[188:189], v[140:141], s[36:37], v[188:189] op_sel_hi:[1,0,1]
	v_pk_fma_f32 v[190:191], v[142:143], s[36:37], v[190:191] op_sel_hi:[1,0,1]
	v_readlane_b32 s29, v37, s28
	s_add_u32 s28, s28, 1
	s_mul_hi_u32 s27, s29, 0x640
	s_mul_i32 s26, s29, 0x640
	s_add_u32 s26, s18, s26
	s_addc_u32 s27, s19, s27
	global_load_dwordx4 v[88:91], v2, s[26:27]
	global_load_dwordx2 v[92:93], v2, s[26:27] offset:16
	global_load_ubyte v94, v3, s[26:27]
	v_readlane_b32 s36, v43, s37
	s_add_u32 s37, s37, 1
	s_waitcnt vmcnt(21)
; #define PB_FENCE asm volatile("" ::: "memory")
; __device__ __forceinline__ void ph_peer_apply(const Params& P, int layer, float* xlat, float* xctx_in, float* xctx_out, int nrows, bool write_next, char* smem, float* xlat_out = nullptr) {
;     ...
;     PB_LOAD(bufA, tv, 0);
;     for (int gq = 0; gq < NG; gq += 2) {
;       PB_LOAD(bufB, tv, gq + 1); PB_FENCE;
;       PB_ACC(bufA, gq);
;       if (gq + 2 < NG) PB_LOAD(bufA, tv, gq + 2);
;       PB_FENCE;
;       PB_ACC(bufB, gq + 1);
;     }
	v_lshlrev_b32_e32 v192, 23, v102
	v_cvt_scalef32_pk32_f32_fp6 v[112:143], v[96:101], v192
	v_pk_fma_f32 v[160:161], v[112:113], s[36:37], v[160:161] op_sel_hi:[1,0,1]
	v_pk_fma_f32 v[162:163], v[114:115], s[36:37], v[162:163] op_sel_hi:[1,0,1]
	v_pk_fma_f32 v[164:165], v[116:117], s[36:37], v[164:165] op_sel_hi:[1,0,1]
	v_pk_fma_f32 v[166:167], v[118:119], s[36:37], v[166:167] op_sel_hi:[1,0,1]
	v_pk_fma_f32 v[168:169], v[120:121], s[36:37], v[168:169] op_sel_hi:[1,0,1]
	v_pk_fma_f32 v[170:171], v[122:123], s[36:37], v[170:171] op_sel_hi:[1,0,1]
	v_pk_fma_f32 v[172:173], v[124:125], s[36:37], v[172:173] op_sel_hi:[1,0,1]
	v_pk_fma_f32 v[174:175], v[126:127], s[36:37], v[174:175] op_sel_hi:[1,0,1]
	v_pk_fma_f32 v[176:177], v[128:129], s[36:37], v[176:177] op_sel_hi:[1,0,1]
	v_pk_fma_f32 v[178:179], v[130:131], s[36:37], v[178:179] op_sel_hi:[1,0,1]
	v_pk_fma_f32 v[180:181], v[132:133], s[36:37], v[180:181] op_sel_hi:[1,0,1]
	v_pk_fma_f32 v[182:183], v[134:135], s[36:37], v[182:183] op_sel_hi:[1,0,1]
	v_pk_fma_f32 v[184:185], v[136:137], s[36:37], v[184:185] op_sel_hi:[1,0,1]
	v_pk_fma_f32 v[186:187], v[138:139], s[36:37], v[186:187] op_sel_hi:[1,0,1]
	v_pk_fma_f32 v[188:189], v[140:141], s[36:37], v[188:189] op_sel_hi:[1,0,1]
	v_pk_fma_f32 v[190:191], v[142:143], s[36:37], v[190:191] op_sel_hi:[1,0,1]
	v_readlane_b32 s29, v37, s28
	s_add_u32 s28, s28, 1
	s_mul_hi_u32 s27, s29, 0x640
	s_mul_i32 s26, s29, 0x640
	s_add_u32 s26, s18, s26
	s_addc_u32 s27, s19, s27
	global_load_dwordx4 v[96:99], v2, s[26:27]
	global_load_dwordx2 v[100:101], v2, s[26:27] offset:16
	global_load_ubyte v102, v3, s[26:27]
	v_readlane_b32 s36, v43, s37
	s_add_u32 s37, s37, 1
	s_waitcnt vmcnt(21)
	v_lshlrev_b32_e32 v192, 23, v110
	v_cvt_scalef32_pk32_f32_fp6 v[112:143], v[104:109], v192
	v_pk_fma_f32 v[160:161], v[112:113], s[36:37], v[160:161] op_sel_hi:[1,0,1]
	v_pk_fma_f32 v[162:163], v[114:115], s[36:37], v[162:163] op_sel_hi:[1,0,1]
	v_pk_fma_f32 v[164:165], v[116:117], s[36:37], v[164:165] op_sel_hi:[1,0,1]
	v_pk_fma_f32 v[166:167], v[118:119], s[36:37], v[166:167] op_sel_hi:[1,0,1]
	v_pk_fma_f32 v[168:169], v[120:121], s[36:37], v[168:169] op_sel_hi:[1,0,1]
	v_pk_fma_f32 v[170:171], v[122:123], s[36:37], v[170:171] op_sel_hi:[1,0,1]
	v_pk_fma_f32 v[172:173], v[124:125], s[36:37], v[172:173] op_sel_hi:[1,0,1]
	v_pk_fma_f32 v[174:175], v[126:127], s[36:37], v[174:175] op_sel_hi:[1,0,1]
	v_pk_fma_f32 v[176:177], v[128:129], s[36:37], v[176:177] op_sel_hi:[1,0,1]
	v_pk_fma_f32 v[178:179], v[130:131], s[36:37], v[178:179] op_sel_hi:[1,0,1]
	v_pk_fma_f32 v[180:181], v[132:133], s[36:37], v[180:181] op_sel_hi:[1,0,1]
	v_pk_fma_f32 v[182:183], v[134:135], s[36:37], v[182:183] op_sel_hi:[1,0,1]
	v_pk_fma_f32 v[184:185], v[136:137], s[36:37], v[184:185] op_sel_hi:[1,0,1]
	v_pk_fma_f32 v[186:187], v[138:139], s[36:37], v[186:187] op_sel_hi:[1,0,1]
	v_pk_fma_f32 v[188:189], v[140:141], s[36:37], v[188:189] op_sel_hi:[1,0,1]
	v_pk_fma_f32 v[190:191], v[142:143], s[36:37], v[190:191] op_sel_hi:[1,0,1]
	v_readlane_b32 s29, v37, s28
	s_add_u32 s28, s28, 1
	s_mul_hi_u32 s27, s29, 0x640
	s_mul_i32 s26, s29, 0x640
	s_add_u32 s26, s18, s26
	s_addc_u32 s27, s19, s27
	global_load_dwordx4 v[104:107], v2, s[26:27]
	global_load_dwordx2 v[108:109], v2, s[26:27] offset:16
	global_load_ubyte v110, v3, s[26:27]
	s_sub_u32 s30, s30, 1
	s_cmp_lg_u32 s30, 0
	s_cbranch_scc1 .Lap0_s2_loop4
	v_readlane_b32 s36, v43, s37
	s_add_u32 s37, s37, 1
	s_waitcnt vmcnt(21)
	v_lshlrev_b32_e32 v192, 23, v54
	v_cvt_scalef32_pk32_f32_fp6 v[112:143], v[48:53], v192
	v_pk_fma_f32 v[160:161], v[112:113], s[36:37], v[160:161] op_sel_hi:[1,0,1]
	v_pk_fma_f32 v[162:163], v[114:115], s[36:37], v[162:163] op_sel_hi:[1,0,1]
	v_pk_fma_f32 v[164:165], v[116:117], s[36:37], v[164:165] op_sel_hi:[1,0,1]
	v_pk_fma_f32 v[166:167], v[118:119], s[36:37], v[166:167] op_sel_hi:[1,0,1]
	v_pk_fma_f32 v[168:169], v[120:121], s[36:37], v[168:169] op_sel_hi:[1,0,1]
	v_pk_fma_f32 v[170:171], v[122:123], s[36:37], v[170:171] op_sel_hi:[1,0,1]
	v_pk_fma_f32 v[172:173], v[124:125], s[36:37], v[172:173] op_sel_hi:[1,0,1]
	v_pk_fma_f32 v[174:175], v[126:127], s[36:37], v[174:175] op_sel_hi:[1,0,1]
	v_pk_fma_f32 v[176:177], v[128:129], s[36:37], v[176:177] op_sel_hi:[1,0,1]
	v_pk_fma_f32 v[178:179], v[130:131], s[36:37], v[178:179] op_sel_hi:[1,0,1]
	v_pk_fma_f32 v[180:181], v[132:133], s[36:37], v[180:181] op_sel_hi:[1,0,1]
	v_pk_fma_f32 v[182:183], v[134:135], s[36:37], v[182:183] op_sel_hi:[1,0,1]
	v_pk_fma_f32 v[184:185], v[136:137], s[36:37], v[184:185] op_sel_hi:[1,0,1]
	v_pk_fma_f32 v[186:187], v[138:139], s[36:37], v[186:187] op_sel_hi:[1,0,1]
	v_pk_fma_f32 v[188:189], v[140:141], s[36:37], v[188:189] op_sel_hi:[1,0,1]
	v_pk_fma_f32 v[190:191], v[142:143], s[36:37], v[190:191] op_sel_hi:[1,0,1]
	v_readlane_b32 s36, v43, s37
	s_add_u32 s37, s37, 1
	s_waitcnt vmcnt(18)
	v_lshlrev_b32_e32 v192, 23, v62
	v_cvt_scalef32_pk32_f32_fp6 v[112:143], v[56:61], v192
	v_pk_fma_f32 v[160:161], v[112:113], s[36:37], v[160:161] op_sel_hi:[1,0,1]
	v_pk_fma_f32 v[162:163], v[114:115], s[36:37], v[162:163] op_sel_hi:[1,0,1]
	v_pk_fma_f32 v[164:165], v[116:117], s[36:37], v[164:165] op_sel_hi:[1,0,1]
	v_pk_fma_f32 v[166:167], v[118:119], s[36:37], v[166:167] op_sel_hi:[1,0,1]
	v_pk_fma_f32 v[168:169], v[120:121], s[36:37], v[168:169] op_sel_hi:[1,0,1]
	v_pk_fma_f32 v[170:171], v[122:123], s[36:37], v[170:171] op_sel_hi:[1,0,1]
	v_pk_fma_f32 v[172:173], v[124:125], s[36:37], v[172:173] op_sel_hi:[1,0,1]
	v_pk_fma_f32 v[174:175], v[126:127], s[36:37], v[174:175] op_sel_hi:[1,0,1]
	v_pk_fma_f32 v[176:177], v[128:129], s[36:37], v[176:177] op_sel_hi:[1,0,1]
	v_pk_fma_f32 v[178:179], v[130:131], s[36:37], v[178:179] op_sel_hi:[1,0,1]
	v_pk_fma_f32 v[180:181], v[132:133], s[36:37], v[180:181] op_sel_hi:[1,0,1]
	v_pk_fma_f32 v[182:183], v[134:135], s[36:37], v[182:183] op_sel_hi:[1,0,1]
	v_pk_fma_f32 v[184:185], v[136:137], s[36:37], v[184:185] op_sel_hi:[1,0,1]
	v_pk_fma_f32 v[186:187], v[138:139], s[36:37], v[186:187] op_sel_hi:[1,0,1]
	v_pk_fma_f32 v[188:189], v[140:141], s[36:37], v[188:189] op_sel_hi:[1,0,1]
	v_pk_fma_f32 v[190:191], v[142:143], s[36:37], v[190:191] op_sel_hi:[1,0,1]
	v_readlane_b32 s36, v43, s37
	s_add_u32 s37, s37, 1
	s_waitcnt vmcnt(15)
; #define PB_FENCE asm volatile("" ::: "memory")
; __device__ __forceinline__ void ph_peer_apply(const Params& P, int layer, float* xlat, float* xctx_in, float* xctx_out, int nrows, bool write_next, char* smem, float* xlat_out = nullptr) {
;     ...
;     PB_LOAD(bufA, tv, 0);
;     for (int gq = 0; gq < NG; gq += 2) {
;       PB_LOAD(bufB, tv, gq + 1); PB_FENCE;
;       PB_ACC(bufA, gq);
;       if (gq + 2 < NG) PB_LOAD(bufA, tv, gq + 2);
;       PB_FENCE;
;       PB_ACC(bufB, gq + 1);
;     }
	v_lshlrev_b32_e32 v192, 23, v70
	v_cvt_scalef32_pk32_f32_fp6 v[112:143], v[64:69], v192
	v_pk_fma_f32 v[160:161], v[112:113], s[36:37], v[160:161] op_sel_hi:[1,0,1]
	v_pk_fma_f32 v[162:163], v[114:115], s[36:37], v[162:163] op_sel_hi:[1,0,1]
	v_pk_fma_f32 v[164:165], v[116:117], s[36:37], v[164:165] op_sel_hi:[1,0,1]
	v_pk_fma_f32 v[166:167], v[118:119], s[36:37], v[166:167] op_sel_hi:[1,0,1]
	v_pk_fma_f32 v[168:169], v[120:121], s[36:37], v[168:169] op_sel_hi:[1,0,1]
	v_pk_fma_f32 v[170:171], v[122:123], s[36:37], v[170:171] op_sel_hi:[1,0,1]
	v_pk_fma_f32 v[172:173], v[124:125], s[36:37], v[172:173] op_sel_hi:[1,0,1]
	v_pk_fma_f32 v[174:175], v[126:127], s[36:37], v[174:175] op_sel_hi:[1,0,1]
	v_pk_fma_f32 v[176:177], v[128:129], s[36:37], v[176:177] op_sel_hi:[1,0,1]
	v_pk_fma_f32 v[178:179], v[130:131], s[36:37], v[178:179] op_sel_hi:[1,0,1]
	v_pk_fma_f32 v[180:181], v[132:133], s[36:37], v[180:181] op_sel_hi:[1,0,1]
	v_pk_fma_f32 v[182:183], v[134:135], s[36:37], v[182:183] op_sel_hi:[1,0,1]
	v_pk_fma_f32 v[184:185], v[136:137], s[36:37], v[184:185] op_sel_hi:[1,0,1]
	v_pk_fma_f32 v[186:187], v[138:139], s[36:37], v[186:187] op_sel_hi:[1,0,1]
	v_pk_fma_f32 v[188:189], v[140:141], s[36:37], v[188:189] op_sel_hi:[1,0,1]
	v_pk_fma_f32 v[190:191], v[142:143], s[36:37], v[190:191] op_sel_hi:[1,0,1]
	v_readlane_b32 s36, v43, s37
	s_add_u32 s37, s37, 1
	s_waitcnt vmcnt(12)
	v_lshlrev_b32_e32 v192, 23, v78
	v_cvt_scalef32_pk32_f32_fp6 v[112:143], v[72:77], v192
	v_pk_fma_f32 v[160:161], v[112:113], s[36:37], v[160:161] op_sel_hi:[1,0,1]
	v_pk_fma_f32 v[162:163], v[114:115], s[36:37], v[162:163] op_sel_hi:[1,0,1]
	v_pk_fma_f32 v[164:165], v[116:117], s[36:37], v[164:165] op_sel_hi:[1,0,1]
	v_pk_fma_f32 v[166:167], v[118:119], s[36:37], v[166:167] op_sel_hi:[1,0,1]
	v_pk_fma_f32 v[168:169], v[120:121], s[36:37], v[168:169] op_sel_hi:[1,0,1]
	v_pk_fma_f32 v[170:171], v[122:123], s[36:37], v[170:171] op_sel_hi:[1,0,1]
	v_pk_fma_f32 v[172:173], v[124:125], s[36:37], v[172:173] op_sel_hi:[1,0,1]
	v_pk_fma_f32 v[174:175], v[126:127], s[36:37], v[174:175] op_sel_hi:[1,0,1]
	v_pk_fma_f32 v[176:177], v[128:129], s[36:37], v[176:177] op_sel_hi:[1,0,1]
	v_pk_fma_f32 v[178:179], v[130:131], s[36:37], v[178:179] op_sel_hi:[1,0,1]
	v_pk_fma_f32 v[180:181], v[132:133], s[36:37], v[180:181] op_sel_hi:[1,0,1]
	v_pk_fma_f32 v[182:183], v[134:135], s[36:37], v[182:183] op_sel_hi:[1,0,1]
	v_pk_fma_f32 v[184:185], v[136:137], s[36:37], v[184:185] op_sel_hi:[1,0,1]
	v_pk_fma_f32 v[186:187], v[138:139], s[36:37], v[186:187] op_sel_hi:[1,0,1]
	v_pk_fma_f32 v[188:189], v[140:141], s[36:37], v[188:189] op_sel_hi:[1,0,1]
	v_pk_fma_f32 v[190:191], v[142:143], s[36:37], v[190:191] op_sel_hi:[1,0,1]
	v_readlane_b32 s36, v43, s37
	s_add_u32 s37, s37, 1
	s_waitcnt vmcnt(9)
	v_lshlrev_b32_e32 v192, 23, v86
	v_cvt_scalef32_pk32_f32_fp6 v[112:143], v[80:85], v192
	v_pk_fma_f32 v[160:161], v[112:113], s[36:37], v[160:161] op_sel_hi:[1,0,1]
	v_pk_fma_f32 v[162:163], v[114:115], s[36:37], v[162:163] op_sel_hi:[1,0,1]
	v_pk_fma_f32 v[164:165], v[116:117], s[36:37], v[164:165] op_sel_hi:[1,0,1]
	v_pk_fma_f32 v[166:167], v[118:119], s[36:37], v[166:167] op_sel_hi:[1,0,1]
	v_pk_fma_f32 v[168:169], v[120:121], s[36:37], v[168:169] op_sel_hi:[1,0,1]
	v_pk_fma_f32 v[170:171], v[122:123], s[36:37], v[170:171] op_sel_hi:[1,0,1]
	v_pk_fma_f32 v[172:173], v[124:125], s[36:37], v[172:173] op_sel_hi:[1,0,1]
	v_pk_fma_f32 v[174:175], v[126:127], s[36:37], v[174:175] op_sel_hi:[1,0,1]
	v_pk_fma_f32 v[176:177], v[128:129], s[36:37], v[176:177] op_sel_hi:[1,0,1]
	v_pk_fma_f32 v[178:179], v[130:131], s[36:37], v[178:179] op_sel_hi:[1,0,1]
	v_pk_fma_f32 v[180:181], v[132:133], s[36:37], v[180:181] op_sel_hi:[1,0,1]
	v_pk_fma_f32 v[182:183], v[134:135], s[36:37], v[182:183] op_sel_hi:[1,0,1]
	v_pk_fma_f32 v[184:185], v[136:137], s[36:37], v[184:185] op_sel_hi:[1,0,1]
	v_pk_fma_f32 v[186:187], v[138:139], s[36:37], v[186:187] op_sel_hi:[1,0,1]
	v_pk_fma_f32 v[188:189], v[140:141], s[36:37], v[188:189] op_sel_hi:[1,0,1]
	v_pk_fma_f32 v[190:191], v[142:143], s[36:37], v[190:191] op_sel_hi:[1,0,1]
	v_readlane_b32 s36, v43, s37
	s_add_u32 s37, s37, 1
	s_waitcnt vmcnt(6)
	v_lshlrev_b32_e32 v192, 23, v94
	v_cvt_scalef32_pk32_f32_fp6 v[112:143], v[88:93], v192
	v_pk_fma_f32 v[160:161], v[112:113], s[36:37], v[160:161] op_sel_hi:[1,0,1]
	v_pk_fma_f32 v[162:163], v[114:115], s[36:37], v[162:163] op_sel_hi:[1,0,1]
	v_pk_fma_f32 v[164:165], v[116:117], s[36:37], v[164:165] op_sel_hi:[1,0,1]
	v_pk_fma_f32 v[166:167], v[118:119], s[36:37], v[166:167] op_sel_hi:[1,0,1]
	v_pk_fma_f32 v[168:169], v[120:121], s[36:37], v[168:169] op_sel_hi:[1,0,1]
	v_pk_fma_f32 v[170:171], v[122:123], s[36:37], v[170:171] op_sel_hi:[1,0,1]
	v_pk_fma_f32 v[172:173], v[124:125], s[36:37], v[172:173] op_sel_hi:[1,0,1]
	v_pk_fma_f32 v[174:175], v[126:127], s[36:37], v[174:175] op_sel_hi:[1,0,1]
	v_pk_fma_f32 v[176:177], v[128:129], s[36:37], v[176:177] op_sel_hi:[1,0,1]
	v_pk_fma_f32 v[178:179], v[130:131], s[36:37], v[178:179] op_sel_hi:[1,0,1]
	v_pk_fma_f32 v[180:181], v[132:133], s[36:37], v[180:181] op_sel_hi:[1,0,1]
	v_pk_fma_f32 v[182:183], v[134:135], s[36:37], v[182:183] op_sel_hi:[1,0,1]
	v_pk_fma_f32 v[184:185], v[136:137], s[36:37], v[184:185] op_sel_hi:[1,0,1]
	v_pk_fma_f32 v[186:187], v[138:139], s[36:37], v[186:187] op_sel_hi:[1,0,1]
	v_pk_fma_f32 v[188:189], v[140:141], s[36:37], v[188:189] op_sel_hi:[1,0,1]
	v_pk_fma_f32 v[190:191], v[142:143], s[36:37], v[190:191] op_sel_hi:[1,0,1]
	v_readlane_b32 s36, v43, s37
	s_add_u32 s37, s37, 1
	s_waitcnt vmcnt(3)
; __device__ __forceinline__ void ph_peer_apply(const Params& P, int layer, float* xlat, float* xctx_in, float* xctx_out, int nrows, bool write_next, char* smem, float* xlat_out = nullptr) {
;     ...
;     const float* xs1 = (row < NL ? xlat + (size_t)row * D : xctx_in + (size_t)(row - NL) * D) + lb * 32;
;     float* xo = (row < NL ? (xlat_out ? xlat_out : xlat) + (size_t)row * D : xctx_out + (size_t)(row - NL) * D) + lb * 32;
;     const float* gt = mod_ptr(P, layer, row, 5) + lb * 32;
;     float s = 0.f;
; #pragma unroll
;     for (int j4 = 0; j4 < 8; ++j4) {
;       float4 xa; const float4 ga = *(const float4*)(gt + j4 * 4);
;       if (row < NL) { const h16x4 xh_ = *(const h16x4*)((const h16*)(xlat + (size_t)row * D) + lb * 32 + j4 * 4); xa = make_float4((float)xh_[0], (float)xh_[1], (float)xh_[2], (float)xh_[3]); }
;       else xa = *(const float4*)(xs1 + j4 * 4);
;       o[j4 * 4 + 0] = ALPHA * xa.x + ga.x * o[j4 * 4 + 0]; o[j4 * 4 + 1] = ALPHA * xa.y + ga.y * o[j4 * 4 + 1];
;       o[j4 * 4 + 2] = ALPHA * xa.z + ga.z * o[j4 * 4 + 2]; o[j4 * 4 + 3] = ALPHA * xa.w + ga.w * o[j4 * 4 + 3];
;       s += (o[j4 * 4 + 0] + o[j4 * 4 + 1]) + (o[j4 * 4 + 2] + o[j4 * 4 + 3]);
	v_lshlrev_b32_e32 v192, 23, v102
	v_cvt_scalef32_pk32_f32_fp6 v[112:143], v[96:101], v192
	v_pk_fma_f32 v[160:161], v[112:113], s[36:37], v[160:161] op_sel_hi:[1,0,1]
	v_pk_fma_f32 v[162:163], v[114:115], s[36:37], v[162:163] op_sel_hi:[1,0,1]
	v_pk_fma_f32 v[164:165], v[116:117], s[36:37], v[164:165] op_sel_hi:[1,0,1]
	v_pk_fma_f32 v[166:167], v[118:119], s[36:37], v[166:167] op_sel_hi:[1,0,1]
	v_pk_fma_f32 v[168:169], v[120:121], s[36:37], v[168:169] op_sel_hi:[1,0,1]
	v_pk_fma_f32 v[170:171], v[122:123], s[36:37], v[170:171] op_sel_hi:[1,0,1]
	v_pk_fma_f32 v[172:173], v[124:125], s[36:37], v[172:173] op_sel_hi:[1,0,1]
	v_pk_fma_f32 v[174:175], v[126:127], s[36:37], v[174:175] op_sel_hi:[1,0,1]
	v_pk_fma_f32 v[176:177], v[128:129], s[36:37], v[176:177] op_sel_hi:[1,0,1]
	v_pk_fma_f32 v[178:179], v[130:131], s[36:37], v[178:179] op_sel_hi:[1,0,1]
	v_pk_fma_f32 v[180:181], v[132:133], s[36:37], v[180:181] op_sel_hi:[1,0,1]
	v_pk_fma_f32 v[182:183], v[134:135], s[36:37], v[182:183] op_sel_hi:[1,0,1]
	v_pk_fma_f32 v[184:185], v[136:137], s[36:37], v[184:185] op_sel_hi:[1,0,1]
	v_pk_fma_f32 v[186:187], v[138:139], s[36:37], v[186:187] op_sel_hi:[1,0,1]
	v_pk_fma_f32 v[188:189], v[140:141], s[36:37], v[188:189] op_sel_hi:[1,0,1]
	v_pk_fma_f32 v[190:191], v[142:143], s[36:37], v[190:191] op_sel_hi:[1,0,1]
	v_readlane_b32 s36, v43, s37
	s_add_u32 s37, s37, 1
	s_waitcnt vmcnt(0)
	v_lshlrev_b32_e32 v192, 23, v110
	v_cvt_scalef32_pk32_f32_fp6 v[112:143], v[104:109], v192
	v_pk_fma_f32 v[160:161], v[112:113], s[36:37], v[160:161] op_sel_hi:[1,0,1]
	v_pk_fma_f32 v[162:163], v[114:115], s[36:37], v[162:163] op_sel_hi:[1,0,1]
	v_pk_fma_f32 v[164:165], v[116:117], s[36:37], v[164:165] op_sel_hi:[1,0,1]
	v_pk_fma_f32 v[166:167], v[118:119], s[36:37], v[166:167] op_sel_hi:[1,0,1]
	v_pk_fma_f32 v[168:169], v[120:121], s[36:37], v[168:169] op_sel_hi:[1,0,1]
	v_pk_fma_f32 v[170:171], v[122:123], s[36:37], v[170:171] op_sel_hi:[1,0,1]
	v_pk_fma_f32 v[172:173], v[124:125], s[36:37], v[172:173] op_sel_hi:[1,0,1]
	v_pk_fma_f32 v[174:175], v[126:127], s[36:37], v[174:175] op_sel_hi:[1,0,1]
	v_pk_fma_f32 v[176:177], v[128:129], s[36:37], v[176:177] op_sel_hi:[1,0,1]
	v_pk_fma_f32 v[178:179], v[130:131], s[36:37], v[178:179] op_sel_hi:[1,0,1]
	v_pk_fma_f32 v[180:181], v[132:133], s[36:37], v[180:181] op_sel_hi:[1,0,1]
	v_pk_fma_f32 v[182:183], v[134:135], s[36:37], v[182:183] op_sel_hi:[1,0,1]
	v_pk_fma_f32 v[184:185], v[136:137], s[36:37], v[184:185] op_sel_hi:[1,0,1]
	v_pk_fma_f32 v[186:187], v[138:139], s[36:37], v[186:187] op_sel_hi:[1,0,1]
	v_pk_fma_f32 v[188:189], v[140:141], s[36:37], v[188:189] op_sel_hi:[1,0,1]
	v_pk_fma_f32 v[190:191], v[142:143], s[36:37], v[190:191] op_sel_hi:[1,0,1]
	s_cmp_ge_u32 s45, 0x8000
	s_cselect_b32 s48, 1, 0
	s_lshr_b32 s49, s45, 14
	s_cmp_lg_u32 s48, 0
	s_cselect_b32 s49, 2, s49
	s_sub_u32 s50, s45, 0x8000
	s_lshl_b32 s15, s45, 13
	s_lshr_b32 s31, s45, 19
	s_add_u32 s40, s6, s15
	s_addc_u32 s41, s7, s31
	s_add_u32 s15, s49, 0
	s_mul_i32 s15, s15, 6
	s_add_u32 s15, s15, 5
	s_lshl_b32 s15, s15, 13
	s_add_u32 s42, s4, 0x4000
	s_addc_u32 s43, s5, 0
	s_add_u32 s42, s42, s15
	s_addc_u32 s43, s43, 0
	global_load_dwordx4 v[112:115], v225, s[42:43]
	global_load_dwordx4 v[116:119], v225, s[42:43] offset:16
	global_load_dwordx4 v[120:123], v225, s[42:43] offset:32
	global_load_dwordx4 v[124:127], v225, s[42:43] offset:48
	global_load_dwordx4 v[128:131], v225, s[42:43] offset:64
	global_load_dwordx4 v[132:135], v225, s[42:43] offset:80
	global_load_dwordx4 v[136:139], v225, s[42:43] offset:96
	global_load_dwordx4 v[140:143], v225, s[42:43] offset:112
	s_mov_b32 s15, 0x3fb504f3
	s_cmp_lg_u32 s48, 0
	s_cbranch_scc1 .Lap0_res_ctx
	global_load_dwordx4 v[192:195], v224, s[40:41]
	global_load_dwordx4 v[196:199], v224, s[40:41] offset:16
	global_load_dwordx4 v[200:203], v224, s[40:41] offset:32
	global_load_dwordx4 v[204:207], v224, s[40:41] offset:48
	s_waitcnt vmcnt(0)
	v_mul_f32_e32 v160, v112, v160
	v_mul_f32_e32 v161, v113, v161
	v_mul_f32_e32 v162, v114, v162
	v_mul_f32_e32 v163, v115, v163
	v_mul_f32_e32 v164, v116, v164
	v_mul_f32_e32 v165, v117, v165
	v_mul_f32_e32 v166, v118, v166
	v_mul_f32_e32 v167, v119, v167
	v_mul_f32_e32 v168, v120, v168
	v_mul_f32_e32 v169, v121, v169
	v_mul_f32_e32 v170, v122, v170
	v_mul_f32_e32 v171, v123, v171
	v_mul_f32_e32 v172, v124, v172
	v_mul_f32_e32 v173, v125, v173
	v_mul_f32_e32 v174, v126, v174
	v_mul_f32_e32 v175, v127, v175
	v_mul_f32_e32 v176, v128, v176
	v_mul_f32_e32 v177, v129, v177
	v_mul_f32_e32 v178, v130, v178
	v_mul_f32_e32 v179, v131, v179
	v_mul_f32_e32 v180, v132, v180
	v_mul_f32_e32 v181, v133, v181
	v_mul_f32_e32 v182, v134, v182
	v_mul_f32_e32 v183, v135, v183
	v_mul_f32_e32 v184, v136, v184
	v_mul_f32_e32 v185, v137, v185
	v_mul_f32_e32 v186, v138, v186
	v_mul_f32_e32 v187, v139, v187
	v_mul_f32_e32 v188, v140, v188
	v_mul_f32_e32 v189, v141, v189
	v_mul_f32_e32 v190, v142, v190
	v_mul_f32_e32 v191, v143, v191
	v_fma_mix_f32 v160, s15, v192, v160 op_sel_hi:[0,1,0]
	v_fma_mix_f32 v161, s15, v192, v161 op_sel:[0,1,0] op_sel_hi:[0,1,0]
	v_fma_mix_f32 v162, s15, v193, v162 op_sel_hi:[0,1,0]
	v_fma_mix_f32 v163, s15, v193, v163 op_sel:[0,1,0] op_sel_hi:[0,1,0]
	v_fma_mix_f32 v164, s15, v194, v164 op_sel_hi:[0,1,0]
	v_fma_mix_f32 v165, s15, v194, v165 op_sel:[0,1,0] op_sel_hi:[0,1,0]
	v_fma_mix_f32 v166, s15, v195, v166 op_sel_hi:[0,1,0]
	v_fma_mix_f32 v167, s15, v195, v167 op_sel:[0,1,0] op_sel_hi:[0,1,0]
	v_fma_mix_f32 v168, s15, v196, v168 op_sel_hi:[0,1,0]
	v_fma_mix_f32 v169, s15, v196, v169 op_sel:[0,1,0] op_sel_hi:[0,1,0]
	v_fma_mix_f32 v170, s15, v197, v170 op_sel_hi:[0,1,0]
	v_fma_mix_f32 v171, s15, v197, v171 op_sel:[0,1,0] op_sel_hi:[0,1,0]
	v_fma_mix_f32 v172, s15, v198, v172 op_sel_hi:[0,1,0]
	v_fma_mix_f32 v173, s15, v198, v173 op_sel:[0,1,0] op_sel_hi:[0,1,0]
	v_fma_mix_f32 v174, s15, v199, v174 op_sel_hi:[0,1,0]
	v_fma_mix_f32 v175, s15, v199, v175 op_sel:[0,1,0] op_sel_hi:[0,1,0]
	v_fma_mix_f32 v176, s15, v200, v176 op_sel_hi:[0,1,0]
	v_fma_mix_f32 v177, s15, v200, v177 op_sel:[0,1,0] op_sel_hi:[0,1,0]
	v_fma_mix_f32 v178, s15, v201, v178 op_sel_hi:[0,1,0]
	v_fma_mix_f32 v179, s15, v201, v179 op_sel:[0,1,0] op_sel_hi:[0,1,0]
	v_fma_mix_f32 v180, s15, v202, v180 op_sel_hi:[0,1,0]
	v_fma_mix_f32 v181, s15, v202, v181 op_sel:[0,1,0] op_sel_hi:[0,1,0]
	v_fma_mix_f32 v182, s15, v203, v182 op_sel_hi:[0,1,0]
	v_fma_mix_f32 v183, s15, v203, v183 op_sel:[0,1,0] op_sel_hi:[0,1,0]
	v_fma_mix_f32 v184, s15, v204, v184 op_sel_hi:[0,1,0]
	v_fma_mix_f32 v185, s15, v204, v185 op_sel:[0,1,0] op_sel_hi:[0,1,0]
	v_fma_mix_f32 v186, s15, v205, v186 op_sel_hi:[0,1,0]
	v_fma_mix_f32 v187, s15, v205, v187 op_sel:[0,1,0] op_sel_hi:[0,1,0]
	v_fma_mix_f32 v188, s15, v206, v188 op_sel_hi:[0,1,0]
	v_fma_mix_f32 v189, s15, v206, v189 op_sel:[0,1,0] op_sel_hi:[0,1,0]
	v_fma_mix_f32 v190, s15, v207, v190 op_sel_hi:[0,1,0]
	v_fma_mix_f32 v191, s15, v207, v191 op_sel:[0,1,0] op_sel_hi:[0,1,0]
	s_branch .Lap0_res_done

; __device__ __forceinline__ void ph_peer_apply(const Params& P, int layer, float* xlat, float* xctx_in, float* xctx_out, int nrows, bool write_next, char* smem, float* xlat_out = nullptr) {
;     ...
;   for (int row = blockIdx.x * (NTHR / 64) + wave; row < nrows; row += gridDim.x * (NTHR / 64)) {
;     float xv[32];
; #pragma unroll
;     for (int j8 = 0; j8 < 4; ++j8) {
;       const h16x8 t = *(const h16x8*)(xq + (size_t)row * D + lb * 32 + j8 * 8);
; #pragma unroll
;       for (int j = 0; j < 8; ++j) xv[j8 * 8 + j] = lact ? (float)t[j] : 0.f;
;     }
;     const int id0 = seli[(size_t)row * NSEL + lane], id1 = seli[(size_t)row * NSEL + 64 + lane];
;     const float g0 = selg[(size_t)row * NSEL + lane], g1 = selg[(size_t)row * NSEL + 64 + lane];
.Lap1_ntl:
	s_add_u32 s50, s50, 1
	s_add_u32 s1, s1, s44
	s_cmp_lt_u32 s1, 0x8000
	s_cbranch_scc1 .Lap1_ntl
	s_mov_b32 s58, 0
	s_mov_b32 s59, 0
	s_mov_b32 s62, 0
	s_mov_b32 s48, 0
	s_mov_b32 s49, 0
	s_mov_b32 s45, s13
	s_lshl_b32 s15, s45, 12
	s_lshr_b32 s31, s45, 20
	s_add_u32 s20, s4, 0xbe4c000
	s_addc_u32 s21, s5, 0
	s_add_u32 s20, s20, s15
	s_addc_u32 s21, s21, s31
	s_lshl_b32 s15, s45, 9
	s_add_u32 s22, s4, 0x1404c000
	s_addc_u32 s23, s5, 0
	s_add_u32 s22, s22, s15
	s_addc_u32 s23, s23, 0
	global_load_dwordx4 v[200:203], v224, s[20:21]
	global_load_dwordx4 v[204:207], v224, s[20:21] offset:16
	global_load_dwordx4 v[208:211], v224, s[20:21] offset:32
	global_load_dwordx4 v[212:215], v224, s[20:21] offset:48
	global_load_dword v36, v226, s[22:23]
	global_load_dword v37, v226, s[22:23] offset:256
	s_waitcnt vmcnt(0)
	v_cvt_f32_f16_e32 v4, v200
	v_cvt_f32_f16_sdwa v5, v200 dst_sel:DWORD dst_unused:UNUSED_PAD src0_sel:WORD_1
	v_cvt_f32_f16_e32 v6, v201
	v_cvt_f32_f16_sdwa v7, v201 dst_sel:DWORD dst_unused:UNUSED_PAD src0_sel:WORD_1
	v_cvt_f32_f16_e32 v8, v202
	v_cvt_f32_f16_sdwa v9, v202 dst_sel:DWORD dst_unused:UNUSED_PAD src0_sel:WORD_1
	v_cvt_f32_f16_e32 v10, v203
	v_cvt_f32_f16_sdwa v11, v203 dst_sel:DWORD dst_unused:UNUSED_PAD src0_sel:WORD_1
	v_cvt_f32_f16_e32 v12, v204
	v_cvt_f32_f16_sdwa v13, v204 dst_sel:DWORD dst_unused:UNUSED_PAD src0_sel:WORD_1
	v_cvt_f32_f16_e32 v14, v205
	v_cvt_f32_f16_sdwa v15, v205 dst_sel:DWORD dst_unused:UNUSED_PAD src0_sel:WORD_1
	v_cvt_f32_f16_e32 v16, v206
	v_cvt_f32_f16_sdwa v17, v206 dst_sel:DWORD dst_unused:UNUSED_PAD src0_sel:WORD_1
	v_cvt_f32_f16_e32 v18, v207
	v_cvt_f32_f16_sdwa v19, v207 dst_sel:DWORD dst_unused:UNUSED_PAD src0_sel:WORD_1
	v_cvt_f32_f16_e32 v20, v208
	v_cvt_f32_f16_sdwa v21, v208 dst_sel:DWORD dst_unused:UNUSED_PAD src0_sel:WORD_1
	v_cvt_f32_f16_e32 v22, v209
	v_cvt_f32_f16_sdwa v23, v209 dst_sel:DWORD dst_unused:UNUSED_PAD src0_sel:WORD_1
	v_cvt_f32_f16_e32 v24, v210
	v_cvt_f32_f16_sdwa v25, v210 dst_sel:DWORD dst_unused:UNUSED_PAD src0_sel:WORD_1
	v_cvt_f32_f16_e32 v26, v211
	v_cvt_f32_f16_sdwa v27, v211 dst_sel:DWORD dst_unused:UNUSED_PAD src0_sel:WORD_1
	v_cvt_f32_f16_e32 v28, v212
	v_cvt_f32_f16_sdwa v29, v212 dst_sel:DWORD dst_unused:UNUSED_PAD src0_sel:WORD_1
	v_cvt_f32_f16_e32 v30, v213
	v_cvt_f32_f16_sdwa v31, v213 dst_sel:DWORD dst_unused:UNUSED_PAD src0_sel:WORD_1
	v_cvt_f32_f16_e32 v32, v214
	v_cvt_f32_f16_sdwa v33, v214 dst_sel:DWORD dst_unused:UNUSED_PAD src0_sel:WORD_1
	v_cvt_f32_f16_e32 v34, v215
	v_cvt_f32_f16_sdwa v35, v215 dst_sel:DWORD dst_unused:UNUSED_PAD src0_sel:WORD_1
	v_lshrrev_b32_e32 v195, 11, v36
	v_lshrrev_b32_e32 v196, 11, v37
	v_cmp_eq_u32_e64 s[52:53], s58, v195
	v_cmp_eq_u32_e64 s[54:55], s58, v196
	v_mov_b32_e32 v44, v36
	s_mov_b32 s61, 0
	s_mov_b32 s57, 0
	s_lshl_b32 s63, s59, 9
	s_mul_i32 s1, s12, 0x2800
	s_add_u32 s63, s63, s1
	s_lshl_b32 s1, s62, 31
	s_or_b32 s63, s63, s1
	v_mov_b32_e32 v45, 0

; #define PB_FENCE asm volatile("" ::: "memory")
; __device__ __forceinline__ void ph_peer_apply(const Params& P, int layer, float* xlat, float* xctx_in, float* xctx_out, int nrows, bool write_next, char* smem, float* xlat_out = nullptr) {
;     ...
;     PB_LOAD(bufA, tv, 0);
;     for (int gq = 0; gq < NG; gq += 2) {
;       PB_LOAD(bufB, tv, gq + 1); PB_FENCE;
;       PB_ACC(bufA, gq);
;       if (gq + 2 < NG) PB_LOAD(bufA, tv, gq + 2);
;       PB_FENCE;
;       PB_ACC(bufB, gq + 1);
;     }
.Lap1_s2_loop4:
	v_readlane_b32 s36, v43, s37
	s_add_u32 s37, s37, 1
	s_waitcnt vmcnt(21)
	v_lshlrev_b32_e32 v192, 23, v54
	v_cvt_scalef32_pk32_f32_fp6 v[112:143], v[48:53], v192
	v_pk_fma_f32 v[160:161], v[112:113], s[36:37], v[160:161] op_sel_hi:[1,0,1]
	v_pk_fma_f32 v[162:163], v[114:115], s[36:37], v[162:163] op_sel_hi:[1,0,1]
	v_pk_fma_f32 v[164:165], v[116:117], s[36:37], v[164:165] op_sel_hi:[1,0,1]
	v_pk_fma_f32 v[166:167], v[118:119], s[36:37], v[166:167] op_sel_hi:[1,0,1]
	v_pk_fma_f32 v[168:169], v[120:121], s[36:37], v[168:169] op_sel_hi:[1,0,1]
	v_pk_fma_f32 v[170:171], v[122:123], s[36:37], v[170:171] op_sel_hi:[1,0,1]
	v_pk_fma_f32 v[172:173], v[124:125], s[36:37], v[172:173] op_sel_hi:[1,0,1]
	v_pk_fma_f32 v[174:175], v[126:127], s[36:37], v[174:175] op_sel_hi:[1,0,1]
	v_pk_fma_f32 v[176:177], v[128:129], s[36:37], v[176:177] op_sel_hi:[1,0,1]
	v_pk_fma_f32 v[178:179], v[130:131], s[36:37], v[178:179] op_sel_hi:[1,0,1]
	v_pk_fma_f32 v[180:181], v[132:133], s[36:37], v[180:181] op_sel_hi:[1,0,1]
	v_pk_fma_f32 v[182:183], v[134:135], s[36:37], v[182:183] op_sel_hi:[1,0,1]
	v_pk_fma_f32 v[184:185], v[136:137], s[36:37], v[184:185] op_sel_hi:[1,0,1]
	v_pk_fma_f32 v[186:187], v[138:139], s[36:37], v[186:187] op_sel_hi:[1,0,1]
	v_pk_fma_f32 v[188:189], v[140:141], s[36:37], v[188:189] op_sel_hi:[1,0,1]
	v_pk_fma_f32 v[190:191], v[142:143], s[36:37], v[190:191] op_sel_hi:[1,0,1]
	v_readlane_b32 s29, v37, s28
	s_add_u32 s28, s28, 1
	s_mul_hi_u32 s27, s29, 0x640
	s_mul_i32 s26, s29, 0x640
	s_add_u32 s26, s18, s26
	s_addc_u32 s27, s19, s27
	global_load_dwordx4 v[48:51], v2, s[26:27]
	global_load_dwordx2 v[52:53], v2, s[26:27] offset:16
	global_load_ubyte v54, v3, s[26:27]
	v_readlane_b32 s36, v43, s37
	s_add_u32 s37, s37, 1
	s_waitcnt vmcnt(21)
	v_lshlrev_b32_e32 v192, 23, v62
	v_cvt_scalef32_pk32_f32_fp6 v[112:143], v[56:61], v192
	v_pk_fma_f32 v[160:161], v[112:113], s[36:37], v[160:161] op_sel_hi:[1,0,1]
	v_pk_fma_f32 v[162:163], v[114:115], s[36:37], v[162:163] op_sel_hi:[1,0,1]
	v_pk_fma_f32 v[164:165], v[116:117], s[36:37], v[164:165] op_sel_hi:[1,0,1]
	v_pk_fma_f32 v[166:167], v[118:119], s[36:37], v[166:167] op_sel_hi:[1,0,1]
	v_pk_fma_f32 v[168:169], v[120:121], s[36:37], v[168:169] op_sel_hi:[1,0,1]
	v_pk_fma_f32 v[170:171], v[122:123], s[36:37], v[170:171] op_sel_hi:[1,0,1]
	v_pk_fma_f32 v[172:173], v[124:125], s[36:37], v[172:173] op_sel_hi:[1,0,1]
	v_pk_fma_f32 v[174:175], v[126:127], s[36:37], v[174:175] op_sel_hi:[1,0,1]
	v_pk_fma_f32 v[176:177], v[128:129], s[36:37], v[176:177] op_sel_hi:[1,0,1]
	v_pk_fma_f32 v[178:179], v[130:131], s[36:37], v[178:179] op_sel_hi:[1,0,1]
	v_pk_fma_f32 v[180:181], v[132:133], s[36:37], v[180:181] op_sel_hi:[1,0,1]
	v_pk_fma_f32 v[182:183], v[134:135], s[36:37], v[182:183] op_sel_hi:[1,0,1]
	v_pk_fma_f32 v[184:185], v[136:137], s[36:37], v[184:185] op_sel_hi:[1,0,1]
	v_pk_fma_f32 v[186:187], v[138:139], s[36:37], v[186:187] op_sel_hi:[1,0,1]
	v_pk_fma_f32 v[188:189], v[140:141], s[36:37], v[188:189] op_sel_hi:[1,0,1]
	v_pk_fma_f32 v[190:191], v[142:143], s[36:37], v[190:191] op_sel_hi:[1,0,1]
	v_readlane_b32 s29, v37, s28
	s_add_u32 s28, s28, 1
	s_mul_hi_u32 s27, s29, 0x640
	s_mul_i32 s26, s29, 0x640
	s_add_u32 s26, s18, s26
	s_addc_u32 s27, s19, s27
	global_load_dwordx4 v[56:59], v2, s[26:27]
	global_load_dwordx2 v[60:61], v2, s[26:27] offset:16
	global_load_ubyte v62, v3, s[26:27]
	v_readlane_b32 s36, v43, s37
	s_add_u32 s37, s37, 1
	s_waitcnt vmcnt(21)
	v_lshlrev_b32_e32 v192, 23, v70
	v_cvt_scalef32_pk32_f32_fp6 v[112:143], v[64:69], v192
	v_pk_fma_f32 v[160:161], v[112:113], s[36:37], v[160:161] op_sel_hi:[1,0,1]
	v_pk_fma_f32 v[162:163], v[114:115], s[36:37], v[162:163] op_sel_hi:[1,0,1]
	v_pk_fma_f32 v[164:165], v[116:117], s[36:37], v[164:165] op_sel_hi:[1,0,1]
	v_pk_fma_f32 v[166:167], v[118:119], s[36:37], v[166:167] op_sel_hi:[1,0,1]
	v_pk_fma_f32 v[168:169], v[120:121], s[36:37], v[168:169] op_sel_hi:[1,0,1]
	v_pk_fma_f32 v[170:171], v[122:123], s[36:37], v[170:171] op_sel_hi:[1,0,1]
	v_pk_fma_f32 v[172:173], v[124:125], s[36:37], v[172:173] op_sel_hi:[1,0,1]
	v_pk_fma_f32 v[174:175], v[126:127], s[36:37], v[174:175] op_sel_hi:[1,0,1]
	v_pk_fma_f32 v[176:177], v[128:129], s[36:37], v[176:177] op_sel_hi:[1,0,1]
	v_pk_fma_f32 v[178:179], v[130:131], s[36:37], v[178:179] op_sel_hi:[1,0,1]
	v_pk_fma_f32 v[180:181], v[132:133], s[36:37], v[180:181] op_sel_hi:[1,0,1]
	v_pk_fma_f32 v[182:183], v[134:135], s[36:37], v[182:183] op_sel_hi:[1,0,1]
	v_pk_fma_f32 v[184:185], v[136:137], s[36:37], v[184:185] op_sel_hi:[1,0,1]
	v_pk_fma_f32 v[186:187], v[138:139], s[36:37], v[186:187] op_sel_hi:[1,0,1]
	v_pk_fma_f32 v[188:189], v[140:141], s[36:37], v[188:189] op_sel_hi:[1,0,1]
	v_pk_fma_f32 v[190:191], v[142:143], s[36:37], v[190:191] op_sel_hi:[1,0,1]
	v_readlane_b32 s29, v37, s28
	s_add_u32 s28, s28, 1
	s_mul_hi_u32 s27, s29, 0x640
	s_mul_i32 s26, s29, 0x640
	s_add_u32 s26, s18, s26
	s_addc_u32 s27, s19, s27
	global_load_dwordx4 v[64:67], v2, s[26:27]
	global_load_dwordx2 v[68:69], v2, s[26:27] offset:16
	global_load_ubyte v70, v3, s[26:27]
	v_readlane_b32 s36, v43, s37
	s_add_u32 s37, s37, 1
	s_waitcnt vmcnt(21)
; #define PB_FENCE asm volatile("" ::: "memory")
; __device__ __forceinline__ void ph_peer_apply(const Params& P, int layer, float* xlat, float* xctx_in, float* xctx_out, int nrows, bool write_next, char* smem, float* xlat_out = nullptr) {
;     ...
;     PB_LOAD(bufA, tv, 0);
;     for (int gq = 0; gq < NG; gq += 2) {
;       PB_LOAD(bufB, tv, gq + 1); PB_FENCE;
;       PB_ACC(bufA, gq);
;       if (gq + 2 < NG) PB_LOAD(bufA, tv, gq + 2);
;       PB_FENCE;
;       PB_ACC(bufB, gq + 1);
;     }
	v_lshlrev_b32_e32 v192, 23, v78
	v_cvt_scalef32_pk32_f32_fp6 v[112:143], v[72:77], v192
	v_pk_fma_f32 v[160:161], v[112:113], s[36:37], v[160:161] op_sel_hi:[1,0,1]
	v_pk_fma_f32 v[162:163], v[114:115], s[36:37], v[162:163] op_sel_hi:[1,0,1]
	v_pk_fma_f32 v[164:165], v[116:117], s[36:37], v[164:165] op_sel_hi:[1,0,1]
	v_pk_fma_f32 v[166:167], v[118:119], s[36:37], v[166:167] op_sel_hi:[1,0,1]
	v_pk_fma_f32 v[168:169], v[120:121], s[36:37], v[168:169] op_sel_hi:[1,0,1]
	v_pk_fma_f32 v[170:171], v[122:123], s[36:37], v[170:171] op_sel_hi:[1,0,1]
	v_pk_fma_f32 v[172:173], v[124:125], s[36:37], v[172:173] op_sel_hi:[1,0,1]
	v_pk_fma_f32 v[174:175], v[126:127], s[36:37], v[174:175] op_sel_hi:[1,0,1]
	v_pk_fma_f32 v[176:177], v[128:129], s[36:37], v[176:177] op_sel_hi:[1,0,1]
	v_pk_fma_f32 v[178:179], v[130:131], s[36:37], v[178:179] op_sel_hi:[1,0,1]
	v_pk_fma_f32 v[180:181], v[132:133], s[36:37], v[180:181] op_sel_hi:[1,0,1]
	v_pk_fma_f32 v[182:183], v[134:135], s[36:37], v[182:183] op_sel_hi:[1,0,1]
	v_pk_fma_f32 v[184:185], v[136:137], s[36:37], v[184:185] op_sel_hi:[1,0,1]
	v_pk_fma_f32 v[186:187], v[138:139], s[36:37], v[186:187] op_sel_hi:[1,0,1]
	v_pk_fma_f32 v[188:189], v[140:141], s[36:37], v[188:189] op_sel_hi:[1,0,1]
	v_pk_fma_f32 v[190:191], v[142:143], s[36:37], v[190:191] op_sel_hi:[1,0,1]
	v_readlane_b32 s29, v37, s28
	s_add_u32 s28, s28, 1
	s_mul_hi_u32 s27, s29, 0x640
	s_mul_i32 s26, s29, 0x640
	s_add_u32 s26, s18, s26
	s_addc_u32 s27, s19, s27
	global_load_dwordx4 v[72:75], v2, s[26:27]
	global_load_dwordx2 v[76:77], v2, s[26:27] offset:16
	global_load_ubyte v78, v3, s[26:27]
	v_readlane_b32 s36, v43, s37
	s_add_u32 s37, s37, 1
	s_waitcnt vmcnt(21)
	v_lshlrev_b32_e32 v192, 23, v86
	v_cvt_scalef32_pk32_f32_fp6 v[112:143], v[80:85], v192
	v_pk_fma_f32 v[160:161], v[112:113], s[36:37], v[160:161] op_sel_hi:[1,0,1]
	v_pk_fma_f32 v[162:163], v[114:115], s[36:37], v[162:163] op_sel_hi:[1,0,1]
	v_pk_fma_f32 v[164:165], v[116:117], s[36:37], v[164:165] op_sel_hi:[1,0,1]
	v_pk_fma_f32 v[166:167], v[118:119], s[36:37], v[166:167] op_sel_hi:[1,0,1]
	v_pk_fma_f32 v[168:169], v[120:121], s[36:37], v[168:169] op_sel_hi:[1,0,1]
	v_pk_fma_f32 v[170:171], v[122:123], s[36:37], v[170:171] op_sel_hi:[1,0,1]
	v_pk_fma_f32 v[172:173], v[124:125], s[36:37], v[172:173] op_sel_hi:[1,0,1]
	v_pk_fma_f32 v[174:175], v[126:127], s[36:37], v[174:175] op_sel_hi:[1,0,1]
	v_pk_fma_f32 v[176:177], v[128:129], s[36:37], v[176:177] op_sel_hi:[1,0,1]
	v_pk_fma_f32 v[178:179], v[130:131], s[36:37], v[178:179] op_sel_hi:[1,0,1]
	v_pk_fma_f32 v[180:181], v[132:133], s[36:37], v[180:181] op_sel_hi:[1,0,1]
	v_pk_fma_f32 v[182:183], v[134:135], s[36:37], v[182:183] op_sel_hi:[1,0,1]
	v_pk_fma_f32 v[184:185], v[136:137], s[36:37], v[184:185] op_sel_hi:[1,0,1]
	v_pk_fma_f32 v[186:187], v[138:139], s[36:37], v[186:187] op_sel_hi:[1,0,1]
	v_pk_fma_f32 v[188:189], v[140:141], s[36:37], v[188:189] op_sel_hi:[1,0,1]
	v_pk_fma_f32 v[190:191], v[142:143], s[36:37], v[190:191] op_sel_hi:[1,0,1]
	v_readlane_b32 s29, v37, s28
	s_add_u32 s28, s28, 1
	s_mul_hi_u32 s27, s29, 0x640
	s_mul_i32 s26, s29, 0x640
	s_add_u32 s26, s18, s26
	s_addc_u32 s27, s19, s27
	global_load_dwordx4 v[80:83], v2, s[26:27]
	global_load_dwordx2 v[84:85], v2, s[26:27] offset:16
	global_load_ubyte v86, v3, s[26:27]
	v_readlane_b32 s36, v43, s37
	s_add_u32 s37, s37, 1
	s_waitcnt vmcnt(21)
	v_lshlrev_b32_e32 v192, 23, v94
	v_cvt_scalef32_pk32_f32_fp6 v[112:143], v[88:93], v192
	v_pk_fma_f32 v[160:161], v[112:113], s[36:37], v[160:161] op_sel_hi:[1,0,1]
	v_pk_fma_f32 v[162:163], v[114:115], s[36:37], v[162:163] op_sel_hi:[1,0,1]
	v_pk_fma_f32 v[164:165], v[116:117], s[36:37], v[164:165] op_sel_hi:[1,0,1]
	v_pk_fma_f32 v[166:167], v[118:119], s[36:37], v[166:167] op_sel_hi:[1,0,1]
	v_pk_fma_f32 v[168:169], v[120:121], s[36:37], v[168:169] op_sel_hi:[1,0,1]
	v_pk_fma_f32 v[170:171], v[122:123], s[36:37], v[170:171] op_sel_hi:[1,0,1]
	v_pk_fma_f32 v[172:173], v[124:125], s[36:37], v[172:173] op_sel_hi:[1,0,1]
	v_pk_fma_f32 v[174:175], v[126:127], s[36:37], v[174:175] op_sel_hi:[1,0,1]
	v_pk_fma_f32 v[176:177], v[128:129], s[36:37], v[176:177] op_sel_hi:[1,0,1]
	v_pk_fma_f32 v[178:179], v[130:131], s[36:37], v[178:179] op_sel_hi:[1,0,1]
	v_pk_fma_f32 v[180:181], v[132:133], s[36:37], v[180:181] op_sel_hi:[1,0,1]
	v_pk_fma_f32 v[182:183], v[134:135], s[36:37], v[182:183] op_sel_hi:[1,0,1]
	v_pk_fma_f32 v[184:185], v[136:137], s[36:37], v[184:185] op_sel_hi:[1,0,1]
	v_pk_fma_f32 v[186:187], v[138:139], s[36:37], v[186:187] op_sel_hi:[1,0,1]
	v_pk_fma_f32 v[188:189], v[140:141], s[36:37], v[188:189] op_sel_hi:[1,0,1]
	v_pk_fma_f32 v[190:191], v[142:143], s[36:37], v[190:191] op_sel_hi:[1,0,1]
	v_readlane_b32 s29, v37, s28
	s_add_u32 s28, s28, 1
	s_mul_hi_u32 s27, s29, 0x640
	s_mul_i32 s26, s29, 0x640
	s_add_u32 s26, s18, s26
	s_addc_u32 s27, s19, s27
	global_load_dwordx4 v[88:91], v2, s[26:27]
	global_load_dwordx2 v[92:93], v2, s[26:27] offset:16
	global_load_ubyte v94, v3, s[26:27]
	v_readlane_b32 s36, v43, s37
	s_add_u32 s37, s37, 1
	s_waitcnt vmcnt(21)
; #define PB_FENCE asm volatile("" ::: "memory")
; __device__ __forceinline__ void ph_peer_apply(const Params& P, int layer, float* xlat, float* xctx_in, float* xctx_out, int nrows, bool write_next, char* smem, float* xlat_out = nullptr) {
;     ...
;     PB_LOAD(bufA, tv, 0);
;     for (int gq = 0; gq < NG; gq += 2) {
;       PB_LOAD(bufB, tv, gq + 1); PB_FENCE;
;       PB_ACC(bufA, gq);
;       if (gq + 2 < NG) PB_LOAD(bufA, tv, gq + 2);
;       PB_FENCE;
;       PB_ACC(bufB, gq + 1);
;     }
	v_lshlrev_b32_e32 v192, 23, v102
	v_cvt_scalef32_pk32_f32_fp6 v[112:143], v[96:101], v192
	v_pk_fma_f32 v[160:161], v[112:113], s[36:37], v[160:161] op_sel_hi:[1,0,1]
	v_pk_fma_f32 v[162:163], v[114:115], s[36:37], v[162:163] op_sel_hi:[1,0,1]
	v_pk_fma_f32 v[164:165], v[116:117], s[36:37], v[164:165] op_sel_hi:[1,0,1]
	v_pk_fma_f32 v[166:167], v[118:119], s[36:37], v[166:167] op_sel_hi:[1,0,1]
	v_pk_fma_f32 v[168:169], v[120:121], s[36:37], v[168:169] op_sel_hi:[1,0,1]
	v_pk_fma_f32 v[170:171], v[122:123], s[36:37], v[170:171] op_sel_hi:[1,0,1]
	v_pk_fma_f32 v[172:173], v[124:125], s[36:37], v[172:173] op_sel_hi:[1,0,1]
	v_pk_fma_f32 v[174:175], v[126:127], s[36:37], v[174:175] op_sel_hi:[1,0,1]
	v_pk_fma_f32 v[176:177], v[128:129], s[36:37], v[176:177] op_sel_hi:[1,0,1]
	v_pk_fma_f32 v[178:179], v[130:131], s[36:37], v[178:179] op_sel_hi:[1,0,1]
	v_pk_fma_f32 v[180:181], v[132:133], s[36:37], v[180:181] op_sel_hi:[1,0,1]
	v_pk_fma_f32 v[182:183], v[134:135], s[36:37], v[182:183] op_sel_hi:[1,0,1]
	v_pk_fma_f32 v[184:185], v[136:137], s[36:37], v[184:185] op_sel_hi:[1,0,1]
	v_pk_fma_f32 v[186:187], v[138:139], s[36:37], v[186:187] op_sel_hi:[1,0,1]
	v_pk_fma_f32 v[188:189], v[140:141], s[36:37], v[188:189] op_sel_hi:[1,0,1]
	v_pk_fma_f32 v[190:191], v[142:143], s[36:37], v[190:191] op_sel_hi:[1,0,1]
	v_readlane_b32 s29, v37, s28
	s_add_u32 s28, s28, 1
	s_mul_hi_u32 s27, s29, 0x640
	s_mul_i32 s26, s29, 0x640
	s_add_u32 s26, s18, s26
	s_addc_u32 s27, s19, s27
	global_load_dwordx4 v[96:99], v2, s[26:27]
	global_load_dwordx2 v[100:101], v2, s[26:27] offset:16
	global_load_ubyte v102, v3, s[26:27]
	v_readlane_b32 s36, v43, s37
	s_add_u32 s37, s37, 1
	s_waitcnt vmcnt(21)
	v_lshlrev_b32_e32 v192, 23, v110
	v_cvt_scalef32_pk32_f32_fp6 v[112:143], v[104:109], v192
	v_pk_fma_f32 v[160:161], v[112:113], s[36:37], v[160:161] op_sel_hi:[1,0,1]
	v_pk_fma_f32 v[162:163], v[114:115], s[36:37], v[162:163] op_sel_hi:[1,0,1]
	v_pk_fma_f32 v[164:165], v[116:117], s[36:37], v[164:165] op_sel_hi:[1,0,1]
	v_pk_fma_f32 v[166:167], v[118:119], s[36:37], v[166:167] op_sel_hi:[1,0,1]
	v_pk_fma_f32 v[168:169], v[120:121], s[36:37], v[168:169] op_sel_hi:[1,0,1]
	v_pk_fma_f32 v[170:171], v[122:123], s[36:37], v[170:171] op_sel_hi:[1,0,1]
	v_pk_fma_f32 v[172:173], v[124:125], s[36:37], v[172:173] op_sel_hi:[1,0,1]
	v_pk_fma_f32 v[174:175], v[126:127], s[36:37], v[174:175] op_sel_hi:[1,0,1]
	v_pk_fma_f32 v[176:177], v[128:129], s[36:37], v[176:177] op_sel_hi:[1,0,1]
	v_pk_fma_f32 v[178:179], v[130:131], s[36:37], v[178:179] op_sel_hi:[1,0,1]
	v_pk_fma_f32 v[180:181], v[132:133], s[36:37], v[180:181] op_sel_hi:[1,0,1]
	v_pk_fma_f32 v[182:183], v[134:135], s[36:37], v[182:183] op_sel_hi:[1,0,1]
	v_pk_fma_f32 v[184:185], v[136:137], s[36:37], v[184:185] op_sel_hi:[1,0,1]
	v_pk_fma_f32 v[186:187], v[138:139], s[36:37], v[186:187] op_sel_hi:[1,0,1]
	v_pk_fma_f32 v[188:189], v[140:141], s[36:37], v[188:189] op_sel_hi:[1,0,1]
	v_pk_fma_f32 v[190:191], v[142:143], s[36:37], v[190:191] op_sel_hi:[1,0,1]
	v_readlane_b32 s29, v37, s28
	s_add_u32 s28, s28, 1
	s_mul_hi_u32 s27, s29, 0x640
	s_mul_i32 s26, s29, 0x640
	s_add_u32 s26, s18, s26
	s_addc_u32 s27, s19, s27
	global_load_dwordx4 v[104:107], v2, s[26:27]
	global_load_dwordx2 v[108:109], v2, s[26:27] offset:16
	global_load_ubyte v110, v3, s[26:27]
	s_sub_u32 s30, s30, 1
	s_cmp_lg_u32 s30, 0
	s_cbranch_scc1 .Lap1_s2_loop4
	v_readlane_b32 s36, v43, s37
	s_add_u32 s37, s37, 1
	s_waitcnt vmcnt(21)
	v_lshlrev_b32_e32 v192, 23, v54
	v_cvt_scalef32_pk32_f32_fp6 v[112:143], v[48:53], v192
	v_pk_fma_f32 v[160:161], v[112:113], s[36:37], v[160:161] op_sel_hi:[1,0,1]
	v_pk_fma_f32 v[162:163], v[114:115], s[36:37], v[162:163] op_sel_hi:[1,0,1]
	v_pk_fma_f32 v[164:165], v[116:117], s[36:37], v[164:165] op_sel_hi:[1,0,1]
	v_pk_fma_f32 v[166:167], v[118:119], s[36:37], v[166:167] op_sel_hi:[1,0,1]
	v_pk_fma_f32 v[168:169], v[120:121], s[36:37], v[168:169] op_sel_hi:[1,0,1]
	v_pk_fma_f32 v[170:171], v[122:123], s[36:37], v[170:171] op_sel_hi:[1,0,1]
	v_pk_fma_f32 v[172:173], v[124:125], s[36:37], v[172:173] op_sel_hi:[1,0,1]
	v_pk_fma_f32 v[174:175], v[126:127], s[36:37], v[174:175] op_sel_hi:[1,0,1]
	v_pk_fma_f32 v[176:177], v[128:129], s[36:37], v[176:177] op_sel_hi:[1,0,1]
	v_pk_fma_f32 v[178:179], v[130:131], s[36:37], v[178:179] op_sel_hi:[1,0,1]
	v_pk_fma_f32 v[180:181], v[132:133], s[36:37], v[180:181] op_sel_hi:[1,0,1]
	v_pk_fma_f32 v[182:183], v[134:135], s[36:37], v[182:183] op_sel_hi:[1,0,1]
	v_pk_fma_f32 v[184:185], v[136:137], s[36:37], v[184:185] op_sel_hi:[1,0,1]
	v_pk_fma_f32 v[186:187], v[138:139], s[36:37], v[186:187] op_sel_hi:[1,0,1]
	v_pk_fma_f32 v[188:189], v[140:141], s[36:37], v[188:189] op_sel_hi:[1,0,1]
	v_pk_fma_f32 v[190:191], v[142:143], s[36:37], v[190:191] op_sel_hi:[1,0,1]
	v_readlane_b32 s36, v43, s37
	s_add_u32 s37, s37, 1
	s_waitcnt vmcnt(18)
	v_lshlrev_b32_e32 v192, 23, v62
	v_cvt_scalef32_pk32_f32_fp6 v[112:143], v[56:61], v192
	v_pk_fma_f32 v[160:161], v[112:113], s[36:37], v[160:161] op_sel_hi:[1,0,1]
	v_pk_fma_f32 v[162:163], v[114:115], s[36:37], v[162:163] op_sel_hi:[1,0,1]
	v_pk_fma_f32 v[164:165], v[116:117], s[36:37], v[164:165] op_sel_hi:[1,0,1]
	v_pk_fma_f32 v[166:167], v[118:119], s[36:37], v[166:167] op_sel_hi:[1,0,1]
	v_pk_fma_f32 v[168:169], v[120:121], s[36:37], v[168:169] op_sel_hi:[1,0,1]
	v_pk_fma_f32 v[170:171], v[122:123], s[36:37], v[170:171] op_sel_hi:[1,0,1]
	v_pk_fma_f32 v[172:173], v[124:125], s[36:37], v[172:173] op_sel_hi:[1,0,1]
	v_pk_fma_f32 v[174:175], v[126:127], s[36:37], v[174:175] op_sel_hi:[1,0,1]
	v_pk_fma_f32 v[176:177], v[128:129], s[36:37], v[176:177] op_sel_hi:[1,0,1]
	v_pk_fma_f32 v[178:179], v[130:131], s[36:37], v[178:179] op_sel_hi:[1,0,1]
	v_pk_fma_f32 v[180:181], v[132:133], s[36:37], v[180:181] op_sel_hi:[1,0,1]
	v_pk_fma_f32 v[182:183], v[134:135], s[36:37], v[182:183] op_sel_hi:[1,0,1]
	v_pk_fma_f32 v[184:185], v[136:137], s[36:37], v[184:185] op_sel_hi:[1,0,1]
	v_pk_fma_f32 v[186:187], v[138:139], s[36:37], v[186:187] op_sel_hi:[1,0,1]
	v_pk_fma_f32 v[188:189], v[140:141], s[36:37], v[188:189] op_sel_hi:[1,0,1]
	v_pk_fma_f32 v[190:191], v[142:143], s[36:37], v[190:191] op_sel_hi:[1,0,1]
	v_readlane_b32 s36, v43, s37
	s_add_u32 s37, s37, 1
	s_waitcnt vmcnt(15)
; #define PB_FENCE asm volatile("" ::: "memory")
; __device__ __forceinline__ void ph_peer_apply(const Params& P, int layer, float* xlat, float* xctx_in, float* xctx_out, int nrows, bool write_next, char* smem, float* xlat_out = nullptr) {
;     ...
;     PB_LOAD(bufA, tv, 0);
;     for (int gq = 0; gq < NG; gq += 2) {
;       PB_LOAD(bufB, tv, gq + 1); PB_FENCE;
;       PB_ACC(bufA, gq);
;       if (gq + 2 < NG) PB_LOAD(bufA, tv, gq + 2);
;       PB_FENCE;
;       PB_ACC(bufB, gq + 1);
;     }
	v_lshlrev_b32_e32 v192, 23, v70
	v_cvt_scalef32_pk32_f32_fp6 v[112:143], v[64:69], v192
	v_pk_fma_f32 v[160:161], v[112:113], s[36:37], v[160:161] op_sel_hi:[1,0,1]
	v_pk_fma_f32 v[162:163], v[114:115], s[36:37], v[162:163] op_sel_hi:[1,0,1]
	v_pk_fma_f32 v[164:165], v[116:117], s[36:37], v[164:165] op_sel_hi:[1,0,1]
	v_pk_fma_f32 v[166:167], v[118:119], s[36:37], v[166:167] op_sel_hi:[1,0,1]
	v_pk_fma_f32 v[168:169], v[120:121], s[36:37], v[168:169] op_sel_hi:[1,0,1]
	v_pk_fma_f32 v[170:171], v[122:123], s[36:37], v[170:171] op_sel_hi:[1,0,1]
	v_pk_fma_f32 v[172:173], v[124:125], s[36:37], v[172:173] op_sel_hi:[1,0,1]
	v_pk_fma_f32 v[174:175], v[126:127], s[36:37], v[174:175] op_sel_hi:[1,0,1]
	v_pk_fma_f32 v[176:177], v[128:129], s[36:37], v[176:177] op_sel_hi:[1,0,1]
	v_pk_fma_f32 v[178:179], v[130:131], s[36:37], v[178:179] op_sel_hi:[1,0,1]
	v_pk_fma_f32 v[180:181], v[132:133], s[36:37], v[180:181] op_sel_hi:[1,0,1]
	v_pk_fma_f32 v[182:183], v[134:135], s[36:37], v[182:183] op_sel_hi:[1,0,1]
	v_pk_fma_f32 v[184:185], v[136:137], s[36:37], v[184:185] op_sel_hi:[1,0,1]
	v_pk_fma_f32 v[186:187], v[138:139], s[36:37], v[186:187] op_sel_hi:[1,0,1]
	v_pk_fma_f32 v[188:189], v[140:141], s[36:37], v[188:189] op_sel_hi:[1,0,1]
	v_pk_fma_f32 v[190:191], v[142:143], s[36:37], v[190:191] op_sel_hi:[1,0,1]
	v_readlane_b32 s36, v43, s37
	s_add_u32 s37, s37, 1
	s_waitcnt vmcnt(12)
	v_lshlrev_b32_e32 v192, 23, v78
	v_cvt_scalef32_pk32_f32_fp6 v[112:143], v[72:77], v192
	v_pk_fma_f32 v[160:161], v[112:113], s[36:37], v[160:161] op_sel_hi:[1,0,1]
	v_pk_fma_f32 v[162:163], v[114:115], s[36:37], v[162:163] op_sel_hi:[1,0,1]
	v_pk_fma_f32 v[164:165], v[116:117], s[36:37], v[164:165] op_sel_hi:[1,0,1]
	v_pk_fma_f32 v[166:167], v[118:119], s[36:37], v[166:167] op_sel_hi:[1,0,1]
	v_pk_fma_f32 v[168:169], v[120:121], s[36:37], v[168:169] op_sel_hi:[1,0,1]
	v_pk_fma_f32 v[170:171], v[122:123], s[36:37], v[170:171] op_sel_hi:[1,0,1]
	v_pk_fma_f32 v[172:173], v[124:125], s[36:37], v[172:173] op_sel_hi:[1,0,1]
	v_pk_fma_f32 v[174:175], v[126:127], s[36:37], v[174:175] op_sel_hi:[1,0,1]
	v_pk_fma_f32 v[176:177], v[128:129], s[36:37], v[176:177] op_sel_hi:[1,0,1]
	v_pk_fma_f32 v[178:179], v[130:131], s[36:37], v[178:179] op_sel_hi:[1,0,1]
	v_pk_fma_f32 v[180:181], v[132:133], s[36:37], v[180:181] op_sel_hi:[1,0,1]
	v_pk_fma_f32 v[182:183], v[134:135], s[36:37], v[182:183] op_sel_hi:[1,0,1]
	v_pk_fma_f32 v[184:185], v[136:137], s[36:37], v[184:185] op_sel_hi:[1,0,1]
	v_pk_fma_f32 v[186:187], v[138:139], s[36:37], v[186:187] op_sel_hi:[1,0,1]
	v_pk_fma_f32 v[188:189], v[140:141], s[36:37], v[188:189] op_sel_hi:[1,0,1]
	v_pk_fma_f32 v[190:191], v[142:143], s[36:37], v[190:191] op_sel_hi:[1,0,1]
	v_readlane_b32 s36, v43, s37
	s_add_u32 s37, s37, 1
	s_waitcnt vmcnt(9)
	v_lshlrev_b32_e32 v192, 23, v86
	v_cvt_scalef32_pk32_f32_fp6 v[112:143], v[80:85], v192
	v_pk_fma_f32 v[160:161], v[112:113], s[36:37], v[160:161] op_sel_hi:[1,0,1]
	v_pk_fma_f32 v[162:163], v[114:115], s[36:37], v[162:163] op_sel_hi:[1,0,1]
	v_pk_fma_f32 v[164:165], v[116:117], s[36:37], v[164:165] op_sel_hi:[1,0,1]
	v_pk_fma_f32 v[166:167], v[118:119], s[36:37], v[166:167] op_sel_hi:[1,0,1]
	v_pk_fma_f32 v[168:169], v[120:121], s[36:37], v[168:169] op_sel_hi:[1,0,1]
	v_pk_fma_f32 v[170:171], v[122:123], s[36:37], v[170:171] op_sel_hi:[1,0,1]
	v_pk_fma_f32 v[172:173], v[124:125], s[36:37], v[172:173] op_sel_hi:[1,0,1]
	v_pk_fma_f32 v[174:175], v[126:127], s[36:37], v[174:175] op_sel_hi:[1,0,1]
	v_pk_fma_f32 v[176:177], v[128:129], s[36:37], v[176:177] op_sel_hi:[1,0,1]
	v_pk_fma_f32 v[178:179], v[130:131], s[36:37], v[178:179] op_sel_hi:[1,0,1]
	v_pk_fma_f32 v[180:181], v[132:133], s[36:37], v[180:181] op_sel_hi:[1,0,1]
	v_pk_fma_f32 v[182:183], v[134:135], s[36:37], v[182:183] op_sel_hi:[1,0,1]
	v_pk_fma_f32 v[184:185], v[136:137], s[36:37], v[184:185] op_sel_hi:[1,0,1]
	v_pk_fma_f32 v[186:187], v[138:139], s[36:37], v[186:187] op_sel_hi:[1,0,1]
	v_pk_fma_f32 v[188:189], v[140:141], s[36:37], v[188:189] op_sel_hi:[1,0,1]
	v_pk_fma_f32 v[190:191], v[142:143], s[36:37], v[190:191] op_sel_hi:[1,0,1]
	v_readlane_b32 s36, v43, s37
	s_add_u32 s37, s37, 1
	s_waitcnt vmcnt(6)
	v_lshlrev_b32_e32 v192, 23, v94
	v_cvt_scalef32_pk32_f32_fp6 v[112:143], v[88:93], v192
	v_pk_fma_f32 v[160:161], v[112:113], s[36:37], v[160:161] op_sel_hi:[1,0,1]
	v_pk_fma_f32 v[162:163], v[114:115], s[36:37], v[162:163] op_sel_hi:[1,0,1]
	v_pk_fma_f32 v[164:165], v[116:117], s[36:37], v[164:165] op_sel_hi:[1,0,1]
	v_pk_fma_f32 v[166:167], v[118:119], s[36:37], v[166:167] op_sel_hi:[1,0,1]
	v_pk_fma_f32 v[168:169], v[120:121], s[36:37], v[168:169] op_sel_hi:[1,0,1]
	v_pk_fma_f32 v[170:171], v[122:123], s[36:37], v[170:171] op_sel_hi:[1,0,1]
	v_pk_fma_f32 v[172:173], v[124:125], s[36:37], v[172:173] op_sel_hi:[1,0,1]
	v_pk_fma_f32 v[174:175], v[126:127], s[36:37], v[174:175] op_sel_hi:[1,0,1]
	v_pk_fma_f32 v[176:177], v[128:129], s[36:37], v[176:177] op_sel_hi:[1,0,1]
	v_pk_fma_f32 v[178:179], v[130:131], s[36:37], v[178:179] op_sel_hi:[1,0,1]
	v_pk_fma_f32 v[180:181], v[132:133], s[36:37], v[180:181] op_sel_hi:[1,0,1]
	v_pk_fma_f32 v[182:183], v[134:135], s[36:37], v[182:183] op_sel_hi:[1,0,1]
	v_pk_fma_f32 v[184:185], v[136:137], s[36:37], v[184:185] op_sel_hi:[1,0,1]
	v_pk_fma_f32 v[186:187], v[138:139], s[36:37], v[186:187] op_sel_hi:[1,0,1]
	v_pk_fma_f32 v[188:189], v[140:141], s[36:37], v[188:189] op_sel_hi:[1,0,1]
	v_pk_fma_f32 v[190:191], v[142:143], s[36:37], v[190:191] op_sel_hi:[1,0,1]
	v_readlane_b32 s36, v43, s37
	s_add_u32 s37, s37, 1
	s_waitcnt vmcnt(3)
; #define PB_FENCE asm volatile("" ::: "memory")
; __device__ __forceinline__ void ph_peer_apply(const Params& P, int layer, float* xlat, float* xctx_in, float* xctx_out, int nrows, bool write_next, char* smem, float* xlat_out = nullptr) {
;     ...
;     PB_LOAD(bufA, tv, 0);
;     for (int gq = 0; gq < NG; gq += 2) {
;       PB_LOAD(bufB, tv, gq + 1); PB_FENCE;
;       PB_ACC(bufA, gq);
;       if (gq + 2 < NG) PB_LOAD(bufA, tv, gq + 2);
;       PB_FENCE;
;       PB_ACC(bufB, gq + 1);
;     }
;     ...
;     const float* xs1 = (row < NL ? xlat + (size_t)row * D : xctx_in + (size_t)(row - NL) * D) + lb * 32;
;     float* xo = (row < NL ? (xlat_out ? xlat_out : xlat) + (size_t)row * D : xctx_out + (size_t)(row - NL) * D) + lb * 32;
;     const float* gt = mod_ptr(P, layer, row, 5) + lb * 32;
;     float s = 0.f;
; #pragma unroll
;     for (int j4 = 0; j4 < 8; ++j4) {
;       float4 xa; const float4 ga = *(const float4*)(gt + j4 * 4);
;       if (row < NL) { const h16x4 xh_ = *(const h16x4*)((const h16*)(xlat + (size_t)row * D) + lb * 32 + j4 * 4); xa = make_float4((float)xh_[0], (float)xh_[1], (float)xh_[2], (float)xh_[3]); }
;       else xa = *(const float4*)(xs1 + j4 * 4);
;       o[j4 * 4 + 0] = ALPHA * xa.x + ga.x * o[j4 * 4 + 0]; o[j4 * 4 + 1] = ALPHA * xa.y + ga.y * o[j4 * 4 + 1];
;       o[j4 * 4 + 2] = ALPHA * xa.z + ga.z * o[j4 * 4 + 2]; o[j4 * 4 + 3] = ALPHA * xa.w + ga.w * o[j4 * 4 + 3];
;       s += (o[j4 * 4 + 0] + o[j4 * 4 + 1]) + (o[j4 * 4 + 2] + o[j4 * 4 + 3]);
	v_lshlrev_b32_e32 v192, 23, v102
	v_cvt_scalef32_pk32_f32_fp6 v[112:143], v[96:101], v192
	v_pk_fma_f32 v[160:161], v[112:113], s[36:37], v[160:161] op_sel_hi:[1,0,1]
	v_pk_fma_f32 v[162:163], v[114:115], s[36:37], v[162:163] op_sel_hi:[1,0,1]
	v_pk_fma_f32 v[164:165], v[116:117], s[36:37], v[164:165] op_sel_hi:[1,0,1]
	v_pk_fma_f32 v[166:167], v[118:119], s[36:37], v[166:167] op_sel_hi:[1,0,1]
	v_pk_fma_f32 v[168:169], v[120:121], s[36:37], v[168:169] op_sel_hi:[1,0,1]
	v_pk_fma_f32 v[170:171], v[122:123], s[36:37], v[170:171] op_sel_hi:[1,0,1]
	v_pk_fma_f32 v[172:173], v[124:125], s[36:37], v[172:173] op_sel_hi:[1,0,1]
	v_pk_fma_f32 v[174:175], v[126:127], s[36:37], v[174:175] op_sel_hi:[1,0,1]
	v_pk_fma_f32 v[176:177], v[128:129], s[36:37], v[176:177] op_sel_hi:[1,0,1]
	v_pk_fma_f32 v[178:179], v[130:131], s[36:37], v[178:179] op_sel_hi:[1,0,1]
	v_pk_fma_f32 v[180:181], v[132:133], s[36:37], v[180:181] op_sel_hi:[1,0,1]
	v_pk_fma_f32 v[182:183], v[134:135], s[36:37], v[182:183] op_sel_hi:[1,0,1]
	v_pk_fma_f32 v[184:185], v[136:137], s[36:37], v[184:185] op_sel_hi:[1,0,1]
	v_pk_fma_f32 v[186:187], v[138:139], s[36:37], v[186:187] op_sel_hi:[1,0,1]
	v_pk_fma_f32 v[188:189], v[140:141], s[36:37], v[188:189] op_sel_hi:[1,0,1]
	v_pk_fma_f32 v[190:191], v[142:143], s[36:37], v[190:191] op_sel_hi:[1,0,1]
	v_readlane_b32 s36, v43, s37
	s_add_u32 s37, s37, 1
	s_waitcnt vmcnt(0)
	v_lshlrev_b32_e32 v192, 23, v110
	v_cvt_scalef32_pk32_f32_fp6 v[112:143], v[104:109], v192
	v_pk_fma_f32 v[160:161], v[112:113], s[36:37], v[160:161] op_sel_hi:[1,0,1]
	v_pk_fma_f32 v[162:163], v[114:115], s[36:37], v[162:163] op_sel_hi:[1,0,1]
	v_pk_fma_f32 v[164:165], v[116:117], s[36:37], v[164:165] op_sel_hi:[1,0,1]
	v_pk_fma_f32 v[166:167], v[118:119], s[36:37], v[166:167] op_sel_hi:[1,0,1]
	v_pk_fma_f32 v[168:169], v[120:121], s[36:37], v[168:169] op_sel_hi:[1,0,1]
	v_pk_fma_f32 v[170:171], v[122:123], s[36:37], v[170:171] op_sel_hi:[1,0,1]
	v_pk_fma_f32 v[172:173], v[124:125], s[36:37], v[172:173] op_sel_hi:[1,0,1]
	v_pk_fma_f32 v[174:175], v[126:127], s[36:37], v[174:175] op_sel_hi:[1,0,1]
	v_pk_fma_f32 v[176:177], v[128:129], s[36:37], v[176:177] op_sel_hi:[1,0,1]
	v_pk_fma_f32 v[178:179], v[130:131], s[36:37], v[178:179] op_sel_hi:[1,0,1]
	v_pk_fma_f32 v[180:181], v[132:133], s[36:37], v[180:181] op_sel_hi:[1,0,1]
	v_pk_fma_f32 v[182:183], v[134:135], s[36:37], v[182:183] op_sel_hi:[1,0,1]
	v_pk_fma_f32 v[184:185], v[136:137], s[36:37], v[184:185] op_sel_hi:[1,0,1]
	v_pk_fma_f32 v[186:187], v[138:139], s[36:37], v[186:187] op_sel_hi:[1,0,1]
	v_pk_fma_f32 v[188:189], v[140:141], s[36:37], v[188:189] op_sel_hi:[1,0,1]
	v_pk_fma_f32 v[190:191], v[142:143], s[36:37], v[190:191] op_sel_hi:[1,0,1]
	s_cmp_ge_u32 s45, 0x8000
	s_cselect_b32 s48, 1, 0
	s_lshr_b32 s49, s45, 14
	s_cmp_lg_u32 s48, 0
	s_cselect_b32 s49, 2, s49
	s_sub_u32 s50, s45, 0x8000
	s_lshl_b32 s15, s45, 13
	s_lshr_b32 s31, s45, 19
	s_add_u32 s40, s6, s15
	s_addc_u32 s41, s7, s31
	s_add_u32 s15, s49, 3
	s_mul_i32 s15, s15, 6
	s_add_u32 s15, s15, 5
	s_lshl_b32 s15, s15, 13
	s_add_u32 s42, s4, 0x4000
	s_addc_u32 s43, s5, 0
	s_add_u32 s42, s42, s15
	s_addc_u32 s43, s43, 0
	global_load_dwordx4 v[112:115], v225, s[42:43]
	global_load_dwordx4 v[116:119], v225, s[42:43] offset:16
	global_load_dwordx4 v[120:123], v225, s[42:43] offset:32
	global_load_dwordx4 v[124:127], v225, s[42:43] offset:48
	global_load_dwordx4 v[128:131], v225, s[42:43] offset:64
	global_load_dwordx4 v[132:135], v225, s[42:43] offset:80
	global_load_dwordx4 v[136:139], v225, s[42:43] offset:96
	global_load_dwordx4 v[140:143], v225, s[42:43] offset:112
	s_mov_b32 s15, 0x3fb504f3
	global_load_dwordx4 v[192:195], v224, s[40:41]
	global_load_dwordx4 v[196:199], v224, s[40:41] offset:16
	global_load_dwordx4 v[200:203], v224, s[40:41] offset:32
	global_load_dwordx4 v[204:207], v224, s[40:41] offset:48
	s_waitcnt vmcnt(0)
	v_mul_f32_e32 v160, v112, v160
	v_mul_f32_e32 v161, v113, v161
	v_mul_f32_e32 v162, v114, v162
	v_mul_f32_e32 v163, v115, v163
	v_mul_f32_e32 v164, v116, v164
	v_mul_f32_e32 v165, v117, v165
	v_mul_f32_e32 v166, v118, v166
	v_mul_f32_e32 v167, v119, v167
	v_mul_f32_e32 v168, v120, v168
	v_mul_f32_e32 v169, v121, v169
	v_mul_f32_e32 v170, v122, v170
	v_mul_f32_e32 v171, v123, v171
	v_mul_f32_e32 v172, v124, v172
	v_mul_f32_e32 v173, v125, v173
	v_mul_f32_e32 v174, v126, v174
	v_mul_f32_e32 v175, v127, v175
	v_mul_f32_e32 v176, v128, v176
	v_mul_f32_e32 v177, v129, v177
	v_mul_f32_e32 v178, v130, v178
	v_mul_f32_e32 v179, v131, v179
	v_mul_f32_e32 v180, v132, v180
	v_mul_f32_e32 v181, v133, v181
	v_mul_f32_e32 v182, v134, v182
	v_mul_f32_e32 v183, v135, v183
	v_mul_f32_e32 v184, v136, v184
	v_mul_f32_e32 v185, v137, v185
	v_mul_f32_e32 v186, v138, v186
	v_mul_f32_e32 v187, v139, v187
	v_mul_f32_e32 v188, v140, v188
	v_mul_f32_e32 v189, v141, v189
	v_mul_f32_e32 v190, v142, v190
	v_mul_f32_e32 v191, v143, v191
	v_fma_mix_f32 v160, s15, v192, v160 op_sel_hi:[0,1,0]
	v_fma_mix_f32 v161, s15, v192, v161 op_sel:[0,1,0] op_sel_hi:[0,1,0]
	v_fma_mix_f32 v162, s15, v193, v162 op_sel_hi:[0,1,0]
	v_fma_mix_f32 v163, s15, v193, v163 op_sel:[0,1,0] op_sel_hi:[0,1,0]
	v_fma_mix_f32 v164, s15, v194, v164 op_sel_hi:[0,1,0]
	v_fma_mix_f32 v165, s15, v194, v165 op_sel:[0,1,0] op_sel_hi:[0,1,0]
	v_fma_mix_f32 v166, s15, v195, v166 op_sel_hi:[0,1,0]
	v_fma_mix_f32 v167, s15, v195, v167 op_sel:[0,1,0] op_sel_hi:[0,1,0]
	v_fma_mix_f32 v168, s15, v196, v168 op_sel_hi:[0,1,0]
	v_fma_mix_f32 v169, s15, v196, v169 op_sel:[0,1,0] op_sel_hi:[0,1,0]
	v_fma_mix_f32 v170, s15, v197, v170 op_sel_hi:[0,1,0]
	v_fma_mix_f32 v171, s15, v197, v171 op_sel:[0,1,0] op_sel_hi:[0,1,0]
; __device__ __forceinline__ float wave_sum(float v) { v = row_sum16(v); v += __shfl_xor(v, 16); v += __shfl_xor(v, 32); return v; }
; __device__ __forceinline__ void ph_peer_apply(const Params& P, int layer, float* xlat, float* xctx_in, float* xctx_out, int nrows, bool write_next, char* smem, float* xlat_out = nullptr) {
;     ...
;       o[j4 * 4 + 0] = ALPHA * xa.x + ga.x * o[j4 * 4 + 0]; o[j4 * 4 + 1] = ALPHA * xa.y + ga.y * o[j4 * 4 + 1];
;       o[j4 * 4 + 2] = ALPHA * xa.z + ga.z * o[j4 * 4 + 2]; o[j4 * 4 + 3] = ALPHA * xa.w + ga.w * o[j4 * 4 + 3];
;       s += (o[j4 * 4 + 0] + o[j4 * 4 + 1]) + (o[j4 * 4 + 2] + o[j4 * 4 + 3]);
;     }
;     s = wave_sum(lact ? s : 0.f);
;     const float mu = s / (float)D;
;     float s2 = 0.f;
; #pragma unroll
;     for (int j = 0; j < 32; ++j) { const float dd = o[j] - mu; s2 += dd * dd; }
;     s2 = wave_sum(lact ? s2 : 0.f);
;     const float rstd = rsqrtf(s2 / (float)D + LN_EPS);
;     const float* gp = g + lb * 32; const float* bp = bb + lb * 32;
;     const float* sh1n = mod_ptr(P, 1, row, 0) + lb * 32;
;     const float* sc1n = mod_ptr(P, 1, row, 1) + lb * 32;
;     if (lact) {
; #pragma unroll
;       for (int j4 = 0; j4 < 8; ++j4) {
;         const float4 gv = *(const float4*)(gp + j4 * 4), bv = *(const float4*)(bp + j4 * 4);
	v_fma_mix_f32 v172, s15, v198, v172 op_sel_hi:[0,1,0]
	v_fma_mix_f32 v173, s15, v198, v173 op_sel:[0,1,0] op_sel_hi:[0,1,0]
	v_fma_mix_f32 v174, s15, v199, v174 op_sel_hi:[0,1,0]
	v_fma_mix_f32 v175, s15, v199, v175 op_sel:[0,1,0] op_sel_hi:[0,1,0]
	v_fma_mix_f32 v176, s15, v200, v176 op_sel_hi:[0,1,0]
	v_fma_mix_f32 v177, s15, v200, v177 op_sel:[0,1,0] op_sel_hi:[0,1,0]
	v_fma_mix_f32 v178, s15, v201, v178 op_sel_hi:[0,1,0]
	v_fma_mix_f32 v179, s15, v201, v179 op_sel:[0,1,0] op_sel_hi:[0,1,0]
	v_fma_mix_f32 v180, s15, v202, v180 op_sel_hi:[0,1,0]
	v_fma_mix_f32 v181, s15, v202, v181 op_sel:[0,1,0] op_sel_hi:[0,1,0]
	v_fma_mix_f32 v182, s15, v203, v182 op_sel_hi:[0,1,0]
	v_fma_mix_f32 v183, s15, v203, v183 op_sel:[0,1,0] op_sel_hi:[0,1,0]
	v_fma_mix_f32 v184, s15, v204, v184 op_sel_hi:[0,1,0]
	v_fma_mix_f32 v185, s15, v204, v185 op_sel:[0,1,0] op_sel_hi:[0,1,0]
	v_fma_mix_f32 v186, s15, v205, v186 op_sel_hi:[0,1,0]
	v_fma_mix_f32 v187, s15, v205, v187 op_sel:[0,1,0] op_sel_hi:[0,1,0]
	v_fma_mix_f32 v188, s15, v206, v188 op_sel_hi:[0,1,0]
	v_fma_mix_f32 v189, s15, v206, v189 op_sel:[0,1,0] op_sel_hi:[0,1,0]
	v_fma_mix_f32 v190, s15, v207, v190 op_sel_hi:[0,1,0]
	v_fma_mix_f32 v191, s15, v207, v191 op_sel:[0,1,0] op_sel_hi:[0,1,0]
	v_add_f32_e32 v208, v160, v161
	v_add_f32_e32 v208, v208, v162
	v_add_f32_e32 v208, v208, v163
	v_add_f32_e32 v208, v208, v164
	v_add_f32_e32 v208, v208, v165
	v_add_f32_e32 v208, v208, v166
	v_add_f32_e32 v208, v208, v167
	v_add_f32_e32 v208, v208, v168
	v_add_f32_e32 v208, v208, v169
	v_add_f32_e32 v208, v208, v170
	v_add_f32_e32 v208, v208, v171
	v_add_f32_e32 v208, v208, v172
	v_add_f32_e32 v208, v208, v173
	v_add_f32_e32 v208, v208, v174
	v_add_f32_e32 v208, v208, v175
	v_add_f32_e32 v208, v208, v176
	v_add_f32_e32 v208, v208, v177
	v_add_f32_e32 v208, v208, v178
	v_add_f32_e32 v208, v208, v179
	v_add_f32_e32 v208, v208, v180
	v_add_f32_e32 v208, v208, v181
	v_add_f32_e32 v208, v208, v182
	v_add_f32_e32 v208, v208, v183
	v_add_f32_e32 v208, v208, v184
	v_add_f32_e32 v208, v208, v185
	v_add_f32_e32 v208, v208, v186
	v_add_f32_e32 v208, v208, v187
	v_add_f32_e32 v208, v208, v188
	v_add_f32_e32 v208, v208, v189
	v_add_f32_e32 v208, v208, v190
	v_add_f32_e32 v208, v208, v191
	s_nop 1
	v_add_f32_dpp v208, v208, v208 quad_perm:[1,0,3,2] row_mask:0xf bank_mask:0xf bound_ctrl:1
	s_nop 1
	v_add_f32_dpp v208, v208, v208 quad_perm:[2,3,0,1] row_mask:0xf bank_mask:0xf bound_ctrl:1
	s_nop 1
	v_add_f32_dpp v208, v208, v208 row_ror:4 row_mask:0xf bank_mask:0xf bound_ctrl:1
	s_nop 1
	v_add_f32_dpp v208, v208, v208 row_ror:8 row_mask:0xf bank_mask:0xf bound_ctrl:1
	v_mov_b32_e32 v193, v208
	s_nop 1
	v_permlane32_swap_b32_e32 v193, v208
	v_add_f32_e32 v208, v208, v193
	v_mov_b32_e32 v193, v208
	s_nop 1
	v_permlane16_swap_b32_e32 v193, v208
	v_add_f32_e32 v208, v208, v193
	v_mul_f32_e32 v210, 0x3a000000, v208
	v_sub_f32_e32 v160, v160, v210
	v_sub_f32_e32 v161, v161, v210
	v_sub_f32_e32 v162, v162, v210
	v_sub_f32_e32 v163, v163, v210
	v_sub_f32_e32 v164, v164, v210
	v_sub_f32_e32 v165, v165, v210
	v_sub_f32_e32 v166, v166, v210
	v_sub_f32_e32 v167, v167, v210
	v_sub_f32_e32 v168, v168, v210
	v_sub_f32_e32 v169, v169, v210
	v_sub_f32_e32 v170, v170, v210
	v_sub_f32_e32 v171, v171, v210
	v_sub_f32_e32 v172, v172, v210
	v_sub_f32_e32 v173, v173, v210
	v_sub_f32_e32 v174, v174, v210
	v_sub_f32_e32 v175, v175, v210
	v_sub_f32_e32 v176, v176, v210
	v_sub_f32_e32 v177, v177, v210
	v_sub_f32_e32 v178, v178, v210
	v_sub_f32_e32 v179, v179, v210
	v_sub_f32_e32 v180, v180, v210
	v_sub_f32_e32 v181, v181, v210
	v_sub_f32_e32 v182, v182, v210
	v_sub_f32_e32 v183, v183, v210
	v_sub_f32_e32 v184, v184, v210
	v_sub_f32_e32 v185, v185, v210
	v_sub_f32_e32 v186, v186, v210
	v_sub_f32_e32 v187, v187, v210
	v_sub_f32_e32 v188, v188, v210
	v_sub_f32_e32 v189, v189, v210
	v_sub_f32_e32 v190, v190, v210
	v_sub_f32_e32 v191, v191, v210
	v_mul_f32_e32 v209, v160, v160
	v_fmac_f32_e32 v209, v161, v161
	v_fmac_f32_e32 v209, v162, v162
	v_fmac_f32_e32 v209, v163, v163
	v_fmac_f32_e32 v209, v164, v164
	v_fmac_f32_e32 v209, v165, v165
	v_fmac_f32_e32 v209, v166, v166
	v_fmac_f32_e32 v209, v167, v167
	v_fmac_f32_e32 v209, v168, v168
	v_fmac_f32_e32 v209, v169, v169
	v_fmac_f32_e32 v209, v170, v170
	v_fmac_f32_e32 v209, v171, v171
	v_fmac_f32_e32 v209, v172, v172
	v_fmac_f32_e32 v209, v173, v173
	v_fmac_f32_e32 v209, v174, v174
	v_fmac_f32_e32 v209, v175, v175
	v_fmac_f32_e32 v209, v176, v176
	v_fmac_f32_e32 v209, v177, v177
	v_fmac_f32_e32 v209, v178, v178
	v_fmac_f32_e32 v209, v179, v179
	v_fmac_f32_e32 v209, v180, v180
	v_fmac_f32_e32 v209, v181, v181
	v_fmac_f32_e32 v209, v182, v182
	v_fmac_f32_e32 v209, v183, v183
	v_fmac_f32_e32 v209, v184, v184
	v_fmac_f32_e32 v209, v185, v185
	v_fmac_f32_e32 v209, v186, v186
	v_fmac_f32_e32 v209, v187, v187
	v_fmac_f32_e32 v209, v188, v188
	v_fmac_f32_e32 v209, v189, v189
	v_fmac_f32_e32 v209, v190, v190
	v_fmac_f32_e32 v209, v191, v191
	s_nop 1
	v_add_f32_dpp v209, v209, v209 quad_perm:[1,0,3,2] row_mask:0xf bank_mask:0xf bound_ctrl:1
	s_nop 1
	v_add_f32_dpp v209, v209, v209 quad_perm:[2,3,0,1] row_mask:0xf bank_mask:0xf bound_ctrl:1
	s_nop 1
	v_add_f32_dpp v209, v209, v209 row_ror:4 row_mask:0xf bank_mask:0xf bound_ctrl:1
	s_nop 1
	v_add_f32_dpp v209, v209, v209 row_ror:8 row_mask:0xf bank_mask:0xf bound_ctrl:1
	v_mov_b32_e32 v193, v209
	s_nop 1
	v_permlane32_swap_b32_e32 v193, v209
	v_add_f32_e32 v209, v209, v193
	v_mov_b32_e32 v193, v209
	s_nop 1
	v_permlane16_swap_b32_e32 v193, v209
	v_add_f32_e32 v209, v209, v193
	v_mov_b32_e32 v211, 0x3727c5ac
	v_fmac_f32_e32 v211, 0x3a000000, v209
	v_rsq_f32_e32 v211, v211
	s_add_u32 s26, s8, 0x6000
	s_addc_u32 s27, s9, 0
	global_load_dwordx4 v[112:115], v225, s[26:27]
	global_load_dwordx4 v[116:119], v225, s[26:27] offset:16
	global_load_dwordx4 v[120:123], v225, s[26:27] offset:32
	global_load_dwordx4 v[124:127], v225, s[26:27] offset:48
	global_load_dwordx4 v[128:131], v225, s[26:27] offset:64
	global_load_dwordx4 v[132:135], v225, s[26:27] offset:80
	global_load_dwordx4 v[136:139], v225, s[26:27] offset:96
	global_load_dwordx4 v[140:143], v225, s[26:27] offset:112
	s_add_u32 s26, s10, 0x6000
	s_addc_u32 s27, s11, 0
	global_load_dwordx4 v[192:195], v225, s[26:27]
	global_load_dwordx4 v[196:199], v225, s[26:27] offset:16
	global_load_dwordx4 v[200:203], v225, s[26:27] offset:32
	global_load_dwordx4 v[204:207], v225, s[26:27] offset:48
	s_waitcnt vmcnt(4)
; __device__ __forceinline__ void ph_peer_apply(const Params& P, int layer, float* xlat, float* xctx_in, float* xctx_out, int nrows, bool write_next, char* smem, float* xlat_out = nullptr) {
;     ...
;     if (lact) {
; #pragma unroll
;       for (int j4 = 0; j4 < 8; ++j4) {
;         const float4 gv = *(const float4*)(gp + j4 * 4), bv = *(const float4*)(bp + j4 * 4);
;         float4 ov;
;         ov.x = (o[j4 * 4 + 0] - mu) * rstd * gv.x + bv.x; ov.y = (o[j4 * 4 + 1] - mu) * rstd * gv.y + bv.y;
;         ov.z = (o[j4 * 4 + 2] - mu) * rstd * gv.z + bv.z; ov.w = (o[j4 * 4 + 3] - mu) * rstd * gv.w + bv.w;
;         if (row < NL && write_next) { h16x4 oh_; oh_[0] = (h16)ov.x; oh_[1] = (h16)ov.y; oh_[2] = (h16)ov.z; oh_[3] = (h16)ov.w; *(h16x4*)((h16*)((xlat_out ? xlat_out : xlat) + (size_t)row * D) + lb * 32 + j4 * 4) = oh_; }
;         else *(float4*)(xo + j4 * 4) = ov;
	v_mul_f32_e32 v160, v160, v211
	v_mul_f32_e32 v161, v161, v211
	v_mul_f32_e32 v162, v162, v211
	v_mul_f32_e32 v163, v163, v211
	v_mul_f32_e32 v164, v164, v211
	v_mul_f32_e32 v165, v165, v211
	v_mul_f32_e32 v166, v166, v211
	v_mul_f32_e32 v167, v167, v211
	v_mul_f32_e32 v168, v168, v211
	v_mul_f32_e32 v169, v169, v211
	v_mul_f32_e32 v170, v170, v211
	v_mul_f32_e32 v171, v171, v211
	v_mul_f32_e32 v172, v172, v211
	v_mul_f32_e32 v173, v173, v211
	v_mul_f32_e32 v174, v174, v211
	v_mul_f32_e32 v175, v175, v211
	v_mul_f32_e32 v176, v176, v211
	v_mul_f32_e32 v177, v177, v211
	v_mul_f32_e32 v178, v178, v211
	v_mul_f32_e32 v179, v179, v211
	v_mul_f32_e32 v180, v180, v211
	v_mul_f32_e32 v181, v181, v211
	v_mul_f32_e32 v182, v182, v211
	v_mul_f32_e32 v183, v183, v211
	v_mul_f32_e32 v184, v184, v211
	v_mul_f32_e32 v185, v185, v211
	v_mul_f32_e32 v186, v186, v211
	v_mul_f32_e32 v187, v187, v211
	v_mul_f32_e32 v188, v188, v211
	v_mul_f32_e32 v189, v189, v211
	v_mul_f32_e32 v190, v190, v211
	v_mul_f32_e32 v191, v191, v211
	v_mul_f32_e32 v160, v160, v112
	v_mul_f32_e32 v161, v161, v113
	v_mul_f32_e32 v162, v162, v114
	v_mul_f32_e32 v163, v163, v115
	v_mul_f32_e32 v164, v164, v116
	v_mul_f32_e32 v165, v165, v117
	v_mul_f32_e32 v166, v166, v118
	v_mul_f32_e32 v167, v167, v119
	v_mul_f32_e32 v168, v168, v120
	v_mul_f32_e32 v169, v169, v121
	v_mul_f32_e32 v170, v170, v122
	v_mul_f32_e32 v171, v171, v123
	v_mul_f32_e32 v172, v172, v124
	v_mul_f32_e32 v173, v173, v125
	v_mul_f32_e32 v174, v174, v126
	v_mul_f32_e32 v175, v175, v127
	v_mul_f32_e32 v176, v176, v128
	v_mul_f32_e32 v177, v177, v129
	v_mul_f32_e32 v178, v178, v130
	v_mul_f32_e32 v179, v179, v131
	v_mul_f32_e32 v180, v180, v132
	v_mul_f32_e32 v181, v181, v133
	v_mul_f32_e32 v182, v182, v134
	v_mul_f32_e32 v183, v183, v135
	v_mul_f32_e32 v184, v184, v136
	v_mul_f32_e32 v185, v185, v137
	v_mul_f32_e32 v186, v186, v138
	v_mul_f32_e32 v187, v187, v139
	v_mul_f32_e32 v188, v188, v140
	v_mul_f32_e32 v189, v189, v141
	v_mul_f32_e32 v190, v190, v142
	v_mul_f32_e32 v191, v191, v143
	s_waitcnt vmcnt(0)
	v_add_f32_e32 v160, v160, v192
	v_add_f32_e32 v161, v161, v193
	v_add_f32_e32 v162, v162, v194
	v_add_f32_e32 v163, v163, v195
	v_add_f32_e32 v164, v164, v196
	v_add_f32_e32 v165, v165, v197
	v_add_f32_e32 v166, v166, v198
	v_add_f32_e32 v167, v167, v199
	v_add_f32_e32 v168, v168, v200
	v_add_f32_e32 v169, v169, v201
	v_add_f32_e32 v170, v170, v202
	v_add_f32_e32 v171, v171, v203
	v_add_f32_e32 v172, v172, v204
	v_add_f32_e32 v173, v173, v205
	v_add_f32_e32 v174, v174, v206
	v_add_f32_e32 v175, v175, v207
	global_load_dwordx4 v[192:195], v225, s[26:27] offset:64
	global_load_dwordx4 v[196:199], v225, s[26:27] offset:80
	global_load_dwordx4 v[200:203], v225, s[26:27] offset:96
	global_load_dwordx4 v[204:207], v225, s[26:27] offset:112
	s_waitcnt vmcnt(0)
	v_add_f32_e32 v176, v176, v192
	v_add_f32_e32 v177, v177, v193
	v_add_f32_e32 v178, v178, v194
	v_add_f32_e32 v179, v179, v195
	v_add_f32_e32 v180, v180, v196
	v_add_f32_e32 v181, v181, v197
	v_add_f32_e32 v182, v182, v198
	v_add_f32_e32 v183, v183, v199
	v_add_f32_e32 v184, v184, v200
	v_add_f32_e32 v185, v185, v201
	v_add_f32_e32 v186, v186, v202
	v_add_f32_e32 v187, v187, v203
	v_add_f32_e32 v188, v188, v204
	v_add_f32_e32 v189, v189, v205
	v_add_f32_e32 v190, v190, v206
	v_add_f32_e32 v191, v191, v207
	global_store_dwordx4 v225, v[160:163], s[40:41]
	global_store_dwordx4 v225, v[164:167], s[40:41] offset:16
	global_store_dwordx4 v225, v[168:171], s[40:41] offset:32
	global_store_dwordx4 v225, v[172:175], s[40:41] offset:48
	global_store_dwordx4 v225, v[176:179], s[40:41] offset:64
	global_store_dwordx4 v225, v[180:183], s[40:41] offset:80
	global_store_dwordx4 v225, v[184:187], s[40:41] offset:96
	global_store_dwordx4 v225, v[188:191], s[40:41] offset:112
	s_add_u32 s14, s14, 1
	s_add_u32 s45, s45, s44
	s_branch .Lap1_s2_tok
